# scan loops: 64-bit address constant adds done as one v_lshl_add_u64 with an SGPR constant (was add_co + nop + addc)
# speedup vs baseline: 1.0108x; 1.0017x over previous
; DI void hgrn2_scan_unit(Frame& F, const Mix0Args& a, int u) {
;     ...
;     auto load_ea = [&](int n_, HgEa& r) __attribute__((always_inline)) {
;         const char* uV = pP + (rowbase + (size_t)n_ * 64) * (size_t)(N1 * 2); const char* uE = pE + (Tb + n_) * 512;
; #pragma unroll
;         for (int i = 0; i < 2; ++i) r.v[i] = *(const unsigned*)(uV + vov[i]);
;         r.er = *(const f32x4*)(uE + vog); };
;     auto load_g = [&](int n_, HgOp& r) __attribute__((always_inline)) { const char* uG = pG + (Tb + n_) * 512; const char* uGa = pP + (rowbase + (size_t)n_ * 64) * (size_t)(N1 * 2);
;         r.g4 = *(const f32x4*)(uG + vog); r.ga = *(const u32x2*)(uGa + voga); };
;     auto load_q = [&](int n_, HgOp& r) __attribute__((always_inline)) { const char* uQ = pQ + (Tb + n_) * 16384;
; #pragma unroll
;         for (int ks = 0; ks < 4; ++ks) r.qf[ks] = *(const bf16x8*)(uQ + ks * 1024 + voq); };
;     auto load_pk = [&](int n_, HgOp& r) __attribute__((always_inline)) { const char* uPm = pPm + (Tb + n_) * 8192; const char* uK = pK + (Tb + n_) * 16384;
; #pragma unroll
;         for (int ks = 0; ks < 2; ++ks) { r.pf[ks] = *(const bf16x8*)(uPm + ks * 1024 + vop); r.kf[ks] = *(const bf16x8*)(uK + ks * 1024 + vok); } };
;     auto load_op = [&](int n_, HgOp& r) __attribute__((always_inline)) { load_g(n_, r); load_q(n_, r); load_pk(n_, r); };
;     u32x2 p_d = {0u, 0u}; float ss_d = 0.f;
;     auto put = [&](int n_) __attribute__((always_inline)) {
;         const size_t r0_ = rowbase + (size_t)n_ * 64;
;         if (fq == 0) unsafeAtomicAdd((float*)(pS + r0_ * 4 + vos), ss_d);
;         *(u32x2*)(pO + r0_ * (size_t)(a.out_ld * 2) + voo) = p_d; };
;     auto stage = [&](const HgEa& e, LAS uchar* VT) __attribute__((always_inline)) {
;         *(LAS unsigned*)(VT + (2 * vp) * S64 + lr * 4) = (e.v[0] & 0xffffu) | (e.v[1] << 16); *(LAS unsigned*)(VT + (2 * vp + 1) * S64 + lr * 4) = (e.v[0] >> 16) | (e.v[1] & 0xffff0000u); };
;     bf16x8 v2[2][2]; f32x4 oacc;
;     auto compute_o = [&](int n, const HgOp& o, LAS uchar* VTc) __attribute__((always_inline)) {
;         LAS uchar* STBc = STB0 + (n & 1) * 32 * S128;
;         bf16x8 sf[4];
; #pragma unroll
;         for (int ks = 0; ks < 4; ++ks) sf[ks] = *(const LAS bf16x8*)(STBc + (v0_ + fr) * S128 + ks * 64 + fq * 16);
; #pragma unroll
;         for (int ks = 0; ks < 2; ++ks) {
; #pragma unroll
.LBB0_218:
	s_or_b64 exec, exec, s[8:9]
	s_add_i32 s19, s18, -1
	v_lshl_add_u64 v[164:165], s[58:59], 0, v[140:141]
	s_mov_b64 s[100:101], 0x25600000
	v_lshl_add_u64 v[60:61], v[164:165], 0, s[100:101]
	s_cmpk_lt_u32 s19, 0x7e
	s_cselect_b64 s[8:9], -1, 0
	s_cmpk_gt_u32 s19, 0x7d
	v_lshl_add_u64 v[160:161], s[58:59], 0, v[132:133]
	v_lshl_add_u64 v[156:157], s[58:59], 0, v[134:135]
	v_lshl_add_u64 v[152:153], s[58:59], 0, v[136:137]
	global_store_dwordx2 v[60:61], v[58:59], off
	s_cbranch_scc1 .LBB0_220
	s_mov_b64 s[100:101], 0x25f00000
	v_lshl_add_u64 v[10:11], v[160:161], 0, s[100:101]
	s_mov_b64 s[100:101], 0x25f00000
	v_lshl_add_u64 v[12:13], v[156:157], 0, s[100:101]
	s_mov_b64 s[100:101], 0x8100000
	v_lshl_add_u64 v[58:59], v[152:153], 0, s[100:101]
	global_load_dword v189, v[10:11], off
	global_load_dword v190, v[12:13], off
	s_nop 0
	global_load_dwordx4 v[10:13], v[58:59], off offset:2048
.LBB0_220:
	v_lshl_add_u64 v[154:155], s[58:59], 0, v[142:143]
	s_mov_b64 s[100:101], 0x25c00000
	v_lshl_add_u64 v[58:59], v[154:155], 0, s[100:101]
	global_load_dwordx2 v[150:151], v[58:59], off
	v_and_b32_e32 v58, 0xffff, v191
	v_lshrrev_b32_e32 v59, 16, v191
	v_lshl_or_b32 v58, v192, 16, v58
	v_and_or_b32 v59, v192, s28, v59
	ds_write2_b32 v185, v58, v59 offset1:40
	s_mov_b64 s[100:101], 0x59300000
	v_lshl_add_u64 v[58:59], v[152:153], 0, s[100:101]
	global_load_dwordx4 v[58:61], v[58:59], off offset:1536
	v_lshl_add_u64 v[168:169], s[58:59], 0, v[144:145]
	s_mov_b64 s[100:101], 0x10c000
	v_lshl_add_u64 v[66:67], v[168:169], 0, s[100:101]
	global_load_dwordx4 v[82:85], v[66:67], off offset:3072
	global_load_dwordx4 v[86:89], v[66:67], off offset:2048
	global_load_dwordx4 v[90:93], v[66:67], off offset:1024
	global_load_dwordx4 v[94:97], v[66:67], off
	ds_read_b128 v[66:69], v186 offset:10240
	ds_read_b128 v[70:73], v186 offset:10304
	ds_read_b128 v[74:77], v186 offset:10368
	s_waitcnt lgkmcnt(2)
	v_mfma_f32_16x16x32_bf16 v[66:69], v[66:69], v[22:25], 0
	s_waitcnt lgkmcnt(1)
	v_mfma_f32_16x16x32_bf16 v[66:69], v[70:73], v[26:29], v[66:69]
	ds_read_b128 v[70:73], v186 offset:10432
	ds_read_b128 v[98:101], v187
	ds_read_b128 v[194:197], v187 offset:64
	ds_read_b128 v[198:201], v187 offset:2560
	ds_read_b128 v[202:205], v187 offset:2624
	s_waitcnt lgkmcnt(5)
	v_mfma_f32_16x16x32_bf16 v[66:69], v[74:77], v[30:33], v[66:69]
	s_waitcnt lgkmcnt(4)
	v_mfma_f32_16x16x32_bf16 v[206:209], v[70:73], v[34:37], v[66:69]
	v_lshl_add_u64 v[158:159], s[58:59], 0, v[146:147]
	s_mov_b32 s16, 0x1d30c000
	s_nop 3
	v_add_co_u32_e32 v66, vcc, s16, v158
	v_lshl_add_u64 v[162:163], s[58:59], 0, v[148:149]
	s_nop 0
	v_addc_co_u32_e32 v67, vcc, 0, v159, vcc
	s_mov_b32 s16, 0x55306000
	v_add_co_u32_e32 v78, vcc, s16, v162
	s_nop 1
	v_addc_co_u32_e32 v79, vcc, 0, v163, vcc
	global_load_dwordx4 v[70:73], v[66:67], off offset:1024
	global_load_dwordx4 v[74:77], v[66:67], off
	s_nop 0
	global_load_dwordx4 v[66:69], v[78:79], off offset:1024
	s_nop 0
	global_load_dwordx4 v[78:81], v[78:79], off
	s_waitcnt lgkmcnt(1)
	v_cndmask_b32_e64 v213, v201, v101, s[6:7]
	v_cndmask_b32_e64 v212, v200, v100, s[6:7]
	v_cndmask_b32_e64 v211, v199, v99, s[6:7]
	v_cndmask_b32_e64 v210, v198, v98, s[6:7]
	v_pk_mul_f32 v[56:57], v[56:57], v[16:17]
	v_pk_mul_f32 v[54:55], v[54:55], v[14:15]
	v_pk_mul_f32 v[64:65], v[64:65], v[16:17]
	v_pk_mul_f32 v[62:63], v[62:63], v[14:15]
	v_mfma_f32_16x16x32_bf16 v[54:57], v[46:49], v[98:101], v[54:57]
	s_waitcnt lgkmcnt(0)
	v_cndmask_b32_e64 v101, v205, v197, s[6:7]
	v_cndmask_b32_e64 v100, v204, v196, s[6:7]
	v_cndmask_b32_e64 v99, v203, v195, s[6:7]
	v_mfma_f32_16x16x32_bf16 v[62:65], v[46:49], v[198:201], v[62:65]
	v_cndmask_b32_e64 v98, v202, v194, s[6:7]
	v_mfma_f32_16x16x32_bf16 v[206:209], v[210:213], v[38:41], v[206:209]
	v_mfma_f32_16x16x32_bf16 v[54:57], v[50:53], v[194:197], v[54:57]
	v_mfma_f32_16x16x32_bf16 v[62:65], v[50:53], v[202:205], v[62:65]
	v_mfma_f32_16x16x32_bf16 v[98:101], v[98:101], v[42:45], v[206:209]
	s_nop 5
	v_mul_f32_e64 v194, v20, v56
	v_mul_f32_e64 v195, v21, v57
	v_pk_mul_f32 v[196:197], v[18:19], v[54:55]
	v_pk_mul_f32 v[198:199], v[18:19], v[62:63]
	v_cvt_pk_bf16_f32 v196, v196, v197
	v_cvt_pk_bf16_f32 v197, v194, v195
	v_pk_mul_f32 v[194:195], v[20:21], v[64:65]
	v_cvt_pk_bf16_f32 v198, v198, v199
	v_cvt_pk_bf16_f32 v199, v194, v195
	v_mul_f32_e32 v193, v99, v99
	v_mul_f32_e32 v194, v101, v101
	v_fmac_f32_e32 v193, v98, v98
	v_fmac_f32_e32 v194, v100, v100
	ds_write2st64_b64 v188, v[196:197], v[198:199] offset0:38 offset1:47
	v_add_f32_e32 v193, v193, v194
	v_mov_b32_e32 v194, v193
	s_waitcnt lgkmcnt(0)
	s_barrier
	s_nop 0
	v_permlane16_swap_b32_e32 v193, v194
	s_waitcnt vmcnt(8)
	v_add_f32_e32 v193, v193, v194
	s_waitcnt vmcnt(0)
	v_mov_b32_e32 v194, v193
	s_nop 1
	v_permlane32_swap_b32_e32 v193, v194
	s_and_saveexec_b64 s[16:17], s[10:11]
	s_cbranch_execz .LBB0_222
	v_add_f32_e32 v193, v193, v194
	global_atomic_add_f32 v[138:139], v193, off offset:256
; #define LAS __attribute__((address_space(3)))
; DI float bflo(unsigned w) { return __uint_as_float(w << 16); }
; DI float bfhi(unsigned w) { return __uint_as_float(w & 0xffff0000u); }
; DI void hgrn2_scan_unit(Frame& F, const Mix0Args& a, int u) {
;     ...
;     auto compute_s = [&](int n, const HgOp& o, const f32x4 er_next) __attribute__((always_inline)) {
;         LAS uchar* STBn = STB0 + ((n + 1) & 1) * 32 * S128;
; #pragma unroll
;         for (int ks = 0; ks < 2; ++ks) oacc = __builtin_amdgcn_mfma_f32_16x16x32_bf16(jtile ? v2[1][ks] : v2[0][ks], o.pf[ks], oacc, 0, 0, 0);
; #pragma unroll
;         for (int vt = 0; vt < 2; ++vt) { st[vt] = st[vt] * o.g4;
; #pragma unroll
;             for (int ks = 0; ks < 2; ++ks) st[vt] = __builtin_amdgcn_mfma_f32_16x16x32_bf16(o.kf[ks], v2[vt][ks], st[vt], 0, 0, 0);
;             const f32x4 se = st[vt] * er_next;
;             u32x2 p; p.x = pk2(se[0], se[1]); p.y = pk2(se[2], se[3]);
;             *(LAS u32x2*)(STBn + (16 * vt + fr) * S128 + (16 * w + 4 * fq) * 2) = p; }
;         const float ss = (oacc[0] * oacc[0] + oacc[1] * oacc[1]) + (oacc[2] * oacc[2] + oacc[3] * oacc[3]);
;         ss_d = fq_sum(ss);
;         const float g0 = bflo(o.ga.x), g1 = bfhi(o.ga.x), g2 = bflo(o.ga.y), g3 = bfhi(o.ga.y);
;         p_d.x = pk2(oacc[0] * anw[0] * fsilu(g0), oacc[1] * anw[1] * fsilu(g1)); p_d.y = pk2(oacc[2] * anw[2] * fsilu(g2), oacc[3] * anw[3] * fsilu(g3)); };
;     auto step = [&](int n, HgEa& ea, HgEa& eb, HgOp& oa, HgOp& ob) __attribute__((always_inline)) {
;         asm volatile("" : "+v"(ea.v[0]), "+v"(ea.v[1]), "+v"(ea.er), "+v"(oa.g4), "+v"(oa.ga) :: "memory");
;         asm volatile("" : "+v"(oa.qf[0]), "+v"(oa.qf[1]), "+v"(oa.qf[2]), "+v"(oa.qf[3]), "+v"(oa.pf[0]), "+v"(oa.pf[1]), "+v"(oa.kf[0]), "+v"(oa.kf[1]) :: "memory");
;         if (n > 0) put(n - 1);
;         if (n + 2 < NCH) load_ea(n + 2, eb);
;         if (n + 1 < NCH) load_g(n + 1, ob);
;         if (n + 1 < NCH) stage(ea, VT0 + ((n + 1) & 1) * VIMG);
;         __builtin_amdgcn_sched_barrier(0);
;         if (n + 1 < NCH) load_q(n + 1, ob);
;         __builtin_amdgcn_sched_barrier(0);
;         compute_o(n, oa, VT0 + (n & 1) * VIMG);
;         __builtin_amdgcn_sched_barrier(0);
;         if (n + 1 < NCH) load_pk(n + 1, ob);
;         __builtin_amdgcn_sched_barrier(0);
;         compute_s(n, oa, ea.er);
;         LDS_BAR(); };
.LBB0_222:
	s_or_b64 exec, exec, s[16:17]
	v_lshlrev_b32_e32 v194, 16, v130
	v_mul_f32_e32 v193, 0xbfb8aa3b, v194
	v_exp_f32_e32 v193, v193
	v_and_b32_e32 v195, 0xffff0000, v130
	v_pk_mul_f32 v[98:99], v[6:7], v[98:99]
	v_pk_mul_f32 v[100:101], v[8:9], v[100:101]
	v_add_f32_e32 v193, 1.0, v193
	v_rcp_f32_e32 v196, v193
	v_mul_f32_e32 v193, 0xbfb8aa3b, v195
	v_exp_f32_e32 v193, v193
	s_nop 0
	v_add_f32_e32 v193, 1.0, v193
	v_rcp_f32_e32 v197, v193
	s_nop 0
	v_pk_mul_f32 v[194:195], v[196:197], v[194:195]
	s_nop 0
	v_pk_mul_f32 v[98:99], v[194:195], v[98:99]
	v_lshlrev_b32_e32 v194, 16, v131
	v_cvt_pk_bf16_f32 v98, v98, v99
	v_mul_f32_e32 v99, 0xbfb8aa3b, v194
	v_exp_f32_e32 v99, v99
	v_and_b32_e32 v195, 0xffff0000, v131
	v_add_f32_e32 v99, 1.0, v99
	v_rcp_f32_e32 v196, v99
	v_mul_f32_e32 v99, 0xbfb8aa3b, v195
	v_exp_f32_e32 v99, v99
	s_nop 0
	v_add_f32_e32 v99, 1.0, v99
	v_rcp_f32_e32 v197, v99
	s_nop 0
	v_pk_mul_f32 v[194:195], v[196:197], v[194:195]
	s_nop 0
	v_pk_mul_f32 v[100:101], v[194:195], v[100:101]
	s_nop 0
	v_cvt_pk_bf16_f32 v99, v100, v101
	s_mov_b64 s[100:101], 0x25900000
	v_lshl_add_u64 v[100:101], v[164:165], 0, s[100:101]
	s_andn2_b64 vcc, exec, s[8:9]
	global_store_dwordx2 v[100:101], v[98:99], off
	s_cbranch_vccnz .LBB0_224
	s_mov_b64 s[100:101], 0x26200000
	v_lshl_add_u64 v[18:19], v[160:161], 0, s[100:101]
	s_mov_b64 s[100:101], 0x26200000
	v_lshl_add_u64 v[20:21], v[156:157], 0, s[100:101]
	s_mov_b64 s[100:101], 0x8100000
	v_lshl_add_u64 v[98:99], v[152:153], 0, s[100:101]
	global_load_dword v191, v[18:19], off
	global_load_dword v192, v[20:21], off
	s_nop 0
	global_load_dwordx4 v[18:21], v[98:99], off offset:2560
.LBB0_224:
	s_cmpk_lt_u32 s18, 0x7f
	s_cselect_b64 s[16:17], -1, 0
	s_cmpk_gt_u32 s18, 0x7e
	s_cbranch_scc1 .LBB0_226
	s_mov_b64 s[100:101], 0x59300000
	v_lshl_add_u64 v[14:15], v[152:153], 0, s[100:101]
	s_mov_b64 s[100:101], 0x25f00000
	v_lshl_add_u64 v[98:99], v[154:155], 0, s[100:101]
	global_load_dwordx4 v[14:17], v[14:15], off offset:2048
	s_nop 0
	global_load_dwordx2 v[130:131], v[98:99], off
	v_and_b32_e32 v98, 0xffff, v189
	v_lshrrev_b32_e32 v99, 16, v189
	v_lshl_or_b32 v98, v190, 16, v98
	v_and_or_b32 v99, v190, s28, v99
	ds_write2_b32 v183, v98, v99 offset1:40
.LBB0_226:
	v_cndmask_b32_e64 v98, 0, 1, s[16:17]
	v_cmp_ne_u32_e64 s[8:9], 1, v98
	s_andn2_b64 vcc, exec, s[16:17]
	s_cbranch_vccnz .LBB0_228
	s_mov_b64 s[100:101], 0x110000
	v_lshl_add_u64 v[34:35], v[168:169], 0, s[100:101]
	global_load_dwordx4 v[22:25], v[34:35], off
	global_load_dwordx4 v[26:29], v[34:35], off offset:1024
	global_load_dwordx4 v[30:33], v[34:35], off offset:2048
	s_nop 0
	global_load_dwordx4 v[34:37], v[34:35], off offset:3072
.LBB0_228:
	ds_read_b128 v[98:101], v103 offset:19456
	ds_read_b128 v[152:155], v103 offset:19520
	s_waitcnt lgkmcnt(1)
	v_mfma_f32_16x16x32_bf16 v[94:97], v[98:101], v[94:97], 0
	ds_read_b128 v[98:101], v103 offset:19584
	s_waitcnt lgkmcnt(1)
	v_mfma_f32_16x16x32_bf16 v[90:93], v[152:155], v[90:93], v[94:97]
	ds_read_b128 v[152:155], v103 offset:19648
	s_waitcnt lgkmcnt(1)
	v_mfma_f32_16x16x32_bf16 v[194:197], v[98:101], v[86:89], v[90:93]
	ds_read_b128 v[98:101], v187 offset:5120
	s_nop 3
	ds_read_b128 v[90:93], v187 offset:5184
	ds_read_b128 v[94:97], v187 offset:7680
	ds_read_b128 v[86:89], v187 offset:7744
	s_waitcnt lgkmcnt(4)
	v_mfma_f32_16x16x32_bf16 v[82:85], v[152:155], v[82:85], v[194:197]
	s_and_b64 vcc, exec, s[8:9]
	s_cbranch_vccnz .LBB0_215
	s_mov_b64 s[100:101], 0x55308000
	v_lshl_add_u64 v[42:43], v[162:163], 0, s[100:101]
	s_mov_b64 s[100:101], 0x1d310000
	v_lshl_add_u64 v[50:51], v[158:159], 0, s[100:101]
	global_load_dwordx4 v[38:41], v[42:43], off
	s_nop 0
	global_load_dwordx4 v[42:45], v[42:43], off offset:1024
	s_nop 0
	global_load_dwordx4 v[46:49], v[50:51], off
	s_nop 0
	global_load_dwordx4 v[50:53], v[50:51], off offset:1024
	s_branch .LBB0_215

; #define LAS __attribute__((address_space(3)))
; DI unsigned pk2(float lo, float hi) { f32x2 v = {lo, hi}; bf16v2 b = __builtin_convertvector(v, bf16v2); return __builtin_bit_cast(unsigned, b); }
; DI void rglru_scan_unit(Frame& F, const Mix0Args& a, int u) {
;     ...
;     LAS uchar* XC0 = F.lds; LAS uchar* WAT = XC0 + 2 * 64 * S128; LAS uchar* WXT = WAT + 32 * S128;
;     LAS float* SEG0 = (LAS float*)(WXT + 32 * S128); LAS float* HPREV = SEG0 + 16;
;     LAS uchar* CVS = F.lds + 65536 + w * 9216;
;     const int gw = F.vcu * 8 + w, NGW = F.G * 8; const bool cv_on = (u == F.vcu);
;     f32x4 cq0[4], cq1[4], cq2[4], cq3[4];
; #pragma unroll
;     for (int i = 0; i < 4; ++i) cq0[i] = cq1[i] = cq2[i] = cq3[i] = (f32x4){0.f, 0.f, 0.f, 0.f};
;     { const int j = tid & 31, kg = tid >> 5; float wv[8], xv[8];
; #pragma unroll
;       for (int i = 0; i < 8; ++i) { const size_t o = ((size_t)(nb * 128 + 8 * kg + i)) * 128 + qq * 32 + j; wv[i] = a.wa[o]; xv[i] = a.wx[o]; }
;       u32x4 p; p.x = pk2(wv[0], wv[1]); p.y = pk2(wv[2], wv[3]); p.z = pk2(wv[4], wv[5]); p.w = pk2(wv[6], wv[7]); *(LAS u32x4*)(WAT + j * S128 + kg * 16) = p;
;       p.x = pk2(xv[0], xv[1]); p.y = pk2(xv[2], xv[3]); p.z = pk2(xv[4], xv[5]); p.w = pk2(xv[6], xv[7]); *(LAS u32x4*)(WXT + j * S128 + kg * 16) = p; }
;     if (tid < 64) HPREV[(tid & 31) * 20 + (tid >> 5)] = 0.f;
;     const int c2 = tid & 63, rg = tid >> 6;
;     float cw[4][2], cbs[2];
; #pragma unroll
;     for (int j = 0; j < 2; ++j) { const int ch = cb + 2 * c2 + j; cbs[j] = a.conv_b[ch];
; #pragma unroll
;         for (int k = 0; k < 4; ++k) cw[k][j] = a.conv_w[k * 4096 + ch]; }
;     const int ltile = w & 3, jtile = w >> 2, l0_ = 16 * ltile, jj = 16 * jtile + fr, co = cb + qq * 32 + jj;
;     const float bav = a.ba[co], bxv = a.bx[co], sp8l2 = 8.0f * LOG2E * log1pf(__expf(-a.lam[co]));
;     const size_t rowbase = (size_t)b * SEQ;
;     const bf16* xcol = a.proj + C_XB + cb + 2 * c2;
;     const bf16* gbcol = a.proj + C_GB + co; bf16* obcol = a.outp + a.ob_col + co;
;     unsigned xr[11], gbr[4];
.LBB0_234:
	s_lshl_b32 s9, s92, 5
	s_and_b32 s2, s92, 3
	s_and_b32 s8, s9, 0xf80
	v_writelane_b32 v253, s2, 50
	s_lshl_b32 s2, s2, 5
	v_lshl_or_b32 v2, s8, 7, v152
	s_mov_b64 s[40:41], s[80:81]
	v_or3_b32 v2, s2, v2, v89
	v_readlane_b32 s76, v253, 3
	v_lshlrev_b32_e32 v2, 2, v2
	v_readlane_b32 s90, v253, 17
	v_readlane_b32 s91, v253, 18
	s_nop 4
	global_load_dword v3, v2, s[90:91]
	global_load_dword v6, v2, s[62:63]
	global_load_dword v4, v2, s[90:91] offset:512
	global_load_dword v7, v2, s[62:63] offset:512
	global_load_dword v5, v2, s[90:91] offset:1024
	global_load_dword v8, v2, s[62:63] offset:1024
	global_load_dword v9, v2, s[90:91] offset:1536
	global_load_dword v10, v2, s[62:63] offset:1536
	global_load_dword v11, v2, s[90:91] offset:2048
	global_load_dword v12, v2, s[62:63] offset:2048
	global_load_dword v13, v2, s[90:91] offset:2560
	global_load_dword v14, v2, s[62:63] offset:2560
	global_load_dword v15, v2, s[90:91] offset:3072
	global_load_dword v16, v2, s[62:63] offset:3072
	global_load_dword v17, v2, s[90:91] offset:3584
	global_load_dword v18, v2, s[62:63] offset:3584
	v_readlane_b32 s77, v253, 4
	v_readlane_b32 s78, v253, 5
	v_readlane_b32 s79, v253, 6
	v_readlane_b32 s80, v253, 7
	v_readlane_b32 s81, v253, 8
	v_readlane_b32 s82, v253, 9
	v_readlane_b32 s83, v253, 10
	v_readlane_b32 s84, v253, 11
	v_readlane_b32 s85, v253, 12
	v_readlane_b32 s86, v253, 13
	v_readlane_b32 s87, v253, 14
	v_readlane_b32 s88, v253, 15
	v_readlane_b32 s89, v253, 16
	s_waitcnt vmcnt(13)
	v_cvt_pk_bf16_f32 v2, v3, v4
	s_waitcnt vmcnt(9)
	v_cvt_pk_bf16_f32 v3, v5, v9
	s_waitcnt vmcnt(5)
	v_cvt_pk_bf16_f32 v4, v11, v13
	s_waitcnt vmcnt(1)
	v_cvt_pk_bf16_f32 v5, v15, v17
	ds_write_b128 v155, v[2:5] offset:36864
	v_cvt_pk_bf16_f32 v2, v6, v7
	v_cvt_pk_bf16_f32 v3, v8, v10
	v_cvt_pk_bf16_f32 v4, v12, v14
	s_waitcnt vmcnt(0)
	v_cvt_pk_bf16_f32 v5, v16, v18
	ds_write_b128 v155, v[2:5] offset:46080
	s_mov_b64 s[2:3], exec
	v_readlane_b32 s36, v252, 0
	v_readlane_b32 s37, v252, 1
	s_and_b64 s[36:37], s[2:3], s[36:37]
	s_mov_b64 exec, s[36:37]
	ds_write_b32 v91, v83 offset:55360
	s_or_b64 exec, exec, s[2:3]
	v_or_b32_e32 v2, s8, v93
	v_readlane_b32 s76, v253, 3
	v_lshlrev_b32_e32 v82, 2, v2
	v_readlane_b32 s86, v253, 13
	v_readlane_b32 s87, v253, 14
	s_and_b32 s2, s9, 0xfe0
	v_readlane_b32 s88, v253, 15
	v_lshl_add_u64 v[2:3], s[86:87], 0, v[82:83]
	s_mov_b64 s[100:101], 0x4000
	v_lshl_add_u64 v[4:5], v[2:3], 0, s[100:101]
	v_readlane_b32 s89, v253, 16
	s_mov_b64 s[100:101], 0x8000
	v_lshl_add_u64 v[6:7], v[2:3], 0, s[100:101]
	v_add_u32_e32 v9, s2, v1
	s_mov_b64 s[100:101], 0xc000
	v_lshl_add_u64 v[2:3], v[2:3], 0, s[100:101]
	global_load_dwordx2 v[100:101], v82, s[88:89]
	global_load_dwordx2 v[104:105], v82, s[86:87]
	global_load_dwordx2 v[106:107], v[4:5], off
	global_load_dwordx2 v[108:109], v[6:7], off
	global_load_dwordx2 v[110:111], v[2:3], off
	v_lshlrev_b32_e32 v2, 2, v9
	global_load_dword v165, v2, s[60:61]
	global_load_dword v167, v2, s[64:65]
	global_load_dword v8, v2, s[66:67]
	s_ashr_i32 s2, s92, 7
	v_readlane_b32 s82, v253, 9
	v_readlane_b32 s83, v253, 10
	s_ashr_i32 s3, s2, 31
	s_lshl_b64 s[82:83], s[2:3], 13
	s_lshl_b32 s96, s8, 1
	s_add_u32 s8, s82, -3
	s_addc_u32 s9, s83, -1
	v_lshl_add_u64 v[2:3], v[84:85], 0, s[96:97]
	v_lshl_add_u64 v[4:5], s[8:9], 0, v[86:87]
	v_mov_b32_e32 v10, 0
	v_readlane_b32 s77, v253, 4
	v_readlane_b32 s78, v253, 5
	v_readlane_b32 s79, v253, 6
	v_readlane_b32 s80, v253, 7
	v_readlane_b32 s81, v253, 8
	v_readlane_b32 s84, v253, 11
	v_readlane_b32 s85, v253, 12
	v_readlane_b32 s90, v253, 17
	v_readlane_b32 s91, v253, 18
	s_and_saveexec_b64 s[8:9], s[40:41]
	s_cbranch_execz .LBB0_238
	v_mad_u64_u32 v[6:7], s[36:37], v4, s33, v[2:3]
	v_mad_i32_i24 v7, v5, s33, v7
	global_load_dword v10, v[6:7], off
.LBB0_238:
	s_or_b64 exec, exec, s[8:9]
	s_and_saveexec_b64 s[8:9], s[40:41]
	s_xor_b64 s[8:9], exec, s[8:9]
	s_cbranch_execz .LBB0_240
	v_mad_u64_u32 v[6:7], s[36:37], v4, s33, v[2:3]
	v_mad_i32_i24 v7, v5, s33, v7
	s_mov_b64 s[100:101], 0xc000
	v_lshl_add_u64 v[6:7], v[6:7], 0, s[100:101]
	global_load_dword v11, v[6:7], off
	v_mad_u64_u32 v[6:7], s[36:37], v4, s33, 0
	v_mad_i32_i24 v7, v5, s33, v7
	s_andn2_saveexec_b64 s[8:9], s[8:9]
	s_cbranch_execnz .LBB0_241
	s_branch .LBB0_242

; #define LDS_BAR() do { asm volatile("s_waitcnt lgkmcnt(0)" ::: "memory"); __builtin_amdgcn_s_barrier(); asm volatile("" ::: "memory"); } while (0)
; #define RG_LOAD(n_) do { const long r0_ = (long)rowbase + (long)(n_) * 64; \
;         _Pragma("unroll") for (int i = 0; i < 11; ++i) xr[i] = ((n_) == 0 && 8 * rg - 3 + i < 0) ? 0u : *(const unsigned*)(xcol + (size_t)(r0_ + 8 * rg - 3 + i) * N1); } while (0)
; #define RG_LOADG(n_) do { const long r0_ = (long)rowbase + (long)(n_) * 64; \
;         _Pragma("unroll") for (int i = 0; i < 4; ++i) gbr[i] = *(const unsigned short*)(gbcol + (size_t)(r0_ + l0_ + 4 * fq + i) * N1); } while (0)
; #define RG_STAGE(xc_) do { LAS uchar* X_ = (xc_); \
;         _Pragma("unroll") for (int i = 0; i < 8; ++i) { f32x2 s2 = (f32x2){cbs[0], cbs[1]}; \
;             _Pragma("unroll") for (int k = 0; k < 4; ++k) s2 += (f32x2){cw[k][0], cw[k][1]} * (f32x2){bflo(xr[i + k]), bfhi(xr[i + k])}; \
;             *(LAS unsigned*)(X_ + (8 * rg + i) * S128 + c2 * 4) = pk2(s2.x, s2.y); } } while (0)
; DI void rglru_scan_unit(Frame& F, const Mix0Args& a, int u) {
;     ...
;     RG_LOAD(0);
;     RG_STAGE(XC0);
;     unsigned gb_cur[4];
;     RG_LOAD(1); RG_LOADG(0);
;     LDS_BAR();
.LBB0_242:
	s_or_b64 exec, exec, s[8:9]
	v_mov_b32_e32 v12, 0
	v_lshl_add_u64 v[4:5], v[2:3], 0, v[6:7]
	s_and_saveexec_b64 s[8:9], s[40:41]
	s_cbranch_execz .LBB0_244
	s_mov_b64 s[100:101], 0x18000
	v_lshl_add_u64 v[6:7], v[4:5], 0, s[100:101]
	global_load_dword v12, v[6:7], off
.LBB0_244:
	s_or_b64 exec, exec, s[8:9]
	v_or_b32_e32 v6, s82, v86
	v_mad_u64_u32 v[6:7], s[8:9], v6, s33, v[2:3]
	v_mad_i32_i24 v7, s83, v159, v7
	global_load_dword v13, v[6:7], off
	s_mov_b64 s[100:101], 0x30000
	v_lshl_add_u64 v[6:7], v[4:5], 0, s[100:101]
	s_mov_b32 s36, 0x60000
	global_load_dword v16, v[6:7], off
	s_mov_b64 s[100:101], 0x3c000
	v_lshl_add_u64 v[6:7], v[4:5], 0, s[100:101]
	s_waitcnt vmcnt(2)
	v_lshlrev_b32_e32 v14, 16, v12
	global_load_dword v17, v[6:7], off
	s_mov_b64 s[100:101], 0x48000
	v_lshl_add_u64 v[6:7], v[4:5], 0, s[100:101]
	v_and_b32_e32 v15, 0xffff0000, v12
	global_load_dword v18, v[6:7], off
	s_mov_b64 s[100:101], 0x54000
	v_lshl_add_u64 v[6:7], v[4:5], 0, s[100:101]
	v_lshlrev_b32_e32 v112, 1, v9
	global_load_dword v19, v[6:7], off
	v_add_co_u32_e32 v6, vcc, s36, v4
	v_readlane_b32 s8, v253, 55
	s_nop 0
	v_addc_co_u32_e32 v7, vcc, 0, v5, vcc
	global_load_dword v20, v[6:7], off
	s_mov_b64 s[100:101], 0x6c000
	v_lshl_add_u64 v[6:7], v[4:5], 0, s[100:101]
	v_mov_b32_e32 v113, v83
	global_load_dword v21, v[6:7], off
	s_mov_b64 s[100:101], 0x78000
	v_lshl_add_u64 v[4:5], v[4:5], 0, s[100:101]
	v_readlane_b32 s9, v253, 56
	global_load_dword v22, v[4:5], off
	v_lshlrev_b32_e32 v6, 16, v10
	v_and_b32_e32 v7, 0xffff0000, v10
	v_pk_fma_f32 v[6:7], v[104:105], v[6:7], v[100:101]
	v_lshlrev_b32_e32 v10, 16, v11
	v_and_b32_e32 v11, 0xffff0000, v11
	v_pk_fma_f32 v[6:7], v[106:107], v[10:11], v[6:7]
	v_lshl_add_u64 v[4:5], s[8:9], 0, v[112:113]
	v_pk_fma_f32 v[6:7], v[108:109], v[14:15], v[6:7]
	v_readlane_b32 s3, v253, 2
	s_cmp_lg_u32 s92, s3
	s_mov_b32 s3, 0x18000
	s_cselect_b64 s[40:41], -1, 0
	s_mov_b32 s93, 0
	v_writelane_b32 v252, s40, 4
	s_waitcnt vmcnt(7)
	v_lshlrev_b32_e32 v12, 16, v13
	v_and_b32_e32 v13, 0xffff0000, v13
	v_pk_fma_f32 v[6:7], v[110:111], v[12:13], v[6:7]
	v_writelane_b32 v252, s41, 5
	v_cvt_pk_bf16_f32 v9, v6, v7
	v_pk_fma_f32 v[6:7], v[104:105], v[10:11], v[100:101]
	s_waitcnt vmcnt(6)
	v_lshlrev_b32_e32 v10, 16, v16
	v_pk_fma_f32 v[6:7], v[106:107], v[14:15], v[6:7]
	v_and_b32_e32 v11, 0xffff0000, v16
	v_pk_fma_f32 v[6:7], v[108:109], v[12:13], v[6:7]
	v_add_u32_e32 v16, 0x400, v156
	v_pk_fma_f32 v[6:7], v[110:111], v[10:11], v[6:7]
	s_nop 0
	v_cvt_pk_bf16_f32 v6, v6, v7
	ds_write2_b32 v156, v9, v6 offset1:72
	v_pk_fma_f32 v[6:7], v[104:105], v[14:15], v[100:101]
	s_waitcnt vmcnt(5)
	v_lshlrev_b32_e32 v14, 16, v17
	v_pk_fma_f32 v[6:7], v[106:107], v[12:13], v[6:7]
	v_and_b32_e32 v15, 0xffff0000, v17
	v_pk_fma_f32 v[6:7], v[108:109], v[10:11], v[6:7]
	s_nop 0
	v_pk_fma_f32 v[6:7], v[110:111], v[14:15], v[6:7]
	s_nop 0
	v_cvt_pk_bf16_f32 v9, v6, v7
	v_pk_fma_f32 v[6:7], v[104:105], v[12:13], v[100:101]
	s_waitcnt vmcnt(4)
	v_lshlrev_b32_e32 v12, 16, v18
	v_pk_fma_f32 v[6:7], v[106:107], v[10:11], v[6:7]
	v_and_b32_e32 v13, 0xffff0000, v18
	v_pk_fma_f32 v[6:7], v[108:109], v[14:15], v[6:7]
	s_nop 0
	v_pk_fma_f32 v[6:7], v[110:111], v[12:13], v[6:7]
	s_nop 0
	v_cvt_pk_bf16_f32 v6, v6, v7
	ds_write2_b32 v156, v9, v6 offset0:144 offset1:216
	v_pk_fma_f32 v[6:7], v[104:105], v[10:11], v[100:101]
	s_waitcnt vmcnt(3)
	v_lshlrev_b32_e32 v10, 16, v19
	v_pk_fma_f32 v[6:7], v[106:107], v[14:15], v[6:7]
	v_and_b32_e32 v11, 0xffff0000, v19
	v_pk_fma_f32 v[6:7], v[108:109], v[12:13], v[6:7]
	s_nop 0
	v_pk_fma_f32 v[6:7], v[110:111], v[10:11], v[6:7]
	s_nop 0
	v_cvt_pk_bf16_f32 v9, v6, v7
	v_pk_fma_f32 v[6:7], v[104:105], v[14:15], v[100:101]
	s_waitcnt vmcnt(2)
	v_lshlrev_b32_e32 v14, 16, v20
	v_pk_fma_f32 v[6:7], v[106:107], v[12:13], v[6:7]
	v_and_b32_e32 v15, 0xffff0000, v20
	v_pk_fma_f32 v[6:7], v[108:109], v[10:11], v[6:7]
	s_nop 0
	v_pk_fma_f32 v[6:7], v[110:111], v[14:15], v[6:7]
	s_nop 0
	v_cvt_pk_bf16_f32 v6, v6, v7
	ds_write2_b32 v16, v9, v6 offset0:32 offset1:104
	v_pk_fma_f32 v[6:7], v[104:105], v[12:13], v[100:101]
	s_waitcnt vmcnt(1)
	v_lshlrev_b32_e32 v12, 16, v21
	v_pk_fma_f32 v[6:7], v[106:107], v[10:11], v[6:7]
	v_and_b32_e32 v13, 0xffff0000, v21
	v_pk_fma_f32 v[6:7], v[108:109], v[14:15], v[6:7]
	s_nop 0
	v_pk_fma_f32 v[6:7], v[110:111], v[12:13], v[6:7]
	s_nop 0
	v_cvt_pk_bf16_f32 v9, v6, v7
	v_pk_fma_f32 v[6:7], v[104:105], v[10:11], v[100:101]
	s_waitcnt vmcnt(0)
	v_lshlrev_b32_e32 v10, 16, v22
	v_pk_fma_f32 v[6:7], v[106:107], v[14:15], v[6:7]
	v_and_b32_e32 v11, 0xffff0000, v22
	v_pk_fma_f32 v[6:7], v[108:109], v[12:13], v[6:7]
	s_nop 0
	v_pk_fma_f32 v[6:7], v[110:111], v[10:11], v[6:7]
	s_nop 0
	v_cvt_pk_bf16_f32 v6, v6, v7
	ds_write2_b32 v16, v9, v6 offset0:176 offset1:248
	v_or_b32_e32 v6, s82, v88
	v_mad_u64_u32 v[2:3], s[8:9], v6, s33, v[2:3]
	v_mad_i32_i24 v3, s83, v159, v3
	v_add_co_u32_e32 v6, vcc, s33, v2
	global_load_dword v130, v[2:3], off
	s_nop 0
	v_addc_co_u32_e32 v7, vcc, 0, v3, vcc
	global_load_dword v132, v[6:7], off
	v_add_co_u32_e32 v6, vcc, s3, v2
	s_mov_b32 s3, 0x24000
	s_nop 0
	v_addc_co_u32_e32 v7, vcc, 0, v3, vcc
	global_load_dword v134, v[6:7], off
	v_add_co_u32_e32 v6, vcc, s3, v2
	s_mov_b32 s3, 0x30000
	s_nop 0
	v_addc_co_u32_e32 v7, vcc, 0, v3, vcc
	global_load_dword v169, v[6:7], off
	v_add_co_u32_e32 v6, vcc, s3, v2
	s_mov_b32 s3, 0x3c000
	s_nop 0
	v_addc_co_u32_e32 v7, vcc, 0, v3, vcc
	global_load_dword v170, v[6:7], off
	v_add_co_u32_e32 v6, vcc, s3, v2
	s_mov_b32 s3, 0x48000
	s_nop 0
	v_addc_co_u32_e32 v7, vcc, 0, v3, vcc
	global_load_dword v171, v[6:7], off
	v_add_co_u32_e32 v6, vcc, s3, v2
	s_mov_b32 s3, 0x54000
	s_nop 0
	v_addc_co_u32_e32 v7, vcc, 0, v3, vcc
	global_load_dword v172, v[6:7], off
	v_add_co_u32_e32 v6, vcc, s3, v2
	s_mov_b32 s3, 0x6c000
	s_nop 0
	v_addc_co_u32_e32 v7, vcc, 0, v3, vcc
	global_load_dword v173, v[6:7], off
	v_add_co_u32_e32 v6, vcc, s36, v2
	s_nop 1
	v_addc_co_u32_e32 v7, vcc, 0, v3, vcc
	global_load_dword v174, v[6:7], off
	v_add_co_u32_e32 v6, vcc, s3, v2
	s_mov_b32 s3, 0x78000
	s_nop 0
	v_addc_co_u32_e32 v7, vcc, 0, v3, vcc
	v_add_co_u32_e32 v2, vcc, s3, v2
	global_load_dword v175, v[6:7], off
	s_nop 0
	v_addc_co_u32_e32 v3, vcc, 0, v3, vcc
	global_load_dword v176, v[2:3], off
	v_or_b32_e32 v2, s82, v90
	v_mad_u64_u32 v[6:7], s[8:9], v2, s33, v[4:5]
	v_mad_i32_i24 v7, s83, v159, v7
	v_add_co_u32_e32 v4, vcc, s33, v6
	global_load_ushort v2, v[6:7], off
	s_nop 0
	v_addc_co_u32_e32 v5, vcc, 0, v7, vcc
	global_load_ushort v3, v[4:5], off
	s_mov_b64 s[100:101], 0x18000
	v_lshl_add_u64 v[4:5], v[6:7], 0, s[100:101]
	s_mov_b32 s3, 0
	s_mov_b64 s[100:101], 0x24000
	v_lshl_add_u64 v[6:7], v[6:7], 0, s[100:101]
	global_load_ushort v4, v[4:5], off
	global_load_ushort v5, v[6:7], off
	s_waitcnt lgkmcnt(0)
	s_barrier
	s_and_b64 vcc, exec, s[40:41]
	s_cbranch_vccnz .LBB0_246
	v_readlane_b32 s3, v253, 62

; #define RG_LOAD(n_) do { const long r0_ = (long)rowbase + (long)(n_) * 64; \
;         _Pragma("unroll") for (int i = 0; i < 11; ++i) xr[i] = ((n_) == 0 && 8 * rg - 3 + i < 0) ? 0u : *(const unsigned*)(xcol + (size_t)(r0_ + 8 * rg - 3 + i) * N1); } while (0)
; #define RG_LOADG(n_) do { const long r0_ = (long)rowbase + (long)(n_) * 64; \
;         _Pragma("unroll") for (int i = 0; i < 4; ++i) gbr[i] = *(const unsigned short*)(gbcol + (size_t)(r0_ + l0_ + 4 * fq + i) * N1); } while (0)
; DI void rglru_scan_unit(Frame& F, const Mix0Args& a, int u) {
;     ...
;         if (n + 2 < NCH) RG_LOAD(n + 2);
;         if (n + 1 < NCH) RG_LOADG(n + 1);
;         if constexpr (CV) { int idx = (n >> 2) * NGW + gw; idx = idx < CV_NIT ? idx : idx - CV_NIT;
;             if constexpr (CQ == 0) cv_issue_q(a.cv, idx, lane, cq0, 0); else if constexpr (CQ == 1) cv_issue_q(a.cv, idx, lane, cq1, 4); else if constexpr (CQ == 2) cv_issue_q(a.cv, idx, lane, cq2, 8); else cv_issue_q(a.cv, idx, lane, cq3, 12); }
.LBB0_263:
	s_waitcnt vmcnt(4)
	v_lshl_add_u64 v[50:51], v[120:121], 0, s[8:9]
	s_mov_b64 s[100:101], 0x258e4000
	v_lshl_add_u64 v[2:3], v[50:51], 0, s[100:101]
	v_lshl_add_u64 v[52:53], v[118:119], 0, s[8:9]
	global_load_dword v18, v[2:3], off
	s_mov_b64 s[100:101], 0x258f0000
	v_lshl_add_u64 v[2:3], v[50:51], 0, s[100:101]
	s_mul_i32 s36, s36, s94
	global_load_dword v19, v[2:3], off
	s_mov_b64 s[100:101], 0x258fc000
	v_lshl_add_u64 v[2:3], v[50:51], 0, s[100:101]
	s_add_i32 s36, s36, s95
	global_load_dword v20, v[2:3], off
	s_mov_b64 s[100:101], 0x25908000
	v_lshl_add_u64 v[2:3], v[50:51], 0, s[100:101]
	s_add_i32 s37, s36, 0xffff7780
	global_load_dword v21, v[2:3], off
	s_mov_b64 s[100:101], 0x25914000
	v_lshl_add_u64 v[2:3], v[50:51], 0, s[100:101]
	s_cmp_lt_i32 s36, 0x8880
	global_load_dword v22, v[2:3], off
	s_mov_b64 s[100:101], 0x25920000
	v_lshl_add_u64 v[2:3], v[50:51], 0, s[100:101]
	s_cselect_b32 s87, s36, s37
	global_load_dword v23, v[2:3], off
	s_mov_b64 s[100:101], 0x2592c000
	v_lshl_add_u64 v[2:3], v[50:51], 0, s[100:101]
	s_cmpk_gt_i32 s87, 0x1fff
	global_load_dword v24, v[2:3], off
	s_mov_b64 s[100:101], 0x25938000
	v_lshl_add_u64 v[2:3], v[50:51], 0, s[100:101]
	s_cselect_b64 s[40:41], -1, 0
	global_load_dword v27, v[2:3], off
	s_mov_b64 s[100:101], 0x25944000
	v_lshl_add_u64 v[2:3], v[50:51], 0, s[100:101]
	s_cmpk_lt_i32 s87, 0x2000
	global_load_dword v25, v[2:3], off
	s_mov_b64 s[100:101], 0x25950000
	v_lshl_add_u64 v[2:3], v[50:51], 0, s[100:101]
	global_load_dword v26, v[2:3], off
	s_mov_b64 s[100:101], 0x2595c000
	v_lshl_add_u64 v[2:3], v[50:51], 0, s[100:101]
	global_load_dword v28, v[2:3], off
	s_mov_b64 s[100:101], 0x2560a000
	v_lshl_add_u64 v[2:3], v[52:53], 0, s[100:101]
	global_load_ushort v37, v[2:3], off
	s_mov_b64 s[100:101], 0x25616000
	v_lshl_add_u64 v[2:3], v[52:53], 0, s[100:101]
	global_load_ushort v36, v[2:3], off
	s_mov_b64 s[100:101], 0x25622000
	v_lshl_add_u64 v[2:3], v[52:53], 0, s[100:101]
	global_load_ushort v34, v[2:3], off
	s_mov_b64 s[100:101], 0x2562e000
	v_lshl_add_u64 v[2:3], v[52:53], 0, s[100:101]
	global_load_ushort v35, v[2:3], off
	s_cbranch_scc1 .LBB0_266
	s_cmpk_gt_u32 s87, 0x687f
	s_cbranch_scc0 .LBB0_267
	s_add_i32 s84, s87, 0xffff9780
	s_mov_b64 s[36:37], s[52:53]
	s_movk_i32 s78, 0x1000
	s_cbranch_execz .LBB0_268
	s_branch .LBB0_269

; #define LAS __attribute__((address_space(3)))
; DI float bf2f(unsigned h) { return __uint_as_float(h << 16); }
; DI float fexp2(float x) { return __builtin_amdgcn_exp2f(x); }
; DI float fsigmoid(float x) { return frcp(1.0f + fexp2(-LOG2E * x)); }
; DI void cv_issue_q(const CvJob& j, int idx, int lane, f32x4 (&v)[4], int r0) {
;     const float* W; int K, N, item; bf16* WT; const float* ks; cv_decode(j, idx, W, K, N, WT, ks, item);
;     const int nblk = N / 64, kb = item / nblk, nb = item % nblk, k0 = 64 * kb, n0 = 64 * nb, q = lane >> 4, c16 = lane & 15;
;     const char* ub = (const char*)(W + (size_t)(k0 + r0) * N + n0);
;     const unsigned vo = (unsigned)((16 * q) * N + 4 * c16) * 4u;
; #pragma unroll
;     for (int i = 0; i < 4; ++i) v[i] = *(const f32x4*)(ub + (size_t)i * N * 4 + vo);
; }
; DI void rglru_scan_unit(Frame& F, const Mix0Args& a, int u) {
;     ...
;         { bf16x8 xf[4], waf[4], wxf[4]; unsigned xcr[4];
; #pragma unroll
;           for (int ks = 0; ks < 4; ++ks) { xf[ks] = *(const LAS bf16x8*)(XCc + (l0_ + fr) * S128 + ks * 64 + fq * 16);
;               waf[ks] = *(const LAS bf16x8*)(WAT + (16 * jtile + fr) * S128 + ks * 64 + fq * 16); wxf[ks] = *(const LAS bf16x8*)(WXT + (16 * jtile + fr) * S128 + ks * 64 + fq * 16); }
; #pragma unroll
;           for (int r = 0; r < 4; ++r) xcr[r] = *(const LAS unsigned short*)(XCc + (l0_ + 4 * fq + r) * S128 + (qq * 32 + jj) * 2);
;           f32x4 R = zero4, I = zero4;
; #pragma unroll
;           for (int ks = 0; ks < 4; ++ks) { R = __builtin_amdgcn_mfma_f32_16x16x32_bf16(xf[ks], waf[ks], R, 0, 0, 0); I = __builtin_amdgcn_mfma_f32_16x16x32_bf16(xf[ks], wxf[ks], I, 0, 0, 0); }
; #pragma unroll
;           for (int r = 0; r < 4; ++r) {
;               const float rr = fsigmoid(R[r] + bav), ig = fsigmoid(I[r] + bxv);
;               const float aa = fexp2(-sp8l2 * rr); const float om = __builtin_fmaf(-aa, aa, 1.0f);
;               av[r] = aa; uv[r] = __builtin_sqrtf(om) * (ig * bf2f(xcr[r]));
;               Hseg = aa * Hseg + uv[r]; Aseg *= aa; } }
.LBB0_269:
	s_lshr_b32 s79, s78, 6
	v_cvt_f32_u32_e32 v2, s79
	s_sub_i32 s90, 0, s79
	s_abs_i32 s89, s84
	s_ashr_i32 s88, s84, 31
	v_rcp_iflag_f32_e32 v2, v2
	v_mul_u32_u24_e32 v29, s78, v102
	v_or_b32_e32 v29, v29, v125
	v_lshlrev_b32_e32 v82, 2, v29
	v_mul_f32_e32 v2, 0x4f7ffffe, v2
	v_cvt_u32_f32_e32 v2, v2
	ds_read_b128 v[6:9], v103 offset:36864
	v_readfirstlane_b32 s91, v2
	s_mul_i32 s90, s90, s91
	s_mul_hi_u32 s90, s91, s90
	s_add_i32 s91, s91, s90
	s_mul_hi_u32 s90, s89, s91
	s_mul_i32 s91, s90, s79
	s_sub_i32 s89, s89, s91
	s_add_i32 vcc_lo, s90, 1
	s_sub_i32 s91, s89, s79
	s_cmp_ge_u32 s89, s79
	s_cselect_b32 s90, vcc_lo, s90
	s_cselect_b32 s89, s91, s89
	s_add_i32 s91, s90, 1
	ds_read_b128 v[2:5], v164
	s_cmp_ge_u32 s89, s79
	s_cselect_b32 s89, s91, s90
	s_xor_b32 s89, s89, s88
	s_sub_i32 s88, s89, s88
	s_mul_i32 s79, s88, s79
	s_lshl_b32 s88, s88, 6
	s_sub_i32 s79, s84, s79
	s_mul_hi_i32 s89, s88, s78
	s_mul_i32 s88, s88, s78
	s_lshl_b32 s90, s79, 6
	s_lshl_b64 s[88:89], s[88:89], 2
	s_add_u32 s79, s36, s88
	ds_read_b128 v[10:13], v103 offset:46080
	ds_read_b128 v[14:17], v164 offset:64
	ds_read_b128 v[30:33], v103 offset:36928
	ds_read_b128 v[38:41], v103 offset:46144
	ds_read_b128 v[42:45], v164 offset:128
	s_addc_u32 s84, s37, s89
	s_ashr_i32 s91, s90, 31
	s_waitcnt lgkmcnt(5)
	v_mfma_f32_16x16x32_bf16 v[6:9], v[2:5], v[6:9], 0
	s_lshl_b64 s[36:37], s[90:91], 2
	s_add_u32 s36, s79, s36
	s_addc_u32 s37, s84, s37
	s_waitcnt lgkmcnt(4)
	v_mfma_f32_16x16x32_bf16 v[10:13], v[2:5], v[10:13], 0
	global_load_dwordx4 v[2:5], v82, s[36:37]
	s_lshl_b32 s96, s78, 2
	v_lshl_add_u64 v[54:55], s[36:37], 0, v[82:83]
	s_waitcnt lgkmcnt(2)
	v_mfma_f32_16x16x32_bf16 v[6:9], v[14:17], v[30:33], v[6:9]
	ds_read_b128 v[30:33], v103 offset:36992
	ds_read_b128 v[46:49], v164 offset:192
	s_waitcnt lgkmcnt(3)
	v_mfma_f32_16x16x32_bf16 v[14:17], v[14:17], v[38:41], v[10:13]
	ds_read_b128 v[38:41], v103 offset:37056
	s_waitcnt lgkmcnt(2)
	v_mfma_f32_16x16x32_bf16 v[30:33], v[42:45], v[30:33], v[6:9]
	v_lshl_add_u64 v[10:11], v[54:55], 0, s[96:97]
	v_lshl_add_u64 v[58:59], v[10:11], 0, s[96:97]
	s_nop 0
	global_load_dwordx4 v[6:9], v[10:11], off
	s_nop 0
	global_load_dwordx4 v[10:13], v[58:59], off
	s_waitcnt lgkmcnt(0)
	v_mfma_f32_16x16x32_bf16 v[30:33], v[46:49], v[38:41], v[30:33]
	ds_read_b128 v[54:57], v103 offset:46208
	ds_read_b128 v[38:41], v103 offset:46272
	v_lshl_add_u64 v[58:59], v[58:59], 0, s[96:97]
	s_waitcnt lgkmcnt(1)
	v_mfma_f32_16x16x32_bf16 v[42:45], v[42:45], v[54:57], v[14:17]
	s_nop 2
	v_add_f32_e32 v29, v165, v30
	v_mul_f32_e32 v29, 0xbfb8aa3b, v29
	v_exp_f32_e32 v29, v29
	s_waitcnt lgkmcnt(0)
	v_mfma_f32_16x16x32_bf16 v[38:41], v[46:49], v[38:41], v[42:45]
	v_add_f32_e32 v31, v165, v31
	v_mul_f32_e32 v31, 0xbfb8aa3b, v31
	v_add_f32_e32 v14, 1.0, v29
	v_rcp_f32_e32 v29, v14
	v_exp_f32_e32 v31, v31
	global_load_dwordx4 v[14:17], v[58:59], off
	ds_read_u16 v42, v113
	ds_read_u16 v43, v113 offset:288
	ds_read_u16 v44, v113 offset:576
	ds_read_u16 v45, v113 offset:864
	v_mul_f32_e64 v29, v29, -v168
	v_exp_f32_e32 v70, v29
	v_add_f32_e32 v29, v167, v38
	v_mul_f32_e32 v29, 0xbfb8aa3b, v29
	v_exp_f32_e32 v29, v29
	v_fma_f32 v30, -v70, v70, 1.0
	v_mul_f32_e32 v38, 0x4f800000, v30
	v_cmp_gt_f32_e32 vcc, s42, v30
	v_add_f32_e32 v29, 1.0, v29
	v_rcp_f32_e32 v29, v29
	v_cndmask_b32_e32 v30, v30, v38, vcc
	v_sqrt_f32_e32 v38, v30
	v_add_f32_e32 v31, 1.0, v31
	v_rcp_f32_e32 v31, v31
	v_add_f32_e32 v32, v165, v32
	v_add_u32_e32 v46, -1, v38
	v_fma_f32 v47, -v46, v38, v30
	v_cmp_ge_f32_e64 s[36:37], 0, v47
	v_add_u32_e32 v47, 1, v38
	v_mul_f32_e32 v32, 0xbfb8aa3b, v32
	v_cndmask_b32_e64 v46, v38, v46, s[36:37]
	v_fma_f32 v38, -v47, v38, v30
	v_cmp_lt_f32_e64 s[36:37], 0, v38
	v_exp_f32_e32 v32, v32
	v_add_f32_e32 v33, v165, v33
	v_cndmask_b32_e64 v38, v46, v47, s[36:37]
	v_mul_f32_e32 v46, 0x37800000, v38
	v_cndmask_b32_e32 v38, v38, v46, vcc
	v_cmp_class_f32_e32 vcc, v30, v158
	v_add_f32_e32 v32, 1.0, v32
	v_rcp_f32_e32 v32, v32
	v_cndmask_b32_e32 v30, v38, v30, vcc
	s_waitcnt lgkmcnt(3)
	v_lshlrev_b32_e32 v38, 16, v42
	v_mul_f32_e32 v29, v29, v38
	v_mul_f32_e32 v71, v29, v30
	v_mul_f32_e64 v29, v31, -v168
	v_exp_f32_e32 v72, v29
	v_add_f32_e32 v29, v167, v39
	v_mul_f32_e32 v29, 0xbfb8aa3b, v29
	v_exp_f32_e32 v29, v29
	v_fma_f32 v30, -v72, v72, 1.0
	v_mul_f32_e32 v31, 0x4f800000, v30
	v_cmp_gt_f32_e32 vcc, s42, v30
	v_add_f32_e32 v29, 1.0, v29
	v_rcp_f32_e32 v29, v29
	v_cndmask_b32_e32 v30, v30, v31, vcc
	v_sqrt_f32_e32 v31, v30
	v_mul_f32_e32 v33, 0xbfb8aa3b, v33
	v_exp_f32_e32 v33, v33
	v_fma_f32 v38, 0, v70, v71
	v_add_u32_e32 v39, -1, v31
	v_fma_f32 v42, -v39, v31, v30
	v_cmp_ge_f32_e64 s[36:37], 0, v42
	v_add_u32_e32 v42, 1, v31
	v_add_f32_e32 v33, 1.0, v33
	v_cndmask_b32_e64 v39, v31, v39, s[36:37]
	v_fma_f32 v31, -v42, v31, v30
	v_cmp_lt_f32_e64 s[36:37], 0, v31
	v_rcp_f32_e32 v33, v33
	s_nop 0
	v_cndmask_b32_e64 v31, v39, v42, s[36:37]
	v_mul_f32_e32 v39, 0x37800000, v31
	v_cndmask_b32_e32 v31, v31, v39, vcc
	v_cmp_class_f32_e32 vcc, v30, v158
	s_nop 1
	v_cndmask_b32_e32 v30, v31, v30, vcc
	s_waitcnt lgkmcnt(2)
	v_lshlrev_b32_e32 v31, 16, v43
	v_mul_f32_e32 v29, v29, v31
	v_mul_f32_e32 v73, v29, v30
	v_mul_f32_e64 v30, v32, -v168
	v_exp_f32_e32 v74, v30
	v_add_f32_e32 v30, v167, v40
	v_mul_f32_e32 v30, 0xbfb8aa3b, v30
	v_exp_f32_e32 v30, v30
	v_fma_f32 v31, -v74, v74, 1.0
	v_mul_f32_e32 v32, 0x4f800000, v31
	v_cmp_gt_f32_e32 vcc, s42, v31
	v_add_f32_e32 v30, 1.0, v30
	v_rcp_f32_e32 v30, v30
	v_cndmask_b32_e32 v31, v31, v32, vcc
	v_sqrt_f32_e32 v32, v31
	v_fma_f32 v29, v72, v38, v73
	v_mul_f32_e32 v38, v70, v72
	v_add_u32_e32 v39, -1, v32
	v_fma_f32 v40, -v39, v32, v31
	v_cmp_ge_f32_e64 s[36:37], 0, v40
	v_add_u32_e32 v40, 1, v32
	s_nop 0
	v_cndmask_b32_e64 v39, v32, v39, s[36:37]
	v_fma_f32 v32, -v40, v32, v31
	v_cmp_lt_f32_e64 s[36:37], 0, v32
	s_nop 1
	v_cndmask_b32_e64 v32, v39, v40, s[36:37]
	v_mul_f32_e32 v39, 0x37800000, v32
	v_cndmask_b32_e32 v32, v32, v39, vcc
	v_cmp_class_f32_e32 vcc, v31, v158
	s_nop 1
	v_cndmask_b32_e32 v31, v32, v31, vcc
	s_waitcnt lgkmcnt(1)
; #define LAS __attribute__((address_space(3)))
; DI float bf2f(unsigned h) { return __uint_as_float(h << 16); }
; DI unsigned pk2(float lo, float hi) { f32x2 v = {lo, hi}; bf16v2 b = __builtin_convertvector(v, bf16v2); return __builtin_bit_cast(unsigned, b); }
; DI float fsilu(float x) { return x * fsigmoid(x); }
; #define LDS_BAR() do { asm volatile("s_waitcnt lgkmcnt(0)" ::: "memory"); __builtin_amdgcn_s_barrier(); asm volatile("" ::: "memory"); } while (0)
; DI void rglru_scan_unit(Frame& F, const Mix0Args& a, int u) {
;     ...
;         const int sgi = ltile * 4 + fq;
;         SEGA[jj * 20 + sgi] = Aseg; SEGH[jj * 20 + sgi] = Hseg;
;         LDS_BAR();
;         float carry = HPREV[jj * 20 + (n & 1)]; float sa[15], sh[15];
;         { f32x4 a4[4], h4[4];
; #pragma unroll
;           for (int i = 0; i < 4; ++i) { a4[i] = *(const LAS f32x4*)(SEGA + jj * 20 + 4 * i); h4[i] = *(const LAS f32x4*)(SEGH + jj * 20 + 4 * i); }
; #pragma unroll
;           for (int s = 0; s < 15; ++s) { sa[s] = a4[s >> 2][s & 3]; sh[s] = h4[s >> 2][s & 3]; } }
; #pragma unroll
;         for (int s = 0; s < 15; ++s) carry = (s < sgi) ? sa[s] * carry + sh[s] : carry;
; #pragma unroll
;         for (int r = 0; r < 4; ++r) { carry = av[r] * carry + uv[r];
;             const float o = carry * fsilu(bf2f(gb_cur[r]));
;             obcol[(row0 + l0_ + 4 * fq + r) * a.out_ld] = (bf16)(pk2(o, 0.f) & 0xffffu); }
;         if (sgi == 15) HPREV[jj * 20 + ((n + 1) & 1)] = carry;
	v_lshlrev_b32_e32 v32, 16, v44
	v_mul_f32_e32 v30, v30, v32
	v_mul_f32_e32 v75, v30, v31
	v_fma_f32 v30, v74, v29, v75
	v_mul_f32_e64 v29, v33, -v168
	v_exp_f32_e32 v76, v29
	v_add_f32_e32 v29, v167, v41
	v_mul_f32_e32 v29, 0xbfb8aa3b, v29
	v_exp_f32_e32 v29, v29
	v_fma_f32 v31, -v76, v76, 1.0
	v_mul_f32_e32 v32, 0x4f800000, v31
	v_cmp_gt_f32_e32 vcc, s42, v31
	v_mul_f32_e32 v33, v74, v38
	v_add_f32_e32 v29, 1.0, v29
	v_cndmask_b32_e32 v31, v31, v32, vcc
	v_sqrt_f32_e32 v32, v31
	v_rcp_f32_e32 v29, v29
	v_add_u32_e32 v38, -1, v32
	v_fma_f32 v39, -v38, v32, v31
	v_cmp_ge_f32_e64 s[36:37], 0, v39
	v_add_u32_e32 v39, 1, v32
	s_nop 0
	v_cndmask_b32_e64 v38, v32, v38, s[36:37]
	v_fma_f32 v32, -v39, v32, v31
	v_cmp_lt_f32_e64 s[36:37], 0, v32
	s_nop 1
	v_cndmask_b32_e64 v32, v38, v39, s[36:37]
	v_mul_f32_e32 v38, 0x37800000, v32
	v_cndmask_b32_e32 v32, v32, v38, vcc
	v_cmp_class_f32_e32 vcc, v31, v158
	s_mov_b32 s36, 0x25300000
	s_nop 0
	v_cndmask_b32_e32 v31, v32, v31, vcc
	s_waitcnt lgkmcnt(0)
	v_lshlrev_b32_e32 v32, 16, v45
	v_mul_f32_e32 v29, v29, v32
	v_mul_f32_e32 v29, v29, v31
	v_fma_f32 v30, v76, v30, v29
	v_mul_f32_e32 v31, v76, v33
	ds_write2st64_b32 v150, v31, v30 offset0:216 offset1:226
	s_waitcnt lgkmcnt(0)
	s_barrier
	ds_read_b32 v77, v149 offset:55360
	ds_read_b128 v[30:33], v149 offset:57856
	ds_read_b128 v[38:41], v149 offset:57872
	ds_read_b128 v[42:45], v149 offset:57888
	ds_read_b128 v[46:49], v149 offset:55296
	ds_read_b128 v[54:57], v149 offset:55312
	ds_read_b128 v[58:61], v149 offset:55328
	ds_read_b128 v[62:65], v149 offset:55344
	ds_read_b128 v[66:69], v149 offset:57904
	s_waitcnt lgkmcnt(4)
	v_fma_f32 v30, v77, v46, v30
	v_cndmask_b32_e64 v30, v30, v77, s[10:11]
	v_fma_f32 v31, v47, v30, v31
	v_cndmask_b32_e64 v30, v30, v31, s[12:13]
	v_fma_f32 v31, v48, v30, v32
	v_cndmask_b32_e64 v30, v30, v31, s[14:15]
	v_fmac_f32_e32 v33, v49, v30
	v_cndmask_b32_e64 v30, v33, v30, s[0:1]
	s_waitcnt lgkmcnt(3)
	v_fma_f32 v31, v54, v30, v38
	v_cndmask_b32_e64 v30, v30, v31, s[16:17]
	v_fma_f32 v31, v55, v30, v39
	v_cndmask_b32_e64 v30, v30, v31, s[18:19]
	v_fma_f32 v31, v56, v30, v40
	v_cndmask_b32_e64 v30, v30, v31, s[20:21]
	v_fmac_f32_e32 v41, v57, v30
	v_cndmask_b32_e64 v30, v30, v41, s[38:39]
	s_waitcnt lgkmcnt(2)
	v_fma_f32 v31, v58, v30, v42
	v_cndmask_b32_e64 v30, v30, v31, s[22:23]
	v_fma_f32 v31, v59, v30, v43
	v_cndmask_b32_e64 v30, v30, v31, s[24:25]
	v_fma_f32 v31, v60, v30, v44
	v_cndmask_b32_e64 v30, v30, v31, s[26:27]
	v_lshlrev_b32_e32 v32, 16, v181
	v_fmac_f32_e32 v45, v61, v30
	v_mul_f32_e32 v33, 0xbfb8aa3b, v32
	v_cndmask_b32_e64 v30, v30, v45, s[4:5]
	v_exp_f32_e32 v33, v33
	s_waitcnt lgkmcnt(0)
	v_fma_f32 v31, v62, v30, v66
	v_cndmask_b32_e64 v30, v30, v31, s[28:29]
	v_fma_f32 v31, v63, v30, v67
	v_cndmask_b32_e64 v30, v30, v31, s[30:31]
	v_add_f32_e32 v31, 1.0, v33
	v_rcp_f32_e32 v31, v31
	v_fmac_f32_e32 v68, v64, v30
	v_cndmask_b32_e64 v30, v30, v68, s[34:35]
	v_fmac_f32_e32 v71, v70, v30
	v_mul_f32_e32 v30, v31, v32
	v_mul_f32_e32 v30, v30, v71
	v_lshlrev_b32_e32 v33, 16, v180
	v_cvt_pk_bf16_f32 v32, v30, s0
	v_mul_f32_e32 v30, 0xbfb8aa3b, v33
	v_exp_f32_e32 v38, v30
	v_lshl_add_u64 v[66:67], v[116:117], 0, s[8:9]
	v_add_co_u32_e32 v30, vcc, s36, v66
	v_fmac_f32_e32 v73, v72, v71
	s_nop 0
	v_addc_co_u32_e32 v31, vcc, 0, v67, vcc
	global_store_short v[30:31], v32, off
	v_add_f32_e32 v30, 1.0, v38
	v_rcp_f32_e32 v30, v30
	v_lshlrev_b32_e32 v32, 16, v179
	v_mul_f32_e32 v31, 0xbfb8aa3b, v32
	v_exp_f32_e32 v31, v31
	v_mul_f32_e32 v30, v30, v33
	v_mul_f32_e32 v30, v30, v73
	v_cvt_pk_bf16_f32 v33, v30, s0
	v_add_f32_e32 v30, 1.0, v31
	v_rcp_f32_e32 v38, v30
	s_mov_b32 s36, 0x2530c000
	v_add_co_u32_e32 v30, vcc, s36, v66
	v_fmac_f32_e32 v75, v74, v73
	s_nop 0
	v_addc_co_u32_e32 v31, vcc, 0, v67, vcc
	global_store_short v[30:31], v33, off
	v_mul_f32_e32 v30, v38, v32
	v_lshlrev_b32_e32 v32, 16, v178
	v_mul_f32_e32 v31, 0xbfb8aa3b, v32
	v_exp_f32_e32 v31, v31
	v_mul_f32_e32 v30, v30, v75
	s_mov_b32 s36, 0x25318000
	v_cvt_pk_bf16_f32 v33, v30, s0
	v_add_f32_e32 v31, 1.0, v31
	v_rcp_f32_e32 v38, v31
	v_add_co_u32_e32 v30, vcc, s36, v66
	v_fmac_f32_e32 v29, v76, v75
	s_nop 0
	v_addc_co_u32_e32 v31, vcc, 0, v67, vcc
	global_store_short v[30:31], v33, off
	v_mul_f32_e32 v30, v38, v32
	v_mul_f32_e32 v30, v30, v29
	v_cvt_pk_bf16_f32 v32, v30, s0
	s_mov_b64 s[100:101], 0x25324000
	v_lshl_add_u64 v[30:31], v[66:67], 0, s[100:101]
	global_store_short v[30:31], v32, off
	s_and_saveexec_b64 s[36:37], s[34:35]
	ds_write_b32 v149, v29 offset:55364
	s_or_b64 exec, exec, s[36:37]
	s_waitcnt vmcnt(22)
	v_lshlrev_b32_e32 v30, 16, v18
	v_and_b32_e32 v31, 0xffff0000, v18
	v_pk_fma_f32 v[30:31], v[104:105], v[30:31], v[100:101]
	s_waitcnt vmcnt(21)
	v_lshlrev_b32_e32 v18, 16, v19
	v_and_b32_e32 v19, 0xffff0000, v19
	v_pk_fma_f32 v[30:31], v[106:107], v[18:19], v[30:31]
	s_waitcnt vmcnt(20)
	v_lshlrev_b32_e32 v32, 16, v20
	v_and_b32_e32 v33, 0xffff0000, v20
	v_pk_fma_f32 v[30:31], v[108:109], v[32:33], v[30:31]
	s_waitcnt vmcnt(19)
	v_lshlrev_b32_e32 v20, 16, v21
	v_and_b32_e32 v21, 0xffff0000, v21
	v_pk_fma_f32 v[18:19], v[104:105], v[18:19], v[100:101]
	v_pk_fma_f32 v[30:31], v[110:111], v[20:21], v[30:31]
	v_pk_fma_f32 v[18:19], v[106:107], v[32:33], v[18:19]
	v_cvt_pk_bf16_f32 v29, v30, v31
	v_pk_fma_f32 v[18:19], v[108:109], v[20:21], v[18:19]
	s_waitcnt vmcnt(18)
; #define RG_LOAD(n_) do { const long r0_ = (long)rowbase + (long)(n_) * 64; \
;         _Pragma("unroll") for (int i = 0; i < 11; ++i) xr[i] = ((n_) == 0 && 8 * rg - 3 + i < 0) ? 0u : *(const unsigned*)(xcol + (size_t)(r0_ + 8 * rg - 3 + i) * N1); } while (0)
; #define RG_LOADG(n_) do { const long r0_ = (long)rowbase + (long)(n_) * 64; \
;         _Pragma("unroll") for (int i = 0; i < 4; ++i) gbr[i] = *(const unsigned short*)(gbcol + (size_t)(r0_ + l0_ + 4 * fq + i) * N1); } while (0)
; DI void rglru_scan_unit(Frame& F, const Mix0Args& a, int u) {
;     ...
;         if (n + 2 < NCH) RG_LOAD(n + 2);
;         if (n + 1 < NCH) RG_LOADG(n + 1);
;         if constexpr (CV) { int idx = (n >> 2) * NGW + gw; idx = idx < CV_NIT ? idx : idx - CV_NIT;
;             if constexpr (CQ == 0) cv_issue_q(a.cv, idx, lane, cq0, 0); else if constexpr (CQ == 1) cv_issue_q(a.cv, idx, lane, cq1, 4); else if constexpr (CQ == 2) cv_issue_q(a.cv, idx, lane, cq2, 8); else cv_issue_q(a.cv, idx, lane, cq3, 12); }
	v_lshlrev_b32_e32 v30, 16, v22
	v_and_b32_e32 v31, 0xffff0000, v22
	v_pk_fma_f32 v[18:19], v[110:111], v[30:31], v[18:19]
	s_waitcnt vmcnt(17)
	v_lshlrev_b32_e32 v22, 16, v23
	v_cvt_pk_bf16_f32 v18, v18, v19
	ds_write2_b32 v123, v29, v18 offset1:72
	v_pk_fma_f32 v[18:19], v[104:105], v[32:33], v[100:101]
	v_and_b32_e32 v23, 0xffff0000, v23
	v_pk_fma_f32 v[18:19], v[106:107], v[20:21], v[18:19]
	v_add_u32_e32 v54, 0x400, v123
	v_pk_fma_f32 v[18:19], v[108:109], v[30:31], v[18:19]
	s_mov_b32 s36, 0x25be4000
	v_pk_fma_f32 v[18:19], v[110:111], v[22:23], v[18:19]
	s_nop 0
	v_cvt_pk_bf16_f32 v29, v18, v19
	v_pk_fma_f32 v[18:19], v[104:105], v[20:21], v[100:101]
	s_waitcnt vmcnt(16)
	v_lshlrev_b32_e32 v20, 16, v24
	v_pk_fma_f32 v[18:19], v[106:107], v[30:31], v[18:19]
	v_and_b32_e32 v21, 0xffff0000, v24
	v_pk_fma_f32 v[18:19], v[108:109], v[22:23], v[18:19]
	s_nop 0
	v_pk_fma_f32 v[18:19], v[110:111], v[20:21], v[18:19]
	s_nop 0
	v_cvt_pk_bf16_f32 v18, v18, v19
	ds_write2_b32 v123, v29, v18 offset0:144 offset1:216
	v_pk_fma_f32 v[18:19], v[104:105], v[30:31], v[100:101]
	s_waitcnt vmcnt(15)
	v_lshlrev_b32_e32 v30, 16, v27
	v_pk_fma_f32 v[18:19], v[106:107], v[22:23], v[18:19]
	v_and_b32_e32 v31, 0xffff0000, v27
	v_pk_fma_f32 v[18:19], v[108:109], v[20:21], v[18:19]
	s_nop 0
	v_pk_fma_f32 v[18:19], v[110:111], v[30:31], v[18:19]
	s_nop 0
	v_cvt_pk_bf16_f32 v24, v18, v19
	v_pk_fma_f32 v[18:19], v[104:105], v[22:23], v[100:101]
	s_waitcnt vmcnt(14)
	v_lshlrev_b32_e32 v22, 16, v25
	v_pk_fma_f32 v[18:19], v[106:107], v[20:21], v[18:19]
	v_and_b32_e32 v23, 0xffff0000, v25
	v_pk_fma_f32 v[18:19], v[108:109], v[30:31], v[18:19]
	s_nop 0
	v_pk_fma_f32 v[18:19], v[110:111], v[22:23], v[18:19]
	s_nop 0
	v_cvt_pk_bf16_f32 v18, v18, v19
	ds_write2_b32 v54, v24, v18 offset0:32 offset1:104
	v_pk_fma_f32 v[18:19], v[104:105], v[20:21], v[100:101]
	s_waitcnt vmcnt(13)
	v_lshlrev_b32_e32 v20, 16, v26
	v_pk_fma_f32 v[18:19], v[106:107], v[30:31], v[18:19]
	v_and_b32_e32 v21, 0xffff0000, v26
	v_pk_fma_f32 v[18:19], v[108:109], v[22:23], v[18:19]
	s_nop 0
	v_pk_fma_f32 v[18:19], v[110:111], v[20:21], v[18:19]
	s_nop 0
	v_cvt_pk_bf16_f32 v24, v18, v19
	v_pk_fma_f32 v[18:19], v[104:105], v[30:31], v[100:101]
	s_nop 0
	v_pk_fma_f32 v[18:19], v[106:107], v[22:23], v[18:19]
	s_nop 0
	v_pk_fma_f32 v[18:19], v[108:109], v[20:21], v[18:19]
	s_waitcnt vmcnt(12)
	v_lshlrev_b32_e32 v20, 16, v28
	v_and_b32_e32 v21, 0xffff0000, v28
	v_pk_fma_f32 v[18:19], v[110:111], v[20:21], v[18:19]
	s_nop 0
	v_cvt_pk_bf16_f32 v18, v18, v19
	ds_write2_b32 v54, v24, v18 offset0:176 offset1:248
	v_add_co_u32_e32 v18, vcc, s36, v50
	s_mov_b32 s36, 0x25bf0000
	s_nop 0
	v_addc_co_u32_e32 v19, vcc, 0, v51, vcc
	global_load_dword v130, v[18:19], off
	v_add_co_u32_e32 v18, vcc, s36, v50
	s_mov_b32 s36, 0x25bfc000
	s_nop 0
	v_addc_co_u32_e32 v19, vcc, 0, v51, vcc
	global_load_dword v132, v[18:19], off
	v_add_co_u32_e32 v18, vcc, s36, v50
	s_mov_b32 s36, 0x25c08000
	s_nop 0
	v_addc_co_u32_e32 v19, vcc, 0, v51, vcc
	global_load_dword v134, v[18:19], off
	v_add_co_u32_e32 v18, vcc, s36, v50
	s_mov_b32 s36, 0x25c14000
	s_nop 0
	v_addc_co_u32_e32 v19, vcc, 0, v51, vcc
	global_load_dword v169, v[18:19], off
	v_add_co_u32_e32 v18, vcc, s36, v50
	s_mov_b32 s36, 0x25c20000
	s_nop 0
	v_addc_co_u32_e32 v19, vcc, 0, v51, vcc
	global_load_dword v170, v[18:19], off
	v_add_co_u32_e32 v18, vcc, s36, v50
	s_mov_b32 s36, 0x25c2c000
	s_nop 0
	v_addc_co_u32_e32 v19, vcc, 0, v51, vcc
	global_load_dword v171, v[18:19], off
	v_add_co_u32_e32 v18, vcc, s36, v50
	s_mov_b32 s36, 0x25c38000
	s_nop 0
	v_addc_co_u32_e32 v19, vcc, 0, v51, vcc
	global_load_dword v172, v[18:19], off
	v_add_co_u32_e32 v18, vcc, s36, v50
	s_mov_b32 s36, 0x25c44000
	s_nop 0
	v_addc_co_u32_e32 v19, vcc, 0, v51, vcc
	global_load_dword v173, v[18:19], off
	v_add_co_u32_e32 v18, vcc, s36, v50
	s_mov_b32 s36, 0x25c50000
	s_nop 0
	v_addc_co_u32_e32 v19, vcc, 0, v51, vcc
	global_load_dword v174, v[18:19], off
	v_add_co_u32_e32 v18, vcc, s36, v50
	s_mov_b32 s36, 0x25c5c000
	s_nop 0
	v_addc_co_u32_e32 v19, vcc, 0, v51, vcc
	global_load_dword v175, v[18:19], off
	v_add_co_u32_e32 v18, vcc, s36, v50
	s_mov_b32 s36, 0x2590a000
	s_nop 0
	v_addc_co_u32_e32 v19, vcc, 0, v51, vcc
	global_load_dword v176, v[18:19], off
	v_add_co_u32_e32 v18, vcc, s36, v52
	s_nop 1
	v_addc_co_u32_e32 v19, vcc, 0, v53, vcc
	global_load_ushort v58, v[18:19], off
	s_mov_b64 s[100:101], 0x25916000
	v_lshl_add_u64 v[18:19], v[52:53], 0, s[100:101]
	global_load_ushort v56, v[18:19], off
	s_mov_b64 s[100:101], 0x25922000
	v_lshl_add_u64 v[18:19], v[52:53], 0, s[100:101]
	global_load_ushort v55, v[18:19], off
	s_mov_b64 s[100:101], 0x2592e000
	v_lshl_add_u64 v[18:19], v[52:53], 0, s[100:101]
	global_load_ushort v57, v[18:19], off
	v_cndmask_b32_e64 v18, 0, 1, s[40:41]
	v_cmp_ne_u32_e64 s[36:37], 1, v18
	s_andn2_b64 vcc, exec, s[40:41]
	s_cbranch_vccnz .LBB0_274
	s_cmpk_gt_u32 s87, 0x687f
	s_cbranch_scc0 .LBB0_275
	s_add_i32 s84, s87, 0xffff9780
	s_mov_b64 s[40:41], s[52:53]
	s_movk_i32 s78, 0x1000
	s_cbranch_execz .LBB0_276
	s_branch .LBB0_277

; #define LAS __attribute__((address_space(3)))
; DI void rglru_scan_unit(Frame& F, const Mix0Args& a, int u) {
;     ...
;     auto rg_step = [&](int n, auto cvt) __attribute__((always_inline)) {
;         constexpr int CQ = decltype(cvt)::value; constexpr bool CV = CQ >= 0;
;         const size_t row0 = rowbase + (size_t)n * 64;
;         LAS uchar* XCc = XC0 + (n & 1) * 64 * S128; LAS uchar* XCn = XC0 + ((n + 1) & 1) * 64 * S128;
;         LAS float* SEGA = SEG0 + (n & 1) * 1280; LAS float* SEGH = SEGA + 640;
; #pragma unroll
;         for (int i = 0; i < 4; ++i) gb_cur[i] = gbr[i];
;         if (n + 1 < NCH) RG_STAGE(XCn);
;         if constexpr (CQ == 0) { if (n > 0) { const int ip = ((n >> 2) - 1) * NGW + gw; if (ip < CV_NIT) cv_finish(a.cv, ip, lane, cq0, cq1, cq2, cq3, CVS); } }
;         if (n + 2 < NCH) RG_LOAD(n + 2);
;         if (n + 1 < NCH) RG_LOADG(n + 1);
;         if constexpr (CV) { int idx = (n >> 2) * NGW + gw; idx = idx < CV_NIT ? idx : idx - CV_NIT;
;             if constexpr (CQ == 0) cv_issue_q(a.cv, idx, lane, cq0, 0); else if constexpr (CQ == 1) cv_issue_q(a.cv, idx, lane, cq1, 4); else if constexpr (CQ == 2) cv_issue_q(a.cv, idx, lane, cq2, 8); else cv_issue_q(a.cv, idx, lane, cq3, 12); }
;         const f32x4 zero4 = (f32x4){0.f, 0.f, 0.f, 0.f};
;         float av[4], uv[4]; float Aseg = 1.f, Hseg = 0.f;
;         { bf16x8 xf[4], waf[4], wxf[4]; unsigned xcr[4];
; #pragma unroll
;           for (int ks = 0; ks < 4; ++ks) { xf[ks] = *(const LAS bf16x8*)(XCc + (l0_ + fr) * S128 + ks * 64 + fq * 16);
;               waf[ks] = *(const LAS bf16x8*)(WAT + (16 * jtile + fr) * S128 + ks * 64 + fq * 16); wxf[ks] = *(const LAS bf16x8*)(WXT + (16 * jtile + fr) * S128 + ks * 64 + fq * 16); }
; #pragma unroll
;           for (int r = 0; r < 4; ++r) xcr[r] = *(const LAS unsigned short*)(XCc + (l0_ + 4 * fq + r) * S128 + (qq * 32 + jj) * 2);
;           f32x4 R = zero4, I = zero4;
; #pragma unroll
;           for (int ks = 0; ks < 4; ++ks) { R = __builtin_amdgcn_mfma_f32_16x16x32_bf16(xf[ks], waf[ks], R, 0, 0, 0); I = __builtin_amdgcn_mfma_f32_16x16x32_bf16(xf[ks], wxf[ks], I, 0, 0, 0); }
; #pragma unroll
;           for (int r = 0; r < 4; ++r) {
;               const float rr = fsigmoid(R[r] + bav), ig = fsigmoid(I[r] + bxv);
;               const float aa = fexp2(-sp8l2 * rr); const float om = __builtin_fmaf(-aa, aa, 1.0f);
.LBB0_277:
	s_lshr_b32 s79, s78, 6
	v_cvt_f32_u32_e32 v18, s79
	s_sub_i32 s90, 0, s79
	s_abs_i32 s89, s84
	s_ashr_i32 s88, s84, 31
	v_rcp_iflag_f32_e32 v18, v18
	v_mul_u32_u24_e32 v42, s78, v102
	v_or_b32_e32 v42, v42, v125
	v_lshlrev_b32_e32 v82, 2, v42
	v_mul_f32_e32 v18, 0x4f7ffffe, v18
	v_cvt_u32_f32_e32 v18, v18
	s_waitcnt vmcnt(26)
	v_lshlrev_b32_e32 v37, 16, v37
	s_waitcnt vmcnt(24)
	v_lshlrev_b32_e32 v34, 16, v34
	ds_read_b128 v[22:25], v103 offset:36864
	v_readfirstlane_b32 s91, v18
	s_mul_i32 s90, s90, s91
	s_mul_hi_u32 s90, s91, s90
	s_add_i32 s91, s91, s90
	s_mul_hi_u32 s90, s89, s91
	s_mul_i32 s91, s90, s79
	s_sub_i32 s89, s89, s91
	s_add_i32 vcc_lo, s90, 1
	s_sub_i32 s91, s89, s79
	s_cmp_ge_u32 s89, s79
	s_cselect_b32 s90, vcc_lo, s90
	s_cselect_b32 s89, s91, s89
	s_add_i32 s91, s90, 1
	s_cmp_ge_u32 s89, s79
	ds_read_b128 v[18:21], v164 offset:18432
	s_cselect_b32 s89, s91, s90
	s_xor_b32 s89, s89, s88
	s_sub_i32 s88, s89, s88
	s_mul_i32 s79, s88, s79
	s_lshl_b32 s88, s88, 6
	s_sub_i32 s79, s84, s79
	s_or_b32 s84, s88, 4
	s_mul_hi_i32 s91, s84, s78
	s_mul_i32 s90, s84, s78
	s_lshl_b32 s88, s79, 6
	s_lshl_b64 s[90:91], s[90:91], 2
	s_add_u32 s79, s40, s90
	ds_read_b128 v[26:29], v103 offset:46080
	ds_read_b128 v[30:33], v164 offset:18496
	ds_read_b128 v[38:41], v103 offset:36928
	ds_read_b128 v[42:45], v103 offset:46144
	ds_read_b128 v[46:49], v164 offset:18560
	s_addc_u32 s84, s41, s91
	s_ashr_i32 s89, s88, 31
	s_waitcnt lgkmcnt(5)
	v_mfma_f32_16x16x32_bf16 v[22:25], v[18:21], v[22:25], 0
	s_lshl_b64 s[40:41], s[88:89], 2
	s_add_u32 s40, s79, s40
	s_addc_u32 s41, s84, s41
	s_waitcnt lgkmcnt(4)
	v_mfma_f32_16x16x32_bf16 v[26:29], v[18:21], v[26:29], 0
	global_load_dwordx4 v[18:21], v82, s[40:41]
	s_lshl_b32 s96, s78, 2
	v_lshl_add_u64 v[64:65], s[40:41], 0, v[82:83]
	s_waitcnt lgkmcnt(2)
	v_mfma_f32_16x16x32_bf16 v[22:25], v[30:33], v[38:41], v[22:25]
	ds_read_b128 v[38:41], v103 offset:36992
	ds_read_b128 v[60:63], v164 offset:18624
	s_waitcnt lgkmcnt(3)
	v_mfma_f32_16x16x32_bf16 v[30:33], v[30:33], v[42:45], v[26:29]
	ds_read_b128 v[42:45], v103 offset:37056
	s_waitcnt lgkmcnt(2)
	v_mfma_f32_16x16x32_bf16 v[38:41], v[46:49], v[38:41], v[22:25]
	v_lshl_add_u64 v[26:27], v[64:65], 0, s[96:97]
	v_lshl_add_u64 v[64:65], v[26:27], 0, s[96:97]
	s_nop 0
	global_load_dwordx4 v[22:25], v[26:27], off
	s_nop 0
	global_load_dwordx4 v[26:29], v[64:65], off
	s_waitcnt lgkmcnt(0)
	v_mfma_f32_16x16x32_bf16 v[38:41], v[60:63], v[42:45], v[38:41]
	ds_read_b128 v[68:71], v103 offset:46208
	ds_read_b128 v[42:45], v103 offset:46272
	v_lshl_add_u64 v[64:65], v[64:65], 0, s[96:97]
	s_waitcnt lgkmcnt(1)
	v_mfma_f32_16x16x32_bf16 v[46:49], v[46:49], v[68:71], v[30:33]
	s_nop 2
	v_add_f32_e32 v38, v165, v38
	v_mul_f32_e32 v38, 0xbfb8aa3b, v38
	v_exp_f32_e32 v38, v38
	s_waitcnt lgkmcnt(0)
	v_mfma_f32_16x16x32_bf16 v[42:45], v[60:63], v[42:45], v[46:49]
	v_add_f32_e32 v39, v165, v39
	v_mul_f32_e32 v39, 0xbfb8aa3b, v39
	v_add_f32_e32 v30, 1.0, v38
	v_rcp_f32_e32 v38, v30
	v_exp_f32_e32 v39, v39
	global_load_dwordx4 v[30:33], v[64:65], off
	ds_read_u16 v47, v177 offset:18432
	ds_read_u16 v49, v177 offset:18720
	ds_read_u16 v59, v177 offset:19008
	ds_read_u16 v60, v177 offset:19296
	v_mul_f32_e64 v38, v38, -v168
	v_exp_f32_e32 v48, v38
	v_add_f32_e32 v38, v167, v42
	v_mul_f32_e32 v38, 0xbfb8aa3b, v38
	v_exp_f32_e32 v38, v38
	v_fma_f32 v42, -v48, v48, 1.0
	v_mul_f32_e32 v46, 0x4f800000, v42
	v_cmp_gt_f32_e32 vcc, s42, v42
	v_add_f32_e32 v38, 1.0, v38
	v_rcp_f32_e32 v38, v38
	v_cndmask_b32_e32 v42, v42, v46, vcc
	v_sqrt_f32_e32 v46, v42
	v_add_f32_e32 v39, 1.0, v39
	v_rcp_f32_e32 v39, v39
	v_add_f32_e32 v40, v165, v40
	v_add_u32_e32 v61, -1, v46
	v_fma_f32 v62, -v61, v46, v42
	v_cmp_ge_f32_e64 s[40:41], 0, v62
	v_add_u32_e32 v62, 1, v46
	v_mul_f32_e32 v40, 0xbfb8aa3b, v40
	v_cndmask_b32_e64 v61, v46, v61, s[40:41]
	v_fma_f32 v46, -v62, v46, v42
	v_cmp_lt_f32_e64 s[40:41], 0, v46
	v_exp_f32_e32 v40, v40
	v_add_f32_e32 v41, v165, v41
	v_cndmask_b32_e64 v46, v61, v62, s[40:41]
	v_mul_f32_e32 v61, 0x37800000, v46
	v_cndmask_b32_e32 v46, v46, v61, vcc
	v_cmp_class_f32_e32 vcc, v42, v158
	v_add_f32_e32 v40, 1.0, v40
	v_rcp_f32_e32 v40, v40
	v_cndmask_b32_e32 v42, v46, v42, vcc
	s_waitcnt lgkmcnt(3)
	v_lshlrev_b32_e32 v46, 16, v47
	v_mul_f32_e32 v38, v38, v46
	v_mul_f32_e32 v64, v38, v42
	v_mul_f32_e64 v38, v39, -v168
	v_exp_f32_e32 v39, v38
	v_add_f32_e32 v38, v167, v43
	v_mul_f32_e32 v38, 0xbfb8aa3b, v38
	v_exp_f32_e32 v38, v38
	v_fma_f32 v42, -v39, v39, 1.0
	v_mul_f32_e32 v43, 0x4f800000, v42
	v_cmp_gt_f32_e32 vcc, s42, v42
	v_add_f32_e32 v38, 1.0, v38
	v_rcp_f32_e32 v38, v38
	v_cndmask_b32_e32 v42, v42, v43, vcc
	v_sqrt_f32_e32 v43, v42
	v_mul_f32_e64 v40, v40, -v168
	v_exp_f32_e32 v65, v40
	v_add_f32_e32 v40, v167, v44
	v_add_u32_e32 v47, -1, v43
	v_fma_f32 v61, -v47, v43, v42
	v_cmp_ge_f32_e64 s[40:41], 0, v61
	v_add_u32_e32 v61, 1, v43
	v_fma_f32 v46, 0, v48, v64
	v_cndmask_b32_e64 v47, v43, v47, s[40:41]
	v_fma_f32 v43, -v61, v43, v42
	v_cmp_lt_f32_e64 s[40:41], 0, v43
	v_mul_f32_e32 v40, 0xbfb8aa3b, v40
	v_exp_f32_e32 v40, v40
	v_cndmask_b32_e64 v43, v47, v61, s[40:41]
	v_mul_f32_e32 v47, 0x37800000, v43
	v_cndmask_b32_e32 v43, v43, v47, vcc
	v_cmp_class_f32_e32 vcc, v42, v158
	v_mul_f32_e32 v41, 0xbfb8aa3b, v41
	v_exp_f32_e32 v41, v41
	v_cndmask_b32_e32 v42, v43, v42, vcc
	s_waitcnt lgkmcnt(2)
; #define LAS __attribute__((address_space(3)))
; DI float bf2f(unsigned h) { return __uint_as_float(h << 16); }
; DI unsigned pk2(float lo, float hi) { f32x2 v = {lo, hi}; bf16v2 b = __builtin_convertvector(v, bf16v2); return __builtin_bit_cast(unsigned, b); }
; DI float fexp2(float x) { return __builtin_amdgcn_exp2f(x); }
; DI float fsigmoid(float x) { return frcp(1.0f + fexp2(-LOG2E * x)); }
; DI float fsilu(float x) { return x * fsigmoid(x); }
; #define LDS_BAR() do { asm volatile("s_waitcnt lgkmcnt(0)" ::: "memory"); __builtin_amdgcn_s_barrier(); asm volatile("" ::: "memory"); } while (0)
; DI void rglru_scan_unit(Frame& F, const Mix0Args& a, int u) {
;     ...
;           for (int r = 0; r < 4; ++r) {
;               const float rr = fsigmoid(R[r] + bav), ig = fsigmoid(I[r] + bxv);
;               const float aa = fexp2(-sp8l2 * rr); const float om = __builtin_fmaf(-aa, aa, 1.0f);
;               av[r] = aa; uv[r] = __builtin_sqrtf(om) * (ig * bf2f(xcr[r]));
;               Hseg = aa * Hseg + uv[r]; Aseg *= aa; } }
;         const int sgi = ltile * 4 + fq;
;         SEGA[jj * 20 + sgi] = Aseg; SEGH[jj * 20 + sgi] = Hseg;
;         LDS_BAR();
;         float carry = HPREV[jj * 20 + (n & 1)]; float sa[15], sh[15];
;         { f32x4 a4[4], h4[4];
; #pragma unroll
;           for (int i = 0; i < 4; ++i) { a4[i] = *(const LAS f32x4*)(SEGA + jj * 20 + 4 * i); h4[i] = *(const LAS f32x4*)(SEGH + jj * 20 + 4 * i); }
; #pragma unroll
;           for (int s = 0; s < 15; ++s) { sa[s] = a4[s >> 2][s & 3]; sh[s] = h4[s >> 2][s & 3]; } }
; #pragma unroll
;         for (int s = 0; s < 15; ++s) carry = (s < sgi) ? sa[s] * carry + sh[s] : carry;
; #pragma unroll
;         for (int r = 0; r < 4; ++r) { carry = av[r] * carry + uv[r];
;             const float o = carry * fsilu(bf2f(gb_cur[r]));
;             obcol[(row0 + l0_ + 4 * fq + r) * a.out_ld] = (bf16)(pk2(o, 0.f) & 0xffffu); }
;         if (sgi == 15) HPREV[jj * 20 + ((n + 1) & 1)] = carry;
	v_lshlrev_b32_e32 v43, 16, v49
	v_mul_f32_e32 v38, v38, v43
	v_mul_f32_e32 v49, v38, v42
	v_fma_f32 v42, -v65, v65, 1.0
	v_mul_f32_e32 v43, 0x4f800000, v42
	v_cmp_gt_f32_e32 vcc, s42, v42
	v_fma_f32 v38, v39, v46, v49
	v_add_f32_e32 v40, 1.0, v40
	v_cndmask_b32_e32 v42, v42, v43, vcc
	v_sqrt_f32_e32 v43, v42
	v_rcp_f32_e32 v40, v40
	v_add_f32_e32 v41, 1.0, v41
	v_rcp_f32_e32 v41, v41
	v_add_u32_e32 v46, -1, v43
	v_fma_f32 v47, -v46, v43, v42
	v_cmp_ge_f32_e64 s[40:41], 0, v47
	v_add_u32_e32 v47, 1, v43
	v_mul_f32_e32 v44, v48, v39
	v_cndmask_b32_e64 v46, v43, v46, s[40:41]
	v_fma_f32 v43, -v47, v43, v42
	v_cmp_lt_f32_e64 s[40:41], 0, v43
	s_nop 1
	v_cndmask_b32_e64 v43, v46, v47, s[40:41]
	v_mul_f32_e32 v46, 0x37800000, v43
	v_cndmask_b32_e32 v43, v43, v46, vcc
	v_cmp_class_f32_e32 vcc, v42, v158
	s_nop 1
	v_cndmask_b32_e32 v42, v43, v42, vcc
	s_waitcnt lgkmcnt(1)
	v_lshlrev_b32_e32 v43, 16, v59
	v_mul_f32_e32 v40, v40, v43
	v_mul_f32_e32 v59, v40, v42
	v_fma_f32 v40, v65, v38, v59
	v_mul_f32_e64 v38, v41, -v168
	v_exp_f32_e32 v80, v38
	v_add_f32_e32 v38, v167, v45
	v_mul_f32_e32 v38, 0xbfb8aa3b, v38
	v_exp_f32_e32 v38, v38
	v_fma_f32 v41, -v80, v80, 1.0
	v_mul_f32_e32 v42, 0x4f800000, v41
	v_cmp_gt_f32_e32 vcc, s42, v41
	v_mul_f32_e32 v43, v65, v44
	v_add_f32_e32 v38, 1.0, v38
	v_cndmask_b32_e32 v41, v41, v42, vcc
	v_sqrt_f32_e32 v42, v41
	v_rcp_f32_e32 v38, v38
	v_add_u32_e32 v44, -1, v42
	v_fma_f32 v45, -v44, v42, v41
	v_cmp_ge_f32_e64 s[40:41], 0, v45
	v_add_u32_e32 v45, 1, v42
	s_nop 0
	v_cndmask_b32_e64 v44, v42, v44, s[40:41]
	v_fma_f32 v42, -v45, v42, v41
	v_cmp_lt_f32_e64 s[40:41], 0, v42
	s_nop 1
	v_cndmask_b32_e64 v42, v44, v45, s[40:41]
	v_mul_f32_e32 v44, 0x37800000, v42
	v_cndmask_b32_e32 v42, v42, v44, vcc
	v_cmp_class_f32_e32 vcc, v41, v158
	s_mov_b32 s40, 0x25600000
	s_nop 0
	v_cndmask_b32_e32 v41, v42, v41, vcc
	s_waitcnt lgkmcnt(0)
	v_lshlrev_b32_e32 v42, 16, v60
	v_mul_f32_e32 v38, v38, v42
	v_mul_f32_e32 v38, v38, v41
	v_fma_f32 v40, v80, v40, v38
	v_mul_f32_e32 v41, v80, v43
	ds_write2st64_b32 v150, v41, v40 offset0:236 offset1:246
	s_waitcnt lgkmcnt(0)
	s_barrier
	ds_read_b32 v81, v149 offset:55364
	ds_read_b128 v[40:43], v149 offset:60416
	ds_read_b128 v[44:47], v149 offset:62976
	ds_read_b128 v[60:63], v149 offset:60432
	ds_read_b128 v[68:71], v149 offset:60448
	ds_read_b128 v[72:75], v149 offset:62992
	ds_read_b128 v[76:79], v149 offset:63008
	ds_read_b128 v[178:181], v149 offset:60464
	ds_read_b128 v[184:187], v149 offset:63024
	s_waitcnt lgkmcnt(6)
	v_fma_f32 v40, v81, v40, v44
	v_cndmask_b32_e64 v40, v40, v81, s[10:11]
	v_fma_f32 v41, v41, v40, v45
	v_cndmask_b32_e64 v40, v40, v41, s[12:13]
	v_fma_f32 v41, v42, v40, v46
	v_cndmask_b32_e64 v40, v40, v41, s[14:15]
	v_fmac_f32_e32 v47, v43, v40
	v_cndmask_b32_e64 v40, v47, v40, s[0:1]
	s_waitcnt lgkmcnt(3)
	v_fma_f32 v41, v60, v40, v72
	v_cndmask_b32_e64 v40, v40, v41, s[16:17]
	v_fma_f32 v41, v61, v40, v73
	v_cndmask_b32_e64 v40, v40, v41, s[18:19]
	v_fma_f32 v41, v62, v40, v74
	v_cndmask_b32_e64 v40, v40, v41, s[20:21]
	v_fmac_f32_e32 v75, v63, v40
	v_cndmask_b32_e64 v40, v40, v75, s[38:39]
	s_waitcnt lgkmcnt(2)
	v_fma_f32 v41, v68, v40, v76
	v_cndmask_b32_e64 v40, v40, v41, s[22:23]
	v_fma_f32 v41, v69, v40, v77
	v_cndmask_b32_e64 v40, v40, v41, s[24:25]
	v_fma_f32 v41, v70, v40, v78
	v_cndmask_b32_e64 v40, v40, v41, s[26:27]
	v_fmac_f32_e32 v79, v71, v40
	v_mul_f32_e32 v42, 0xbfb8aa3b, v37
	v_cndmask_b32_e64 v40, v40, v79, s[4:5]
	v_exp_f32_e32 v42, v42
	s_waitcnt lgkmcnt(0)
	v_fma_f32 v41, v178, v40, v184
	v_cndmask_b32_e64 v40, v40, v41, s[28:29]
	v_fma_f32 v41, v179, v40, v185
	v_cndmask_b32_e64 v40, v40, v41, s[30:31]
	v_add_f32_e32 v41, 1.0, v42
	v_rcp_f32_e32 v41, v41
	v_fmac_f32_e32 v186, v180, v40
	v_cndmask_b32_e64 v40, v40, v186, s[34:35]
	v_fmac_f32_e32 v64, v48, v40
	v_mul_f32_e32 v37, v41, v37
	v_lshlrev_b32_e32 v41, 16, v36
	v_mul_f32_e32 v36, 0xbfb8aa3b, v41
	v_exp_f32_e32 v42, v36
	v_mul_f32_e32 v37, v37, v64
	v_add_co_u32_e32 v36, vcc, s40, v66
	v_cvt_pk_bf16_f32 v40, v37, s0
	s_nop 0
	v_addc_co_u32_e32 v37, vcc, 0, v67, vcc
	global_store_short v[36:37], v40, off
	v_add_f32_e32 v36, 1.0, v42
	v_rcp_f32_e32 v36, v36
	v_mul_f32_e32 v37, 0xbfb8aa3b, v34
	v_exp_f32_e32 v37, v37
	v_fmac_f32_e32 v49, v39, v64
	v_mul_f32_e32 v36, v36, v41
	v_mul_f32_e32 v36, v36, v49
	v_cvt_pk_bf16_f32 v39, v36, s0
	v_add_f32_e32 v36, 1.0, v37
	s_mov_b32 s40, 0x2560c000
	v_rcp_f32_e32 v40, v36
	v_add_co_u32_e32 v36, vcc, s40, v66
	v_fmac_f32_e32 v59, v65, v49
	s_nop 0
	v_addc_co_u32_e32 v37, vcc, 0, v67, vcc
	global_store_short v[36:37], v39, off
	s_waitcnt vmcnt(29)
	v_lshlrev_b32_e32 v36, 16, v35
	v_mul_f32_e32 v35, 0xbfb8aa3b, v36
	v_exp_f32_e32 v35, v35
	v_mul_f32_e32 v34, v40, v34
	v_mul_f32_e32 v34, v34, v59
	s_mov_b32 s40, 0x25618000
	v_add_f32_e32 v35, 1.0, v35
	v_rcp_f32_e32 v39, v35
	v_cvt_pk_bf16_f32 v37, v34, s0
	v_add_co_u32_e32 v34, vcc, s40, v66
	v_fmac_f32_e32 v38, v80, v59
	s_nop 0
	v_addc_co_u32_e32 v35, vcc, 0, v67, vcc
	global_store_short v[34:35], v37, off
	v_mul_f32_e32 v34, v39, v36
	v_mul_f32_e32 v34, v34, v38
	v_cvt_pk_bf16_f32 v36, v34, s0
	s_mov_b64 s[100:101], 0x25624000
	v_lshl_add_u64 v[34:35], v[66:67], 0, s[100:101]
	global_store_short v[34:35], v36, off
	s_and_saveexec_b64 s[40:41], s[34:35]
	ds_write_b32 v149, v38 offset:55360
	s_or_b64 exec, exec, s[40:41]
	s_waitcnt vmcnt(22)
; #define LAS __attribute__((address_space(3)))
; #define LDS_BAR() do { asm volatile("s_waitcnt lgkmcnt(0)" ::: "memory"); __builtin_amdgcn_s_barrier(); asm volatile("" ::: "memory"); } while (0)
; #define RG_LOAD(n_) do { const long r0_ = (long)rowbase + (long)(n_) * 64; \
;         _Pragma("unroll") for (int i = 0; i < 11; ++i) xr[i] = ((n_) == 0 && 8 * rg - 3 + i < 0) ? 0u : *(const unsigned*)(xcol + (size_t)(r0_ + 8 * rg - 3 + i) * N1); } while (0)
; #define RG_LOADG(n_) do { const long r0_ = (long)rowbase + (long)(n_) * 64; \
;         _Pragma("unroll") for (int i = 0; i < 4; ++i) gbr[i] = *(const unsigned short*)(gbcol + (size_t)(r0_ + l0_ + 4 * fq + i) * N1); } while (0)
; #define RG_STAGE(xc_) do { LAS uchar* X_ = (xc_); \
;         _Pragma("unroll") for (int i = 0; i < 8; ++i) { f32x2 s2 = (f32x2){cbs[0], cbs[1]}; \
;             _Pragma("unroll") for (int k = 0; k < 4; ++k) s2 += (f32x2){cw[k][0], cw[k][1]} * (f32x2){bflo(xr[i + k]), bfhi(xr[i + k])}; \
;             *(LAS unsigned*)(X_ + (8 * rg + i) * S128 + c2 * 4) = pk2(s2.x, s2.y); } } while (0)
; DI void rglru_scan_unit(Frame& F, const Mix0Args& a, int u) {
;     ...
;     RG_LOAD(0);
;     RG_STAGE(XC0);
;     unsigned gb_cur[4];
;     RG_LOAD(1); RG_LOADG(0);
;     LDS_BAR();
;     const int nsl = cv_on ? min(NCH / 4, max(0, (CV_NIT - 8 * F.vcu + NGW - 1) / NGW)) : 0;
;     auto rg_step = [&](int n, auto cvt) __attribute__((always_inline)) {
;         constexpr int CQ = decltype(cvt)::value; constexpr bool CV = CQ >= 0;
;         const size_t row0 = rowbase + (size_t)n * 64;
;         LAS uchar* XCc = XC0 + (n & 1) * 64 * S128; LAS uchar* XCn = XC0 + ((n + 1) & 1) * 64 * S128;
;         LAS float* SEGA = SEG0 + (n & 1) * 1280; LAS float* SEGH = SEGA + 640;
; #pragma unroll
;         for (int i = 0; i < 4; ++i) gb_cur[i] = gbr[i];
;         if (n + 1 < NCH) RG_STAGE(XCn);
;         if constexpr (CQ == 0) { if (n > 0) { const int ip = ((n >> 2) - 1) * NGW + gw; if (ip < CV_NIT) cv_finish(a.cv, ip, lane, cq0, cq1, cq2, cq3, CVS); } }
;         if (n + 2 < NCH) RG_LOAD(n + 2);
;         if (n + 1 < NCH) RG_LOADG(n + 1);
	v_lshlrev_b32_e32 v34, 16, v130
	v_and_b32_e32 v35, 0xffff0000, v130
	v_pk_fma_f32 v[34:35], v[104:105], v[34:35], v[100:101]
	s_waitcnt vmcnt(21)
	v_lshlrev_b32_e32 v36, 16, v132
	v_and_b32_e32 v37, 0xffff0000, v132
	v_pk_fma_f32 v[34:35], v[106:107], v[36:37], v[34:35]
	s_waitcnt vmcnt(20)
	v_lshlrev_b32_e32 v38, 16, v134
	v_and_b32_e32 v39, 0xffff0000, v134
	v_pk_fma_f32 v[34:35], v[108:109], v[38:39], v[34:35]
	s_waitcnt vmcnt(19)
	v_lshlrev_b32_e32 v40, 16, v169
	v_and_b32_e32 v41, 0xffff0000, v169
	v_pk_fma_f32 v[34:35], v[110:111], v[40:41], v[34:35]
	s_or_b32 s40, s93, 2
	v_cvt_pk_bf16_f32 v42, v34, v35
	v_pk_fma_f32 v[34:35], v[104:105], v[36:37], v[100:101]
	s_waitcnt vmcnt(18)
	v_lshlrev_b32_e32 v36, 16, v170
	v_pk_fma_f32 v[34:35], v[106:107], v[38:39], v[34:35]
	v_and_b32_e32 v37, 0xffff0000, v170
	v_pk_fma_f32 v[34:35], v[108:109], v[40:41], v[34:35]
	s_cmpk_gt_u32 s40, 0x7d
	v_pk_fma_f32 v[34:35], v[110:111], v[36:37], v[34:35]
	s_nop 0
	v_cvt_pk_bf16_f32 v34, v34, v35
	ds_write2_b32 v183, v42, v34 offset1:72
	v_pk_fma_f32 v[34:35], v[104:105], v[38:39], v[100:101]
	s_waitcnt vmcnt(17)
	v_lshlrev_b32_e32 v38, 16, v171
	v_pk_fma_f32 v[34:35], v[106:107], v[40:41], v[34:35]
	v_and_b32_e32 v39, 0xffff0000, v171
	v_pk_fma_f32 v[34:35], v[108:109], v[36:37], v[34:35]
	s_nop 0
	v_pk_fma_f32 v[34:35], v[110:111], v[38:39], v[34:35]
	s_nop 0
	v_cvt_pk_bf16_f32 v42, v34, v35
	v_pk_fma_f32 v[34:35], v[104:105], v[40:41], v[100:101]
	s_waitcnt vmcnt(16)
	v_lshlrev_b32_e32 v40, 16, v172
	v_pk_fma_f32 v[34:35], v[106:107], v[36:37], v[34:35]
	v_and_b32_e32 v41, 0xffff0000, v172
	v_pk_fma_f32 v[34:35], v[108:109], v[38:39], v[34:35]
	s_nop 0
	v_pk_fma_f32 v[34:35], v[110:111], v[40:41], v[34:35]
	s_nop 0
	v_cvt_pk_bf16_f32 v34, v34, v35
	ds_write2_b32 v183, v42, v34 offset0:144 offset1:216
	v_pk_fma_f32 v[34:35], v[104:105], v[36:37], v[100:101]
	s_waitcnt vmcnt(15)
	v_lshlrev_b32_e32 v36, 16, v173
	v_pk_fma_f32 v[34:35], v[106:107], v[38:39], v[34:35]
	v_and_b32_e32 v37, 0xffff0000, v173
	v_pk_fma_f32 v[34:35], v[108:109], v[40:41], v[34:35]
	s_nop 0
	v_pk_fma_f32 v[34:35], v[110:111], v[36:37], v[34:35]
	s_nop 0
	v_cvt_pk_bf16_f32 v42, v34, v35
	v_pk_fma_f32 v[34:35], v[104:105], v[38:39], v[100:101]
	s_waitcnt vmcnt(14)
	v_lshlrev_b32_e32 v38, 16, v174
	v_pk_fma_f32 v[34:35], v[106:107], v[40:41], v[34:35]
	v_and_b32_e32 v39, 0xffff0000, v174
	v_pk_fma_f32 v[34:35], v[108:109], v[36:37], v[34:35]
	s_nop 0
	v_pk_fma_f32 v[34:35], v[110:111], v[38:39], v[34:35]
	s_nop 0
	v_cvt_pk_bf16_f32 v34, v34, v35
	ds_write2_b32 v182, v42, v34 offset0:32 offset1:104
	v_pk_fma_f32 v[34:35], v[104:105], v[40:41], v[100:101]
	s_waitcnt vmcnt(13)
	v_lshlrev_b32_e32 v40, 16, v175
	v_pk_fma_f32 v[34:35], v[106:107], v[36:37], v[34:35]
	v_and_b32_e32 v41, 0xffff0000, v175
	v_pk_fma_f32 v[34:35], v[108:109], v[38:39], v[34:35]
	s_nop 0
	v_pk_fma_f32 v[34:35], v[110:111], v[40:41], v[34:35]
	s_nop 0
	v_cvt_pk_bf16_f32 v42, v34, v35
	v_pk_fma_f32 v[34:35], v[104:105], v[36:37], v[100:101]
	s_waitcnt vmcnt(12)
	v_lshlrev_b32_e32 v36, 16, v176
	v_pk_fma_f32 v[34:35], v[106:107], v[38:39], v[34:35]
	v_and_b32_e32 v37, 0xffff0000, v176
	v_pk_fma_f32 v[34:35], v[108:109], v[40:41], v[34:35]
	s_nop 0
	v_pk_fma_f32 v[34:35], v[110:111], v[36:37], v[34:35]
	s_nop 0
	v_cvt_pk_bf16_f32 v34, v34, v35
	ds_write2_b32 v182, v42, v34 offset0:176 offset1:248
	s_cbranch_scc1 .LBB0_281
	s_mov_b64 s[100:101], 0x25ee4000
	v_lshl_add_u64 v[34:35], v[50:51], 0, s[100:101]
	global_load_dword v130, v[34:35], off
	s_mov_b64 s[100:101], 0x25ef0000
	v_lshl_add_u64 v[34:35], v[50:51], 0, s[100:101]
	global_load_dword v132, v[34:35], off
	s_mov_b64 s[100:101], 0x25efc000
	v_lshl_add_u64 v[34:35], v[50:51], 0, s[100:101]
	global_load_dword v134, v[34:35], off
	s_mov_b64 s[100:101], 0x25f08000
	v_lshl_add_u64 v[34:35], v[50:51], 0, s[100:101]
	global_load_dword v169, v[34:35], off
	s_mov_b64 s[100:101], 0x25f14000
	v_lshl_add_u64 v[34:35], v[50:51], 0, s[100:101]
	global_load_dword v170, v[34:35], off
	s_mov_b64 s[100:101], 0x25f20000
	v_lshl_add_u64 v[34:35], v[50:51], 0, s[100:101]
	global_load_dword v171, v[34:35], off
	s_mov_b64 s[100:101], 0x25f2c000
	v_lshl_add_u64 v[34:35], v[50:51], 0, s[100:101]
	global_load_dword v172, v[34:35], off
	s_mov_b64 s[100:101], 0x25f38000
	v_lshl_add_u64 v[34:35], v[50:51], 0, s[100:101]
	global_load_dword v173, v[34:35], off
	s_mov_b64 s[100:101], 0x25f44000
	v_lshl_add_u64 v[34:35], v[50:51], 0, s[100:101]
	global_load_dword v174, v[34:35], off
	s_mov_b64 s[100:101], 0x25f50000
	v_lshl_add_u64 v[34:35], v[50:51], 0, s[100:101]
	global_load_dword v175, v[34:35], off
	s_mov_b64 s[100:101], 0x25f5c000
	v_lshl_add_u64 v[34:35], v[50:51], 0, s[100:101]
	global_load_dword v176, v[34:35], off
.LBB0_281:
	s_mov_b64 s[100:101], 0x25c0a000
	v_lshl_add_u64 v[34:35], v[52:53], 0, s[100:101]
	global_load_ushort v59, v[34:35], off
	s_mov_b64 s[100:101], 0x25c16000
	v_lshl_add_u64 v[34:35], v[52:53], 0, s[100:101]
	global_load_ushort v60, v[34:35], off
	s_mov_b64 s[100:101], 0x25c22000
	v_lshl_add_u64 v[34:35], v[52:53], 0, s[100:101]
	global_load_ushort v61, v[34:35], off
	s_mov_b64 s[100:101], 0x25c2e000
	v_lshl_add_u64 v[34:35], v[52:53], 0, s[100:101]
	global_load_ushort v62, v[34:35], off
	s_and_b64 vcc, exec, s[36:37]
	s_cbranch_vccnz .LBB0_284
	s_cmpk_gt_u32 s87, 0x687f
	s_cbranch_scc0 .LBB0_285
	s_add_i32 s84, s87, 0xffff9780
	s_mov_b64 s[40:41], s[52:53]
	s_movk_i32 s78, 0x1000
	s_cbranch_execz .LBB0_286
	s_branch .LBB0_287

; #define LAS __attribute__((address_space(3)))
; DI void rglru_scan_unit(Frame& F, const Mix0Args& a, int u) {
;     ...
;     auto rg_step = [&](int n, auto cvt) __attribute__((always_inline)) {
;         constexpr int CQ = decltype(cvt)::value; constexpr bool CV = CQ >= 0;
;         const size_t row0 = rowbase + (size_t)n * 64;
;         LAS uchar* XCc = XC0 + (n & 1) * 64 * S128; LAS uchar* XCn = XC0 + ((n + 1) & 1) * 64 * S128;
;         LAS float* SEGA = SEG0 + (n & 1) * 1280; LAS float* SEGH = SEGA + 640;
; #pragma unroll
;         for (int i = 0; i < 4; ++i) gb_cur[i] = gbr[i];
;         if (n + 1 < NCH) RG_STAGE(XCn);
;         if constexpr (CQ == 0) { if (n > 0) { const int ip = ((n >> 2) - 1) * NGW + gw; if (ip < CV_NIT) cv_finish(a.cv, ip, lane, cq0, cq1, cq2, cq3, CVS); } }
;         if (n + 2 < NCH) RG_LOAD(n + 2);
;         if (n + 1 < NCH) RG_LOADG(n + 1);
;         if constexpr (CV) { int idx = (n >> 2) * NGW + gw; idx = idx < CV_NIT ? idx : idx - CV_NIT;
;             if constexpr (CQ == 0) cv_issue_q(a.cv, idx, lane, cq0, 0); else if constexpr (CQ == 1) cv_issue_q(a.cv, idx, lane, cq1, 4); else if constexpr (CQ == 2) cv_issue_q(a.cv, idx, lane, cq2, 8); else cv_issue_q(a.cv, idx, lane, cq3, 12); }
;         const f32x4 zero4 = (f32x4){0.f, 0.f, 0.f, 0.f};
;         float av[4], uv[4]; float Aseg = 1.f, Hseg = 0.f;
;         { bf16x8 xf[4], waf[4], wxf[4]; unsigned xcr[4];
; #pragma unroll
;           for (int ks = 0; ks < 4; ++ks) { xf[ks] = *(const LAS bf16x8*)(XCc + (l0_ + fr) * S128 + ks * 64 + fq * 16);
;               waf[ks] = *(const LAS bf16x8*)(WAT + (16 * jtile + fr) * S128 + ks * 64 + fq * 16); wxf[ks] = *(const LAS bf16x8*)(WXT + (16 * jtile + fr) * S128 + ks * 64 + fq * 16); }
; #pragma unroll
;           for (int r = 0; r < 4; ++r) xcr[r] = *(const LAS unsigned short*)(XCc + (l0_ + 4 * fq + r) * S128 + (qq * 32 + jj) * 2);
;           f32x4 R = zero4, I = zero4;
; #pragma unroll
;           for (int ks = 0; ks < 4; ++ks) { R = __builtin_amdgcn_mfma_f32_16x16x32_bf16(xf[ks], waf[ks], R, 0, 0, 0); I = __builtin_amdgcn_mfma_f32_16x16x32_bf16(xf[ks], wxf[ks], I, 0, 0, 0); }
; #pragma unroll
;           for (int r = 0; r < 4; ++r) {
;               const float rr = fsigmoid(R[r] + bav), ig = fsigmoid(I[r] + bxv);
;               const float aa = fexp2(-sp8l2 * rr); const float om = __builtin_fmaf(-aa, aa, 1.0f);
.LBB0_287:
	s_lshr_b32 s79, s78, 6
	v_cvt_f32_u32_e32 v34, s79
	s_sub_i32 s90, 0, s79
	s_abs_i32 s89, s84
	s_ashr_i32 s88, s84, 31
	v_rcp_iflag_f32_e32 v34, v34
	v_mul_u32_u24_e32 v63, s78, v102
	v_or_b32_e32 v63, v63, v125
	v_lshlrev_b32_e32 v82, 2, v63
	v_mul_f32_e32 v34, 0x4f7ffffe, v34
	v_cvt_u32_f32_e32 v34, v34
	s_waitcnt vmcnt(15)
	v_lshlrev_b32_e32 v58, 16, v58
	s_waitcnt vmcnt(14)
	v_lshlrev_b32_e32 v56, 16, v56
	s_waitcnt vmcnt(13)
	v_lshlrev_b32_e32 v55, 16, v55
	v_readfirstlane_b32 s91, v34
	ds_read_b128 v[34:37], v164
	ds_read_b128 v[38:41], v103 offset:36864
	s_mul_i32 s90, s90, s91
	s_mul_hi_u32 s90, s91, s90
	s_add_i32 s91, s91, s90
	s_mul_hi_u32 s90, s89, s91
	s_mul_i32 s91, s90, s79
	s_sub_i32 s89, s89, s91
	s_add_i32 vcc_lo, s90, 1
	s_sub_i32 s91, s89, s79
	s_cmp_ge_u32 s89, s79
	ds_read_b128 v[42:45], v103 offset:46080
	ds_read_b128 v[46:49], v164 offset:64
	ds_read_b128 v[68:71], v103 offset:36928
	ds_read_b128 v[72:75], v103 offset:46144
	ds_read_b128 v[76:79], v164 offset:128
	s_cselect_b32 s90, vcc_lo, s90
	s_waitcnt lgkmcnt(5)
	v_mfma_f32_16x16x32_bf16 v[38:41], v[34:37], v[38:41], 0
	s_cselect_b32 s89, s91, s89
	s_add_i32 s91, s90, 1
	s_cmp_ge_u32 s89, s79
	s_cselect_b32 s89, s91, s90
	s_waitcnt lgkmcnt(4)
	v_mfma_f32_16x16x32_bf16 v[34:37], v[34:37], v[42:45], 0
	s_xor_b32 s89, s89, s88
	s_sub_i32 s88, s89, s88
	s_mul_i32 s79, s88, s79
	s_waitcnt lgkmcnt(2)
	v_mfma_f32_16x16x32_bf16 v[38:41], v[46:49], v[68:71], v[38:41]
	ds_read_b128 v[42:45], v103 offset:36992
	ds_read_b128 v[68:71], v164 offset:192
	s_lshl_b32 s88, s88, 6
	s_sub_i32 s79, s84, s79
	s_or_b32 s84, s88, 8
	s_waitcnt lgkmcnt(3)
	v_mfma_f32_16x16x32_bf16 v[34:37], v[46:49], v[72:75], v[34:37]
	ds_read_b128 v[46:49], v103 offset:37056
	s_mul_hi_i32 s91, s84, s78
	s_mul_i32 s90, s84, s78
	s_waitcnt lgkmcnt(2)
	v_mfma_f32_16x16x32_bf16 v[72:75], v[76:79], v[42:45], v[38:41]
	s_lshl_b32 s88, s79, 6
	s_lshl_b64 s[90:91], s[90:91], 2
	s_add_u32 s79, s40, s90
	s_addc_u32 s84, s41, s91
	s_ashr_i32 s89, s88, 31
	s_lshl_b64 s[40:41], s[88:89], 2
	s_waitcnt lgkmcnt(0)
	v_mfma_f32_16x16x32_bf16 v[72:75], v[68:71], v[46:49], v[72:75]
	s_add_u32 s40, s79, s40
	s_addc_u32 s41, s84, s41
	s_lshl_b32 s96, s78, 2
	v_lshl_add_u64 v[64:65], s[40:41], 0, v[82:83]
	v_lshl_add_u64 v[64:65], v[64:65], 0, s[96:97]
	s_nop 2
	v_add_f32_e32 v46, v165, v72
	v_lshl_add_u64 v[80:81], v[64:65], 0, s[96:97]
	global_load_dwordx4 v[38:41], v[64:65], off
	global_load_dwordx4 v[42:45], v[80:81], off
	ds_read_b128 v[178:181], v103 offset:46208
	ds_read_b128 v[182:185], v103 offset:46272
	v_mul_f32_e32 v46, 0xbfb8aa3b, v46
	v_exp_f32_e32 v48, v46
	s_waitcnt lgkmcnt(1)
	v_mfma_f32_16x16x32_bf16 v[76:79], v[76:79], v[178:181], v[34:37]
	v_lshl_add_u64 v[46:47], v[80:81], 0, s[96:97]
	v_add_f32_e32 v73, v165, v73
	s_nop 0
	v_add_f32_e32 v34, 1.0, v48
	v_rcp_f32_e32 v63, v34
	s_waitcnt lgkmcnt(0)
	v_mfma_f32_16x16x32_bf16 v[68:71], v[68:71], v[182:185], v[76:79]
	global_load_dwordx4 v[34:37], v82, s[40:41]
	s_nop 0
	global_load_dwordx4 v[46:49], v[46:47], off
	v_mul_f32_e32 v73, 0xbfb8aa3b, v73
	v_mul_f32_e64 v63, v63, -v168
	v_exp_f32_e32 v64, v63
	s_nop 1
	v_add_f32_e32 v63, v167, v68
	v_mul_f32_e32 v63, 0xbfb8aa3b, v63
	v_exp_f32_e32 v63, v63
	v_fma_f32 v65, -v64, v64, 1.0
	v_mul_f32_e32 v68, 0x4f800000, v65
	v_cmp_gt_f32_e32 vcc, s42, v65
	v_exp_f32_e32 v73, v73
	v_add_f32_e32 v63, 1.0, v63
	v_cndmask_b32_e32 v65, v65, v68, vcc
	v_sqrt_f32_e32 v68, v65
	v_rcp_f32_e32 v63, v63
	ds_read_u16 v72, v113
	ds_read_u16 v76, v113 offset:288
	ds_read_u16 v77, v113 offset:576
	ds_read_u16 v78, v113 offset:864
	v_add_u32_e32 v79, -1, v68
	v_fma_f32 v80, -v79, v68, v65
	v_cmp_ge_f32_e64 s[40:41], 0, v80
	v_add_u32_e32 v80, 1, v68
	s_waitcnt lgkmcnt(3)
	v_lshlrev_b32_e32 v72, 16, v72
	v_cndmask_b32_e64 v79, v68, v79, s[40:41]
	v_fma_f32 v68, -v80, v68, v65
	v_cmp_lt_f32_e64 s[40:41], 0, v68
	v_mul_f32_e32 v63, v63, v72
	s_nop 0
	v_cndmask_b32_e64 v68, v79, v80, s[40:41]
	v_mul_f32_e32 v79, 0x37800000, v68
	v_cndmask_b32_e32 v68, v68, v79, vcc
	v_cmp_class_f32_e32 vcc, v65, v158
	s_nop 1
	v_cndmask_b32_e32 v65, v68, v65, vcc
	v_add_f32_e32 v68, 1.0, v73
	v_rcp_f32_e32 v68, v68
	v_mul_f32_e32 v80, v63, v65
	v_mul_f32_e64 v63, v68, -v168
	v_exp_f32_e32 v81, v63
	v_add_f32_e32 v63, v167, v69
	v_mul_f32_e32 v63, 0xbfb8aa3b, v63
	v_exp_f32_e32 v63, v63
	v_fma_f32 v65, -v81, v81, 1.0
	v_mul_f32_e32 v68, 0x4f800000, v65
	v_cmp_gt_f32_e32 vcc, s42, v65
	v_add_f32_e32 v63, 1.0, v63
	v_rcp_f32_e32 v63, v63
	v_cndmask_b32_e32 v65, v65, v68, vcc
	v_sqrt_f32_e32 v68, v65
	v_fma_f32 v69, 0, v64, v80
	v_add_u32_e32 v72, -1, v68
	v_fma_f32 v73, -v72, v68, v65
	v_cmp_ge_f32_e64 s[40:41], 0, v73
	v_add_u32_e32 v73, 1, v68
	s_nop 0
	v_cndmask_b32_e64 v72, v68, v72, s[40:41]
	v_fma_f32 v68, -v73, v68, v65
	v_cmp_lt_f32_e64 s[40:41], 0, v68
	s_nop 1
	v_cndmask_b32_e64 v68, v72, v73, s[40:41]
	v_mul_f32_e32 v72, 0x37800000, v68
	v_cndmask_b32_e32 v68, v68, v72, vcc
	v_add_f32_e32 v72, v165, v74
	v_mul_f32_e32 v72, 0xbfb8aa3b, v72
	v_exp_f32_e32 v72, v72
	v_cmp_class_f32_e32 vcc, v65, v158
	v_add_f32_e32 v72, 1.0, v72
	v_rcp_f32_e32 v72, v72
	v_cndmask_b32_e32 v65, v68, v65, vcc
	s_waitcnt lgkmcnt(2)
; #define LAS __attribute__((address_space(3)))
; DI float bf2f(unsigned h) { return __uint_as_float(h << 16); }
; DI unsigned pk2(float lo, float hi) { f32x2 v = {lo, hi}; bf16v2 b = __builtin_convertvector(v, bf16v2); return __builtin_bit_cast(unsigned, b); }
; DI float fexp2(float x) { return __builtin_amdgcn_exp2f(x); }
; DI float fsigmoid(float x) { return frcp(1.0f + fexp2(-LOG2E * x)); }
; DI float fsilu(float x) { return x * fsigmoid(x); }
; #define LDS_BAR() do { asm volatile("s_waitcnt lgkmcnt(0)" ::: "memory"); __builtin_amdgcn_s_barrier(); asm volatile("" ::: "memory"); } while (0)
; DI void rglru_scan_unit(Frame& F, const Mix0Args& a, int u) {
;     ...
;           for (int r = 0; r < 4; ++r) {
;               const float rr = fsigmoid(R[r] + bav), ig = fsigmoid(I[r] + bxv);
;               const float aa = fexp2(-sp8l2 * rr); const float om = __builtin_fmaf(-aa, aa, 1.0f);
;               av[r] = aa; uv[r] = __builtin_sqrtf(om) * (ig * bf2f(xcr[r]));
;               Hseg = aa * Hseg + uv[r]; Aseg *= aa; } }
;         const int sgi = ltile * 4 + fq;
;         SEGA[jj * 20 + sgi] = Aseg; SEGH[jj * 20 + sgi] = Hseg;
;         LDS_BAR();
;         float carry = HPREV[jj * 20 + (n & 1)]; float sa[15], sh[15];
;         { f32x4 a4[4], h4[4];
; #pragma unroll
;           for (int i = 0; i < 4; ++i) { a4[i] = *(const LAS f32x4*)(SEGA + jj * 20 + 4 * i); h4[i] = *(const LAS f32x4*)(SEGH + jj * 20 + 4 * i); }
; #pragma unroll
;           for (int s = 0; s < 15; ++s) { sa[s] = a4[s >> 2][s & 3]; sh[s] = h4[s >> 2][s & 3]; } }
; #pragma unroll
;         for (int s = 0; s < 15; ++s) carry = (s < sgi) ? sa[s] * carry + sh[s] : carry;
; #pragma unroll
;         for (int r = 0; r < 4; ++r) { carry = av[r] * carry + uv[r];
;             const float o = carry * fsilu(bf2f(gb_cur[r]));
;             obcol[(row0 + l0_ + 4 * fq + r) * a.out_ld] = (bf16)(pk2(o, 0.f) & 0xffffu); }
;         if (sgi == 15) HPREV[jj * 20 + ((n + 1) & 1)] = carry;
	v_lshlrev_b32_e32 v68, 16, v76
	v_mul_f32_e32 v63, v63, v68
	v_mul_f32_e32 v82, v63, v65
	v_mul_f32_e64 v65, v72, -v168
	v_exp_f32_e32 v122, v65
	v_fma_f32 v63, v81, v69, v82
	v_add_f32_e32 v65, v167, v70
	v_mul_f32_e32 v65, 0xbfb8aa3b, v65
	v_fma_f32 v68, -v122, v122, 1.0
	v_mul_f32_e32 v69, 0x4f800000, v68
	v_cmp_gt_f32_e32 vcc, s42, v68
	v_exp_f32_e32 v65, v65
	v_mul_f32_e32 v70, v64, v81
	v_cndmask_b32_e32 v68, v68, v69, vcc
	v_sqrt_f32_e32 v69, v68
	v_add_f32_e32 v65, 1.0, v65
	v_rcp_f32_e32 v65, v65
	v_mul_f32_e32 v70, v122, v70
	v_add_u32_e32 v72, -1, v69
	v_fma_f32 v73, -v72, v69, v68
	v_cmp_ge_f32_e64 s[40:41], 0, v73
	v_add_u32_e32 v73, 1, v69
	s_nop 0
	v_cndmask_b32_e64 v72, v69, v72, s[40:41]
	v_fma_f32 v69, -v73, v69, v68
	v_cmp_lt_f32_e64 s[40:41], 0, v69
	s_nop 1
	v_cndmask_b32_e64 v69, v72, v73, s[40:41]
	v_mul_f32_e32 v72, 0x37800000, v69
	v_cndmask_b32_e32 v69, v69, v72, vcc
	v_add_f32_e32 v72, v165, v75
	v_mul_f32_e32 v72, 0xbfb8aa3b, v72
	v_exp_f32_e32 v72, v72
	v_cmp_class_f32_e32 vcc, v68, v158
	v_add_f32_e32 v72, 1.0, v72
	v_rcp_f32_e32 v72, v72
	v_cndmask_b32_e32 v68, v69, v68, vcc
	s_waitcnt lgkmcnt(1)
	v_lshlrev_b32_e32 v69, 16, v77
	v_mul_f32_e32 v65, v65, v69
	v_mul_f32_e32 v124, v65, v68
	v_fma_f32 v65, v122, v63, v124
	v_mul_f32_e64 v63, v72, -v168
	v_exp_f32_e32 v126, v63
	v_add_f32_e32 v63, v167, v71
	v_mul_f32_e32 v63, 0xbfb8aa3b, v63
	v_exp_f32_e32 v63, v63
	v_fma_f32 v68, -v126, v126, 1.0
	v_mul_f32_e32 v69, 0x4f800000, v68
	v_cmp_gt_f32_e32 vcc, s42, v68
	v_add_f32_e32 v63, 1.0, v63
	v_rcp_f32_e32 v63, v63
	v_cndmask_b32_e32 v68, v68, v69, vcc
	v_sqrt_f32_e32 v69, v68
	s_nop 0
	v_add_u32_e32 v71, -1, v69
	v_fma_f32 v72, -v71, v69, v68
	v_cmp_ge_f32_e64 s[40:41], 0, v72
	v_add_u32_e32 v72, 1, v69
	s_nop 0
	v_cndmask_b32_e64 v71, v69, v71, s[40:41]
	v_fma_f32 v69, -v72, v69, v68
	v_cmp_lt_f32_e64 s[40:41], 0, v69
	s_nop 1
	v_cndmask_b32_e64 v69, v71, v72, s[40:41]
	v_mul_f32_e32 v71, 0x37800000, v69
	v_cndmask_b32_e32 v69, v69, v71, vcc
	v_cmp_class_f32_e32 vcc, v68, v158
	s_mov_b32 s40, 0x25900000
	s_nop 0
	v_cndmask_b32_e32 v68, v69, v68, vcc
	s_waitcnt lgkmcnt(0)
	v_lshlrev_b32_e32 v69, 16, v78
	v_mul_f32_e32 v63, v63, v69
	v_mul_f32_e32 v63, v63, v68
	v_fma_f32 v65, v126, v65, v63
	v_mul_f32_e32 v68, v126, v70
	ds_write2st64_b32 v150, v68, v65 offset0:216 offset1:226
	s_waitcnt lgkmcnt(0)
	s_barrier
	ds_read_b32 v65, v149 offset:55360
	ds_read_b128 v[68:71], v149 offset:57856
	ds_read_b128 v[72:75], v149 offset:57872
	ds_read_b128 v[76:79], v149 offset:57888
	ds_read_b128 v[178:181], v149 offset:55296
	ds_read_b128 v[182:185], v149 offset:55312
	ds_read_b128 v[186:189], v149 offset:55328
	ds_read_b128 v[190:193], v149 offset:55344
	ds_read_b128 v[194:197], v149 offset:57904
	s_waitcnt lgkmcnt(4)
	v_fma_f32 v68, v65, v178, v68
	v_cndmask_b32_e64 v65, v68, v65, s[10:11]
	v_fma_f32 v68, v179, v65, v69
	v_cndmask_b32_e64 v65, v65, v68, s[12:13]
	v_fma_f32 v68, v180, v65, v70
	v_cndmask_b32_e64 v65, v65, v68, s[14:15]
	v_fmac_f32_e32 v71, v181, v65
	v_cndmask_b32_e64 v65, v71, v65, s[0:1]
	s_waitcnt lgkmcnt(3)
	v_fma_f32 v68, v182, v65, v72
	v_cndmask_b32_e64 v65, v65, v68, s[16:17]
	v_fma_f32 v68, v183, v65, v73
	v_cndmask_b32_e64 v65, v65, v68, s[18:19]
	v_fma_f32 v68, v184, v65, v74
	v_cndmask_b32_e64 v65, v65, v68, s[20:21]
	v_fmac_f32_e32 v75, v185, v65
	v_cndmask_b32_e64 v65, v65, v75, s[38:39]
	s_waitcnt lgkmcnt(2)
	v_fma_f32 v68, v186, v65, v76
	v_cndmask_b32_e64 v65, v65, v68, s[22:23]
	v_fma_f32 v68, v187, v65, v77
	v_cndmask_b32_e64 v65, v65, v68, s[24:25]
	v_fma_f32 v68, v188, v65, v78
	v_cndmask_b32_e64 v65, v65, v68, s[26:27]
	v_fmac_f32_e32 v79, v189, v65
	v_mul_f32_e32 v69, 0xbfb8aa3b, v58
	v_cndmask_b32_e64 v65, v65, v79, s[4:5]
	v_exp_f32_e32 v69, v69
	s_waitcnt lgkmcnt(0)
	v_fma_f32 v68, v190, v65, v194
	v_cndmask_b32_e64 v65, v65, v68, s[28:29]
	v_fma_f32 v68, v191, v65, v195
	v_cndmask_b32_e64 v65, v65, v68, s[30:31]
	v_add_f32_e32 v68, 1.0, v69
	v_rcp_f32_e32 v68, v68
	v_fmac_f32_e32 v196, v192, v65
	v_cndmask_b32_e64 v65, v65, v196, s[34:35]
	v_fmac_f32_e32 v80, v64, v65
	v_mul_f32_e32 v64, 0xbfb8aa3b, v56
	v_mul_f32_e32 v58, v68, v58
	v_exp_f32_e32 v68, v64
	v_mul_f32_e32 v58, v58, v80
	v_add_co_u32_e32 v64, vcc, s40, v66
	v_cvt_pk_bf16_f32 v58, v58, s0
	s_nop 0
	v_addc_co_u32_e32 v65, vcc, 0, v67, vcc
	global_store_short v[64:65], v58, off
	v_add_f32_e32 v58, 1.0, v68
	v_mul_f32_e32 v64, 0xbfb8aa3b, v55
	v_rcp_f32_e32 v58, v58
	v_exp_f32_e32 v64, v64
	v_fmac_f32_e32 v82, v81, v80
	s_mov_b32 s40, 0x2590c000
	v_mul_f32_e32 v56, v58, v56
	v_add_f32_e32 v58, 1.0, v64
	v_rcp_f32_e32 v58, v58
	v_mul_f32_e32 v56, v56, v82
	v_add_co_u32_e32 v64, vcc, s40, v66
	v_cvt_pk_bf16_f32 v56, v56, s0
	s_nop 0
	v_addc_co_u32_e32 v65, vcc, 0, v67, vcc
	v_mul_f32_e32 v55, v58, v55
	s_waitcnt vmcnt(17)
	v_lshlrev_b32_e32 v58, 16, v57
	global_store_short v[64:65], v56, off
	v_mul_f32_e32 v56, 0xbfb8aa3b, v58
	v_exp_f32_e32 v57, v56
	v_fmac_f32_e32 v124, v122, v82
	s_mov_b32 s40, 0x25918000
	v_mul_f32_e32 v55, v55, v124
	v_add_f32_e32 v57, 1.0, v57
	v_rcp_f32_e32 v64, v57
	v_add_co_u32_e32 v56, vcc, s40, v66
	v_cvt_pk_bf16_f32 v55, v55, s0
	s_nop 0
	v_addc_co_u32_e32 v57, vcc, 0, v67, vcc
	global_store_short v[56:57], v55, off
	v_fmac_f32_e32 v63, v126, v124
	v_mul_f32_e32 v55, v64, v58
	v_mul_f32_e32 v55, v55, v63
	s_mov_b64 s[100:101], 0x25924000
	v_lshl_add_u64 v[56:57], v[66:67], 0, s[100:101]
	v_cvt_pk_bf16_f32 v55, v55, s0
	global_store_short v[56:57], v55, off
	s_and_saveexec_b64 s[40:41], s[34:35]
	ds_write_b32 v149, v63 offset:55364
	s_or_b64 exec, exec, s[40:41]
	s_or_b32 s78, s93, 3
	s_cmpk_lt_u32 s78, 0x7f
	s_cselect_b64 s[40:41], -1, 0
	s_cmpk_gt_u32 s78, 0x7e
	s_cbranch_scc1 .LBB0_291
; #define LAS __attribute__((address_space(3)))
; #define LDS_BAR() do { asm volatile("s_waitcnt lgkmcnt(0)" ::: "memory"); __builtin_amdgcn_s_barrier(); asm volatile("" ::: "memory"); } while (0)
; #define RG_LOAD(n_) do { const long r0_ = (long)rowbase + (long)(n_) * 64; \
;         _Pragma("unroll") for (int i = 0; i < 11; ++i) xr[i] = ((n_) == 0 && 8 * rg - 3 + i < 0) ? 0u : *(const unsigned*)(xcol + (size_t)(r0_ + 8 * rg - 3 + i) * N1); } while (0)
; #define RG_LOADG(n_) do { const long r0_ = (long)rowbase + (long)(n_) * 64; \
;         _Pragma("unroll") for (int i = 0; i < 4; ++i) gbr[i] = *(const unsigned short*)(gbcol + (size_t)(r0_ + l0_ + 4 * fq + i) * N1); } while (0)
; #define RG_STAGE(xc_) do { LAS uchar* X_ = (xc_); \
;         _Pragma("unroll") for (int i = 0; i < 8; ++i) { f32x2 s2 = (f32x2){cbs[0], cbs[1]}; \
;             _Pragma("unroll") for (int k = 0; k < 4; ++k) s2 += (f32x2){cw[k][0], cw[k][1]} * (f32x2){bflo(xr[i + k]), bfhi(xr[i + k])}; \
;             *(LAS unsigned*)(X_ + (8 * rg + i) * S128 + c2 * 4) = pk2(s2.x, s2.y); } } while (0)
; DI void rglru_scan_unit(Frame& F, const Mix0Args& a, int u) {
;     ...
;     RG_LOAD(0);
;     RG_STAGE(XC0);
;     unsigned gb_cur[4];
;     RG_LOAD(1); RG_LOADG(0);
;     LDS_BAR();
;     const int nsl = cv_on ? min(NCH / 4, max(0, (CV_NIT - 8 * F.vcu + NGW - 1) / NGW)) : 0;
;     auto rg_step = [&](int n, auto cvt) __attribute__((always_inline)) {
;         constexpr int CQ = decltype(cvt)::value; constexpr bool CV = CQ >= 0;
;         const size_t row0 = rowbase + (size_t)n * 64;
;         LAS uchar* XCc = XC0 + (n & 1) * 64 * S128; LAS uchar* XCn = XC0 + ((n + 1) & 1) * 64 * S128;
;         LAS float* SEGA = SEG0 + (n & 1) * 1280; LAS float* SEGH = SEGA + 640;
; #pragma unroll
;         for (int i = 0; i < 4; ++i) gb_cur[i] = gbr[i];
;         if (n + 1 < NCH) RG_STAGE(XCn);
;         if constexpr (CQ == 0) { if (n > 0) { const int ip = ((n >> 2) - 1) * NGW + gw; if (ip < CV_NIT) cv_finish(a.cv, ip, lane, cq0, cq1, cq2, cq3, CVS); } }
;         if (n + 2 < NCH) RG_LOAD(n + 2);
;         if (n + 1 < NCH) RG_LOADG(n + 1);
	v_lshlrev_b32_e32 v56, 16, v130
	v_and_b32_e32 v57, 0xffff0000, v130
	v_pk_fma_f32 v[56:57], v[104:105], v[56:57], v[100:101]
	v_lshlrev_b32_e32 v64, 16, v132
	v_and_b32_e32 v65, 0xffff0000, v132
	v_pk_fma_f32 v[56:57], v[106:107], v[64:65], v[56:57]
	v_lshlrev_b32_e32 v68, 16, v134
	v_and_b32_e32 v69, 0xffff0000, v134
	v_pk_fma_f32 v[56:57], v[108:109], v[68:69], v[56:57]
	s_waitcnt vmcnt(19)
	v_lshlrev_b32_e32 v70, 16, v169
	v_and_b32_e32 v71, 0xffff0000, v169
	v_pk_fma_f32 v[56:57], v[110:111], v[70:71], v[56:57]
	s_nop 0
	v_cvt_pk_bf16_f32 v55, v56, v57
	v_pk_fma_f32 v[56:57], v[104:105], v[64:65], v[100:101]
	s_waitcnt vmcnt(18)
	v_lshlrev_b32_e32 v64, 16, v170
	v_pk_fma_f32 v[56:57], v[106:107], v[68:69], v[56:57]
	v_and_b32_e32 v65, 0xffff0000, v170
	v_pk_fma_f32 v[56:57], v[108:109], v[70:71], v[56:57]
	s_nop 0
	v_pk_fma_f32 v[56:57], v[110:111], v[64:65], v[56:57]
	s_nop 0
	v_cvt_pk_bf16_f32 v56, v56, v57
	ds_write2_b32 v123, v55, v56 offset1:72
	v_pk_fma_f32 v[56:57], v[104:105], v[68:69], v[100:101]
	s_waitcnt vmcnt(17)
	v_lshlrev_b32_e32 v68, 16, v171
	v_pk_fma_f32 v[56:57], v[106:107], v[70:71], v[56:57]
	v_and_b32_e32 v69, 0xffff0000, v171
	v_pk_fma_f32 v[56:57], v[108:109], v[64:65], v[56:57]
	s_nop 0
	v_pk_fma_f32 v[56:57], v[110:111], v[68:69], v[56:57]
	s_nop 0
	v_cvt_pk_bf16_f32 v55, v56, v57
	v_pk_fma_f32 v[56:57], v[104:105], v[70:71], v[100:101]
	s_waitcnt vmcnt(16)
	v_lshlrev_b32_e32 v70, 16, v172
	v_pk_fma_f32 v[56:57], v[106:107], v[64:65], v[56:57]
	v_and_b32_e32 v71, 0xffff0000, v172
	v_pk_fma_f32 v[56:57], v[108:109], v[68:69], v[56:57]
	s_nop 0
	v_pk_fma_f32 v[56:57], v[110:111], v[70:71], v[56:57]
	s_nop 0
	v_cvt_pk_bf16_f32 v56, v56, v57
	ds_write2_b32 v123, v55, v56 offset0:144 offset1:216
	v_pk_fma_f32 v[56:57], v[104:105], v[64:65], v[100:101]
	s_waitcnt vmcnt(15)
	v_lshlrev_b32_e32 v64, 16, v173
	v_pk_fma_f32 v[56:57], v[106:107], v[68:69], v[56:57]
	v_and_b32_e32 v65, 0xffff0000, v173
	v_pk_fma_f32 v[56:57], v[108:109], v[70:71], v[56:57]
	s_nop 0
	v_pk_fma_f32 v[56:57], v[110:111], v[64:65], v[56:57]
	s_nop 0
	v_cvt_pk_bf16_f32 v55, v56, v57
	v_pk_fma_f32 v[56:57], v[104:105], v[68:69], v[100:101]
	s_waitcnt vmcnt(14)
	v_lshlrev_b32_e32 v68, 16, v174
	v_pk_fma_f32 v[56:57], v[106:107], v[70:71], v[56:57]
	v_and_b32_e32 v69, 0xffff0000, v174
	v_pk_fma_f32 v[56:57], v[108:109], v[64:65], v[56:57]
	s_nop 0
	v_pk_fma_f32 v[56:57], v[110:111], v[68:69], v[56:57]
	s_nop 0
	v_cvt_pk_bf16_f32 v56, v56, v57
	ds_write2_b32 v54, v55, v56 offset0:32 offset1:104
	v_pk_fma_f32 v[56:57], v[104:105], v[70:71], v[100:101]
	s_waitcnt vmcnt(13)
	v_lshlrev_b32_e32 v70, 16, v175
	v_pk_fma_f32 v[56:57], v[106:107], v[64:65], v[56:57]
	v_and_b32_e32 v71, 0xffff0000, v175
	v_pk_fma_f32 v[56:57], v[108:109], v[68:69], v[56:57]
	s_nop 0
	v_pk_fma_f32 v[56:57], v[110:111], v[70:71], v[56:57]
	s_nop 0
	v_cvt_pk_bf16_f32 v55, v56, v57
	v_pk_fma_f32 v[56:57], v[104:105], v[64:65], v[100:101]
	s_waitcnt vmcnt(12)
	v_lshlrev_b32_e32 v64, 16, v176
	v_pk_fma_f32 v[56:57], v[106:107], v[68:69], v[56:57]
	v_and_b32_e32 v65, 0xffff0000, v176
	v_pk_fma_f32 v[56:57], v[108:109], v[70:71], v[56:57]
	s_nop 0
	v_pk_fma_f32 v[56:57], v[110:111], v[64:65], v[56:57]
	s_nop 0
	v_cvt_pk_bf16_f32 v56, v56, v57
	ds_write2_b32 v54, v55, v56 offset0:176 offset1:248
.LBB0_291:
	s_cmpk_gt_u32 s78, 0x7d
	s_cbranch_scc1 .LBB0_293
	s_mov_b64 s[100:101], 0x261e4000
	v_lshl_add_u64 v[54:55], v[50:51], 0, s[100:101]
	global_load_dword v130, v[54:55], off
	s_mov_b64 s[100:101], 0x261f0000
	v_lshl_add_u64 v[54:55], v[50:51], 0, s[100:101]
	global_load_dword v132, v[54:55], off
	s_mov_b64 s[100:101], 0x261fc000
	v_lshl_add_u64 v[54:55], v[50:51], 0, s[100:101]
	global_load_dword v134, v[54:55], off
	s_mov_b64 s[100:101], 0x26208000
	v_lshl_add_u64 v[54:55], v[50:51], 0, s[100:101]
	global_load_dword v169, v[54:55], off
	s_mov_b64 s[100:101], 0x26214000
	v_lshl_add_u64 v[54:55], v[50:51], 0, s[100:101]
	global_load_dword v170, v[54:55], off
	s_mov_b64 s[100:101], 0x26220000
	v_lshl_add_u64 v[54:55], v[50:51], 0, s[100:101]
	global_load_dword v171, v[54:55], off
	s_mov_b64 s[100:101], 0x2622c000
	v_lshl_add_u64 v[54:55], v[50:51], 0, s[100:101]
	global_load_dword v172, v[54:55], off
	s_mov_b64 s[100:101], 0x26238000
	v_lshl_add_u64 v[54:55], v[50:51], 0, s[100:101]
	global_load_dword v173, v[54:55], off
	s_mov_b64 s[100:101], 0x26244000
	v_lshl_add_u64 v[54:55], v[50:51], 0, s[100:101]
	global_load_dword v174, v[54:55], off
	s_mov_b64 s[100:101], 0x26250000
	v_lshl_add_u64 v[54:55], v[50:51], 0, s[100:101]
	s_mov_b64 s[100:101], 0x2625c000
	v_lshl_add_u64 v[50:51], v[50:51], 0, s[100:101]
	global_load_dword v175, v[54:55], off
	global_load_dword v176, v[50:51], off
.LBB0_293:
	s_waitcnt vmcnt(11)
	v_and_b32_e32 v71, 0xffff, v59
	s_waitcnt vmcnt(10)
	v_and_b32_e32 v70, 0xffff, v60
	s_waitcnt vmcnt(9)
	v_and_b32_e32 v69, 0xffff, v61
	s_waitcnt vmcnt(8)
	v_and_b32_e32 v68, 0xffff, v62
	s_andn2_b64 vcc, exec, s[40:41]
	v_mov_b32_e32 v178, v68
	v_mov_b32_e32 v179, v69
	v_mov_b32_e32 v180, v70
	v_mov_b32_e32 v181, v71
	s_cbranch_vccnz .LBB0_295
	s_mov_b64 s[100:101], 0x25f0a000
	v_lshl_add_u64 v[50:51], v[52:53], 0, s[100:101]
	global_load_ushort v181, v[50:51], off
	s_mov_b64 s[100:101], 0x25f16000
	v_lshl_add_u64 v[50:51], v[52:53], 0, s[100:101]
	global_load_ushort v180, v[50:51], off
	s_mov_b64 s[100:101], 0x25f22000
	v_lshl_add_u64 v[50:51], v[52:53], 0, s[100:101]
	global_load_ushort v179, v[50:51], off
	s_mov_b64 s[100:101], 0x25f2e000
	v_lshl_add_u64 v[50:51], v[52:53], 0, s[100:101]
	global_load_ushort v178, v[50:51], off

; #define LAS __attribute__((address_space(3)))
; DI void rglru_scan_unit(Frame& F, const Mix0Args& a, int u) {
;     ...
;     auto rg_step = [&](int n, auto cvt) __attribute__((always_inline)) {
;         constexpr int CQ = decltype(cvt)::value; constexpr bool CV = CQ >= 0;
;         const size_t row0 = rowbase + (size_t)n * 64;
;         LAS uchar* XCc = XC0 + (n & 1) * 64 * S128; LAS uchar* XCn = XC0 + ((n + 1) & 1) * 64 * S128;
;         LAS float* SEGA = SEG0 + (n & 1) * 1280; LAS float* SEGH = SEGA + 640;
; #pragma unroll
;         for (int i = 0; i < 4; ++i) gb_cur[i] = gbr[i];
;         if (n + 1 < NCH) RG_STAGE(XCn);
;         if constexpr (CQ == 0) { if (n > 0) { const int ip = ((n >> 2) - 1) * NGW + gw; if (ip < CV_NIT) cv_finish(a.cv, ip, lane, cq0, cq1, cq2, cq3, CVS); } }
;         if (n + 2 < NCH) RG_LOAD(n + 2);
;         if (n + 1 < NCH) RG_LOADG(n + 1);
;         if constexpr (CV) { int idx = (n >> 2) * NGW + gw; idx = idx < CV_NIT ? idx : idx - CV_NIT;
;             if constexpr (CQ == 0) cv_issue_q(a.cv, idx, lane, cq0, 0); else if constexpr (CQ == 1) cv_issue_q(a.cv, idx, lane, cq1, 4); else if constexpr (CQ == 2) cv_issue_q(a.cv, idx, lane, cq2, 8); else cv_issue_q(a.cv, idx, lane, cq3, 12); }
;         const f32x4 zero4 = (f32x4){0.f, 0.f, 0.f, 0.f};
;         float av[4], uv[4]; float Aseg = 1.f, Hseg = 0.f;
;         { bf16x8 xf[4], waf[4], wxf[4]; unsigned xcr[4];
; #pragma unroll
;           for (int ks = 0; ks < 4; ++ks) { xf[ks] = *(const LAS bf16x8*)(XCc + (l0_ + fr) * S128 + ks * 64 + fq * 16);
;               waf[ks] = *(const LAS bf16x8*)(WAT + (16 * jtile + fr) * S128 + ks * 64 + fq * 16); wxf[ks] = *(const LAS bf16x8*)(WXT + (16 * jtile + fr) * S128 + ks * 64 + fq * 16); }
; #pragma unroll
;           for (int r = 0; r < 4; ++r) xcr[r] = *(const LAS unsigned short*)(XCc + (l0_ + 4 * fq + r) * S128 + (qq * 32 + jj) * 2);
;           f32x4 R = zero4, I = zero4;
; #pragma unroll
;           for (int ks = 0; ks < 4; ++ks) { R = __builtin_amdgcn_mfma_f32_16x16x32_bf16(xf[ks], waf[ks], R, 0, 0, 0); I = __builtin_amdgcn_mfma_f32_16x16x32_bf16(xf[ks], wxf[ks], I, 0, 0, 0); }
; #pragma unroll
;           for (int r = 0; r < 4; ++r) {
;               const float rr = fsigmoid(R[r] + bav), ig = fsigmoid(I[r] + bxv);
;               const float aa = fexp2(-sp8l2 * rr); const float om = __builtin_fmaf(-aa, aa, 1.0f);
.LBB0_302:
	s_lshr_b32 s41, s40, 6
	v_cvt_f32_u32_e32 v50, s41
	s_sub_i32 s84, 0, s41
	s_abs_i32 s79, s87
	s_ashr_i32 s78, s87, 31
	v_rcp_iflag_f32_e32 v50, v50
	v_mul_u32_u24_e32 v76, s40, v102
	v_or_b32_e32 v80, v76, v125
	v_lshlrev_b32_e32 v82, 2, v80
	v_mul_f32_e32 v50, 0x4f7ffffe, v50
	v_cvt_u32_f32_e32 v50, v50
	v_lshlrev_b32_e32 v71, 16, v71
	v_lshlrev_b32_e32 v69, 16, v69
	ds_read_b128 v[54:57], v103 offset:36864
	v_readfirstlane_b32 s88, v50
	ds_read_b128 v[50:53], v164 offset:18432
	s_mul_i32 s84, s84, s88
	s_mul_hi_u32 s84, s88, s84
	s_add_i32 s88, s88, s84
	s_mul_hi_u32 s84, s79, s88
	s_mul_i32 s88, s84, s41
	s_sub_i32 s79, s79, s88
	s_add_i32 s89, s84, 1
	s_sub_i32 s88, s79, s41
	s_cmp_ge_u32 s79, s41
	ds_read_b128 v[58:61], v103 offset:46080
	ds_read_b128 v[62:65], v164 offset:18496
	ds_read_b128 v[72:75], v103 offset:36928
	ds_read_b128 v[76:79], v103 offset:46144
	ds_read_b128 v[182:185], v164 offset:18560
	s_cselect_b32 s84, s89, s84
	s_waitcnt lgkmcnt(5)
	v_mfma_f32_16x16x32_bf16 v[54:57], v[50:53], v[54:57], 0
	s_cselect_b32 s79, s88, s79
	s_add_i32 s88, s84, 1
	s_cmp_ge_u32 s79, s41
	s_cselect_b32 s79, s88, s84
	s_waitcnt lgkmcnt(4)
	v_mfma_f32_16x16x32_bf16 v[50:53], v[50:53], v[58:61], 0
	s_xor_b32 s79, s79, s78
	s_sub_i32 s78, s79, s78
	s_mul_i32 s41, s78, s41
	s_waitcnt lgkmcnt(2)
	v_mfma_f32_16x16x32_bf16 v[54:57], v[62:65], v[72:75], v[54:57]
	ds_read_b128 v[58:61], v103 offset:36992
	ds_read_b128 v[72:75], v164 offset:18624
	s_lshl_b32 s78, s78, 6
	s_or_b32 s79, s78, 12
	s_waitcnt lgkmcnt(3)
	v_mfma_f32_16x16x32_bf16 v[50:53], v[62:65], v[76:79], v[50:53]
	ds_read_b128 v[76:79], v103 offset:37056
	s_sub_i32 s41, s87, s41
	s_mul_hi_i32 s89, s79, s40
	s_mul_i32 s88, s79, s40
	s_waitcnt lgkmcnt(2)
	v_mfma_f32_16x16x32_bf16 v[54:57], v[182:185], v[58:61], v[54:57]
	s_lshl_b32 s78, s41, 6
	s_lshl_b64 s[88:89], s[88:89], 2
	s_add_u32 s41, s36, s88
	s_addc_u32 s84, s37, s89
	s_ashr_i32 s79, s78, 31
	s_lshl_b64 s[36:37], s[78:79], 2
	s_waitcnt lgkmcnt(0)
	v_mfma_f32_16x16x32_bf16 v[76:79], v[72:75], v[76:79], v[54:57]
	s_add_u32 s36, s41, s36
	s_addc_u32 s37, s84, s37
	s_lshl_b32 s96, s40, 2
	v_lshl_add_u64 v[80:81], s[36:37], 0, v[82:83]
	v_lshl_add_u64 v[62:63], v[80:81], 0, s[96:97]
	s_nop 2
	v_add_f32_e32 v54, v165, v76
	v_lshl_add_u64 v[80:81], v[62:63], 0, s[96:97]
	global_load_dwordx4 v[58:61], v[62:63], off
	s_nop 0
	global_load_dwordx4 v[62:65], v[80:81], off
	ds_read_b128 v[186:189], v103 offset:46208
	ds_read_b128 v[190:193], v103 offset:46272
	v_mul_f32_e32 v54, 0xbfb8aa3b, v54
	v_exp_f32_e32 v54, v54
	s_waitcnt lgkmcnt(1)
	v_mfma_f32_16x16x32_bf16 v[182:185], v[182:185], v[186:189], v[50:53]
	v_lshl_add_u64 v[80:81], v[80:81], 0, s[96:97]
	v_add_f32_e32 v77, v165, v77
	s_nop 0
	v_add_f32_e32 v50, 1.0, v54
	v_rcp_f32_e32 v76, v50
	global_load_dwordx4 v[54:57], v82, s[36:37]
	global_load_dwordx4 v[50:53], v[80:81], off
	s_waitcnt lgkmcnt(0)
	v_mfma_f32_16x16x32_bf16 v[72:75], v[72:75], v[190:193], v[182:185]
	v_mul_f32_e32 v77, 0xbfb8aa3b, v77
	v_mul_f32_e64 v76, v76, -v168
	v_exp_f32_e32 v82, v76
	v_exp_f32_e32 v77, v77
	ds_read_u16 v81, v177 offset:18432
	ds_read_u16 v122, v177 offset:18720
	ds_read_u16 v124, v177 offset:19008
	ds_read_u16 v126, v177 offset:19296
	v_add_f32_e32 v72, v167, v72
	v_fma_f32 v76, -v82, v82, 1.0
	v_mul_f32_e32 v80, 0x4f800000, v76
	v_cmp_gt_f32_e32 vcc, s42, v76
	v_mul_f32_e32 v72, 0xbfb8aa3b, v72
	v_exp_f32_e32 v72, v72
	v_cndmask_b32_e32 v76, v76, v80, vcc
	v_sqrt_f32_e32 v80, v76
	v_add_f32_e32 v77, 1.0, v77
	v_add_f32_e32 v72, 1.0, v72
	v_rcp_f32_e32 v72, v72
	v_add_u32_e32 v128, -1, v80
	v_fma_f32 v182, -v128, v80, v76
	v_cmp_ge_f32_e64 s[36:37], 0, v182
	v_add_u32_e32 v182, 1, v80
	v_rcp_f32_e32 v77, v77
	v_cndmask_b32_e64 v128, v80, v128, s[36:37]
	v_fma_f32 v80, -v182, v80, v76
	v_cmp_lt_f32_e64 s[36:37], 0, v80
	v_add_f32_e32 v78, v165, v78
	v_mul_f32_e32 v78, 0xbfb8aa3b, v78
	v_cndmask_b32_e64 v80, v128, v182, s[36:37]
	v_mul_f32_e32 v128, 0x37800000, v80
	v_cndmask_b32_e32 v80, v80, v128, vcc
	v_cmp_class_f32_e32 vcc, v76, v158
	v_exp_f32_e32 v78, v78
	v_add_f32_e32 v74, v167, v74
	v_cndmask_b32_e32 v76, v80, v76, vcc
	s_waitcnt lgkmcnt(3)
	v_lshlrev_b32_e32 v80, 16, v81
	v_mul_f32_e32 v72, v72, v80
	v_mul_f32_e32 v128, v72, v76
	v_mul_f32_e64 v72, v77, -v168
	v_exp_f32_e32 v206, v72
	v_add_f32_e32 v72, v167, v73
	v_mul_f32_e32 v72, 0xbfb8aa3b, v72
	v_exp_f32_e32 v72, v72
	v_fma_f32 v73, -v206, v206, 1.0
	v_mul_f32_e32 v76, 0x4f800000, v73
	v_cmp_gt_f32_e32 vcc, s42, v73
	v_add_f32_e32 v72, 1.0, v72
	v_add_f32_e32 v78, 1.0, v78
	v_cndmask_b32_e32 v73, v73, v76, vcc
	v_sqrt_f32_e32 v76, v73
	v_rcp_f32_e32 v72, v72
	v_rcp_f32_e32 v78, v78
	v_fma_f32 v77, 0, v82, v128
	v_add_u32_e32 v80, -1, v76
	v_fma_f32 v81, -v80, v76, v73
	v_cmp_ge_f32_e64 s[36:37], 0, v81
	v_add_u32_e32 v81, 1, v76
	v_mul_f32_e32 v74, 0xbfb8aa3b, v74
	v_cndmask_b32_e64 v80, v76, v80, s[36:37]
	v_fma_f32 v76, -v81, v76, v73
	v_cmp_lt_f32_e64 s[36:37], 0, v76
	v_exp_f32_e32 v74, v74
	v_add_f32_e32 v79, v165, v79
	v_cndmask_b32_e64 v76, v80, v81, s[36:37]
	v_mul_f32_e32 v80, 0x37800000, v76
	v_cndmask_b32_e32 v76, v76, v80, vcc
	v_cmp_class_f32_e32 vcc, v73, v158
	v_mul_f32_e32 v79, 0xbfb8aa3b, v79
	v_exp_f32_e32 v79, v79
	v_cndmask_b32_e32 v73, v76, v73, vcc
	s_waitcnt lgkmcnt(2)
; #define LAS __attribute__((address_space(3)))
; DI float bf2f(unsigned h) { return __uint_as_float(h << 16); }
; DI unsigned pk2(float lo, float hi) { f32x2 v = {lo, hi}; bf16v2 b = __builtin_convertvector(v, bf16v2); return __builtin_bit_cast(unsigned, b); }
; DI float fexp2(float x) { return __builtin_amdgcn_exp2f(x); }
; DI float fsigmoid(float x) { return frcp(1.0f + fexp2(-LOG2E * x)); }
; DI float fsilu(float x) { return x * fsigmoid(x); }
; #define LDS_BAR() do { asm volatile("s_waitcnt lgkmcnt(0)" ::: "memory"); __builtin_amdgcn_s_barrier(); asm volatile("" ::: "memory"); } while (0)
; DI void rglru_scan_unit(Frame& F, const Mix0Args& a, int u) {
;     ...
;           for (int r = 0; r < 4; ++r) {
;               const float rr = fsigmoid(R[r] + bav), ig = fsigmoid(I[r] + bxv);
;               const float aa = fexp2(-sp8l2 * rr); const float om = __builtin_fmaf(-aa, aa, 1.0f);
;               av[r] = aa; uv[r] = __builtin_sqrtf(om) * (ig * bf2f(xcr[r]));
;               Hseg = aa * Hseg + uv[r]; Aseg *= aa; } }
;         const int sgi = ltile * 4 + fq;
;         SEGA[jj * 20 + sgi] = Aseg; SEGH[jj * 20 + sgi] = Hseg;
;         LDS_BAR();
;         float carry = HPREV[jj * 20 + (n & 1)]; float sa[15], sh[15];
;         { f32x4 a4[4], h4[4];
; #pragma unroll
;           for (int i = 0; i < 4; ++i) { a4[i] = *(const LAS f32x4*)(SEGA + jj * 20 + 4 * i); h4[i] = *(const LAS f32x4*)(SEGH + jj * 20 + 4 * i); }
; #pragma unroll
;           for (int s = 0; s < 15; ++s) { sa[s] = a4[s >> 2][s & 3]; sh[s] = h4[s >> 2][s & 3]; } }
; #pragma unroll
;         for (int s = 0; s < 15; ++s) carry = (s < sgi) ? sa[s] * carry + sh[s] : carry;
; #pragma unroll
;         for (int r = 0; r < 4; ++r) { carry = av[r] * carry + uv[r];
;             const float o = carry * fsilu(bf2f(gb_cur[r]));
;             obcol[(row0 + l0_ + 4 * fq + r) * a.out_ld] = (bf16)(pk2(o, 0.f) & 0xffffu); }
;         if (sgi == 15) HPREV[jj * 20 + ((n + 1) & 1)] = carry;
	v_lshlrev_b32_e32 v76, 16, v122
	v_mul_f32_e32 v72, v72, v76
	v_mul_f32_e64 v76, v78, -v168
	v_exp_f32_e32 v122, v76
	v_mul_f32_e32 v73, v72, v73
	v_fma_f32 v72, v206, v77, v73
	v_add_f32_e32 v74, 1.0, v74
	v_fma_f32 v76, -v122, v122, 1.0
	v_mul_f32_e32 v77, 0x4f800000, v76
	v_cmp_gt_f32_e32 vcc, s42, v76
	v_rcp_f32_e32 v74, v74
	v_add_f32_e32 v79, 1.0, v79
	v_cndmask_b32_e32 v76, v76, v77, vcc
	v_sqrt_f32_e32 v77, v76
	v_rcp_f32_e32 v79, v79
	v_mul_f32_e32 v78, v82, v206
	v_add_u32_e32 v80, -1, v77
	v_fma_f32 v81, -v80, v77, v76
	v_cmp_ge_f32_e64 s[36:37], 0, v81
	v_add_u32_e32 v81, 1, v77
	s_nop 0
	v_cndmask_b32_e64 v80, v77, v80, s[36:37]
	v_fma_f32 v77, -v81, v77, v76
	v_cmp_lt_f32_e64 s[36:37], 0, v77
	s_nop 1
	v_cndmask_b32_e64 v77, v80, v81, s[36:37]
	v_mul_f32_e32 v80, 0x37800000, v77
	v_cndmask_b32_e32 v77, v77, v80, vcc
	v_cmp_class_f32_e32 vcc, v76, v158
	s_nop 1
	v_cndmask_b32_e32 v76, v77, v76, vcc
	s_waitcnt lgkmcnt(1)
	v_lshlrev_b32_e32 v77, 16, v124
	v_mul_f32_e32 v74, v74, v77
	v_mul_f32_e32 v124, v74, v76
	v_fma_f32 v74, v122, v72, v124
	v_mul_f32_e64 v72, v79, -v168
	v_exp_f32_e32 v207, v72
	v_add_f32_e32 v72, v167, v75
	v_mul_f32_e32 v72, 0xbfb8aa3b, v72
	v_exp_f32_e32 v72, v72
	v_fma_f32 v75, -v207, v207, 1.0
	v_mul_f32_e32 v76, 0x4f800000, v75
	v_cmp_gt_f32_e32 vcc, s42, v75
	v_mul_f32_e32 v77, v122, v78
	v_add_f32_e32 v72, 1.0, v72
	v_cndmask_b32_e32 v75, v75, v76, vcc
	v_sqrt_f32_e32 v76, v75
	v_rcp_f32_e32 v72, v72
	v_add_u32_e32 v78, -1, v76
	v_fma_f32 v79, -v78, v76, v75
	v_cmp_ge_f32_e64 s[36:37], 0, v79
	v_add_u32_e32 v79, 1, v76
	s_nop 0
	v_cndmask_b32_e64 v78, v76, v78, s[36:37]
	v_fma_f32 v76, -v79, v76, v75
	v_cmp_lt_f32_e64 s[36:37], 0, v76
	s_nop 1
	v_cndmask_b32_e64 v76, v78, v79, s[36:37]
	v_mul_f32_e32 v78, 0x37800000, v76
	v_cndmask_b32_e32 v76, v76, v78, vcc
	v_cmp_class_f32_e32 vcc, v75, v158
	s_mov_b32 s36, 0x25c00000
	s_nop 0
	v_cndmask_b32_e32 v75, v76, v75, vcc
	s_waitcnt lgkmcnt(0)
	v_lshlrev_b32_e32 v76, 16, v126
	v_mul_f32_e32 v72, v72, v76
	v_mul_f32_e32 v72, v72, v75
	v_fma_f32 v74, v207, v74, v72
	v_mul_f32_e32 v75, v207, v77
	ds_write2st64_b32 v150, v75, v74 offset0:236 offset1:246
	s_waitcnt lgkmcnt(0)
	s_barrier
	ds_read_b32 v126, v149 offset:55364
	ds_read_b128 v[74:77], v149 offset:60416
	ds_read_b128 v[78:81], v149 offset:62976
	ds_read_b128 v[182:185], v149 offset:60432
	ds_read_b128 v[186:189], v149 offset:60448
	ds_read_b128 v[190:193], v149 offset:62992
	ds_read_b128 v[194:197], v149 offset:63008
	ds_read_b128 v[198:201], v149 offset:60464
	ds_read_b128 v[202:205], v149 offset:63024
	s_waitcnt lgkmcnt(6)
	v_fma_f32 v74, v126, v74, v78
	v_cndmask_b32_e64 v74, v74, v126, s[10:11]
	v_fma_f32 v75, v75, v74, v79
	v_cndmask_b32_e64 v74, v74, v75, s[12:13]
	v_fma_f32 v75, v76, v74, v80
	v_cndmask_b32_e64 v74, v74, v75, s[14:15]
	v_fmac_f32_e32 v81, v77, v74
	v_cndmask_b32_e64 v74, v81, v74, s[0:1]
	s_waitcnt lgkmcnt(3)
	v_fma_f32 v75, v182, v74, v190
	v_cndmask_b32_e64 v74, v74, v75, s[16:17]
	v_fma_f32 v75, v183, v74, v191
	v_cndmask_b32_e64 v74, v74, v75, s[18:19]
	v_fma_f32 v75, v184, v74, v192
	v_cndmask_b32_e64 v74, v74, v75, s[20:21]
	v_fmac_f32_e32 v193, v185, v74
	v_cndmask_b32_e64 v74, v74, v193, s[38:39]
	s_waitcnt lgkmcnt(2)
	v_fma_f32 v75, v186, v74, v194
	v_cndmask_b32_e64 v74, v74, v75, s[22:23]
	v_fma_f32 v75, v187, v74, v195
	v_cndmask_b32_e64 v74, v74, v75, s[24:25]
	v_fma_f32 v75, v188, v74, v196
	v_cndmask_b32_e64 v74, v74, v75, s[26:27]
	v_fmac_f32_e32 v197, v189, v74
	v_mul_f32_e32 v76, 0xbfb8aa3b, v71
	v_cndmask_b32_e64 v74, v74, v197, s[4:5]
	v_exp_f32_e32 v76, v76
	s_waitcnt lgkmcnt(0)
	v_fma_f32 v75, v198, v74, v202
	v_cndmask_b32_e64 v74, v74, v75, s[28:29]
	v_fma_f32 v75, v199, v74, v203
	v_cndmask_b32_e64 v74, v74, v75, s[30:31]
	v_add_f32_e32 v75, 1.0, v76
	v_rcp_f32_e32 v75, v75
	v_fmac_f32_e32 v204, v200, v74
	v_cndmask_b32_e64 v74, v74, v204, s[34:35]
	v_fmac_f32_e32 v128, v82, v74
	v_mul_f32_e32 v71, v75, v71
	v_lshlrev_b32_e32 v75, 16, v70
	v_mul_f32_e32 v70, 0xbfb8aa3b, v75
	v_exp_f32_e32 v76, v70
	v_mul_f32_e32 v71, v71, v128
	v_add_co_u32_e32 v70, vcc, s36, v66
	v_cvt_pk_bf16_f32 v74, v71, s0
	s_nop 0
	v_addc_co_u32_e32 v71, vcc, 0, v67, vcc
	global_store_short v[70:71], v74, off
	v_add_f32_e32 v70, 1.0, v76
	v_rcp_f32_e32 v70, v70
	v_mul_f32_e32 v71, 0xbfb8aa3b, v69
	v_exp_f32_e32 v71, v71
	v_fmac_f32_e32 v73, v206, v128
	v_mul_f32_e32 v70, v70, v75
	v_mul_f32_e32 v70, v70, v73
	v_cvt_pk_bf16_f32 v74, v70, s0
	v_add_f32_e32 v70, 1.0, v71
	s_mov_b32 s36, 0x25c0c000
	v_rcp_f32_e32 v75, v70
	v_add_co_u32_e32 v70, vcc, s36, v66
	v_fmac_f32_e32 v124, v122, v73
	s_nop 0
	v_addc_co_u32_e32 v71, vcc, 0, v67, vcc
	global_store_short v[70:71], v74, off
	v_lshlrev_b32_e32 v70, 16, v68
	v_mul_f32_e32 v68, 0xbfb8aa3b, v70
	v_exp_f32_e32 v71, v68
	v_mul_f32_e32 v69, v75, v69
	v_mul_f32_e32 v69, v69, v124
	v_cvt_pk_bf16_f32 v73, v69, s0
	v_add_f32_e32 v69, 1.0, v71
	v_rcp_f32_e32 v71, v69
	s_mov_b32 s36, 0x25c18000
	v_add_co_u32_e32 v68, vcc, s36, v66
	v_fmac_f32_e32 v72, v207, v124
	s_nop 0
	v_addc_co_u32_e32 v69, vcc, 0, v67, vcc
	global_store_short v[68:69], v73, off
	v_mul_f32_e32 v68, v71, v70
	v_mul_f32_e32 v68, v68, v72
	s_mov_b64 s[100:101], 0x25c24000
	v_lshl_add_u64 v[66:67], v[66:67], 0, s[100:101]
	v_cvt_pk_bf16_f32 v68, v68, s0
	global_store_short v[66:67], v68, off
	s_and_saveexec_b64 s[36:37], s[34:35]
	s_cbranch_execz .LBB0_248
	ds_write_b32 v149, v72 offset:55360
	s_branch .LBB0_248

; #define LAS __attribute__((address_space(3)))
; #define LDS_BAR() do { asm volatile("s_waitcnt lgkmcnt(0)" ::: "memory"); __builtin_amdgcn_s_barrier(); asm volatile("" ::: "memory"); } while (0)
; #define RG_LOAD(n_) do { const long r0_ = (long)rowbase + (long)(n_) * 64; \
;         _Pragma("unroll") for (int i = 0; i < 11; ++i) xr[i] = ((n_) == 0 && 8 * rg - 3 + i < 0) ? 0u : *(const unsigned*)(xcol + (size_t)(r0_ + 8 * rg - 3 + i) * N1); } while (0)
; #define RG_LOADG(n_) do { const long r0_ = (long)rowbase + (long)(n_) * 64; \
;         _Pragma("unroll") for (int i = 0; i < 4; ++i) gbr[i] = *(const unsigned short*)(gbcol + (size_t)(r0_ + l0_ + 4 * fq + i) * N1); } while (0)
; #define RG_STAGE(xc_) do { LAS uchar* X_ = (xc_); \
;         _Pragma("unroll") for (int i = 0; i < 8; ++i) { f32x2 s2 = (f32x2){cbs[0], cbs[1]}; \
;             _Pragma("unroll") for (int k = 0; k < 4; ++k) s2 += (f32x2){cw[k][0], cw[k][1]} * (f32x2){bflo(xr[i + k]), bfhi(xr[i + k])}; \
;             *(LAS unsigned*)(X_ + (8 * rg + i) * S128 + c2 * 4) = pk2(s2.x, s2.y); } } while (0)
; DI void rglru_scan_unit(Frame& F, const Mix0Args& a, int u) {
;     ...
;     RG_LOAD(0);
;     RG_STAGE(XC0);
;     unsigned gb_cur[4];
;     RG_LOAD(1); RG_LOADG(0);
;     LDS_BAR();
;     const int nsl = cv_on ? min(NCH / 4, max(0, (CV_NIT - 8 * F.vcu + NGW - 1) / NGW)) : 0;
;     auto rg_step = [&](int n, auto cvt) __attribute__((always_inline)) {
;         constexpr int CQ = decltype(cvt)::value; constexpr bool CV = CQ >= 0;
;         const size_t row0 = rowbase + (size_t)n * 64;
;         LAS uchar* XCc = XC0 + (n & 1) * 64 * S128; LAS uchar* XCn = XC0 + ((n + 1) & 1) * 64 * S128;
;         LAS float* SEGA = SEG0 + (n & 1) * 1280; LAS float* SEGH = SEGA + 640;
; #pragma unroll
;         for (int i = 0; i < 4; ++i) gb_cur[i] = gbr[i];
;         if (n + 1 < NCH) RG_STAGE(XCn);
;         if constexpr (CQ == 0) { if (n > 0) { const int ip = ((n >> 2) - 1) * NGW + gw; if (ip < CV_NIT) cv_finish(a.cv, ip, lane, cq0, cq1, cq2, cq3, CVS); } }
;         if (n + 2 < NCH) RG_LOAD(n + 2);
;         if (n + 1 < NCH) RG_LOADG(n + 1);
.LBB0_324:
	s_cmpk_gt_u32 s93, 0x7d
	s_cbranch_scc1 .LBB0_326
	v_lshl_add_u64 v[10:11], v[6:7], 0, s[8:9]
	s_mov_b64 s[100:101], 0x258e4000
	v_lshl_add_u64 v[12:13], v[10:11], 0, s[100:101]
	global_load_dword v130, v[12:13], off
	s_mov_b64 s[100:101], 0x258f0000
	v_lshl_add_u64 v[12:13], v[10:11], 0, s[100:101]
	global_load_dword v132, v[12:13], off
	s_mov_b64 s[100:101], 0x258fc000
	v_lshl_add_u64 v[12:13], v[10:11], 0, s[100:101]
	global_load_dword v134, v[12:13], off
	s_mov_b64 s[100:101], 0x25908000
	v_lshl_add_u64 v[12:13], v[10:11], 0, s[100:101]
	global_load_dword v169, v[12:13], off
	s_mov_b64 s[100:101], 0x25914000
	v_lshl_add_u64 v[12:13], v[10:11], 0, s[100:101]
	global_load_dword v170, v[12:13], off
	s_mov_b64 s[100:101], 0x25920000
	v_lshl_add_u64 v[12:13], v[10:11], 0, s[100:101]
	global_load_dword v171, v[12:13], off
	s_mov_b64 s[100:101], 0x2592c000
	v_lshl_add_u64 v[12:13], v[10:11], 0, s[100:101]
	global_load_dword v172, v[12:13], off
	s_mov_b64 s[100:101], 0x25938000
	v_lshl_add_u64 v[12:13], v[10:11], 0, s[100:101]
	global_load_dword v173, v[12:13], off
	s_mov_b64 s[100:101], 0x25944000
	v_lshl_add_u64 v[12:13], v[10:11], 0, s[100:101]
	global_load_dword v174, v[12:13], off
	s_mov_b64 s[100:101], 0x25950000
	v_lshl_add_u64 v[12:13], v[10:11], 0, s[100:101]
	s_mov_b64 s[100:101], 0x2595c000
	v_lshl_add_u64 v[10:11], v[10:11], 0, s[100:101]
	global_load_dword v175, v[12:13], off
	global_load_dword v176, v[10:11], off
.LBB0_326:
	s_andn2_b64 vcc, exec, s[36:37]
	s_waitcnt vmcnt(8)
	v_mov_b32_e32 v13, v178
	v_mov_b32_e32 v12, v179
	v_mov_b32_e32 v11, v180
	v_mov_b32_e32 v10, v181
	s_cbranch_vccnz .LBB0_328
	v_lshl_add_u64 v[14:15], v[4:5], 0, s[8:9]
	s_mov_b64 s[100:101], 0x2560a000
	v_lshl_add_u64 v[10:11], v[14:15], 0, s[100:101]
	s_mov_b64 s[100:101], 0x25616000
	v_lshl_add_u64 v[12:13], v[14:15], 0, s[100:101]
	global_load_ushort v10, v[10:11], off
	global_load_ushort v11, v[12:13], off
	s_mov_b64 s[100:101], 0x25622000
	v_lshl_add_u64 v[12:13], v[14:15], 0, s[100:101]
	s_mov_b64 s[100:101], 0x2562e000
	v_lshl_add_u64 v[14:15], v[14:15], 0, s[100:101]
	global_load_ushort v12, v[12:13], off
	global_load_ushort v13, v[14:15], off

; DI void ssd_unit(Frame& F, const Mix1Args& a, int u) {
;     ...
;     const int c2x = tid & 31, rg4 = tid >> 5;
;     float xw[4][2], xb[2];
; #pragma unroll
;     for (int j = 0; j < 2; ++j) { const int chx = h * 64 + 2 * c2x + j; xb[j] = a.conv_b[chx];
; #pragma unroll
;         for (int k = 0; k < 4; ++k) xw[k][j] = a.conv_w[k * 10240 + chx]; }
;     const float Dh = a.d_skip[h];
.LBB0_675:
	s_and_b32 s93, s92, 0x7f
	v_lshl_or_b32 v90, s93, 8, v197
	v_lshl_add_u64 v[2:3], s[72:73], 0, v[90:91]
	s_mov_b64 s[100:101], 0xa000
	v_lshl_add_u64 v[4:5], v[2:3], 0, s[100:101]
	s_lshl_b32 s38, s93, 2
	s_waitcnt vmcnt(5)
	s_mov_b64 s[100:101], 0x14000
	v_lshl_add_u64 v[6:7], v[2:3], 0, s[100:101]
	global_load_dwordx2 v[100:101], v90, s[74:75]
	global_load_dwordx2 v[102:103], v90, s[72:73]
	s_mov_b64 s[100:101], 0x1e000
	v_lshl_add_u64 v[2:3], v[2:3], 0, s[100:101]
	global_load_dwordx2 v[104:105], v[4:5], off
	global_load_dwordx2 v[106:107], v[6:7], off
	global_load_dwordx2 v[108:109], v[2:3], off
	v_mov_b32_e32 v2, s38
	global_load_dword v110, v2, s[48:49]
	s_mov_b64 s[38:39], 0
	v_mov_b32_e32 v2, v188
	v_mov_b32_e32 v3, v187

; DI void ssd_unit(Frame& F, const Mix1Args& a, int u) {
;     ...
;     auto load_st = [&](int n_, SsdSt& r) __attribute__((always_inline)) {
;         const size_t T_ = ((size_t)(b * 128 + n_)) * 8 + g; const long r0_ = (long)rowbase + (long)n_ * 64;
;         const char* uCB = pCB + T_ * 8192; const char* uX = pP + (r0_ - 3) * (long)(N3P * 2); const char* uT = pT + (((size_t)(b * 128 + n_)) * 128 + h) * 512;
;         r.cb = *(const u32x4*)(uCB + vo16);
; #pragma unroll
;         for (int i = 0; i < 7; ++i) r.x[i] = (n_ == 0 && 4 * rg4 - 3 + i < 0) ? 0u : *(const unsigned*)(uX + vox[i]);
;         r.tb[0] = *(const float*)(uT + vot); r.tb[1] = *(const float*)(uT + 256 + vot); };
;     auto load_z = [&](int n_, SsdOp& r) __attribute__((always_inline)) { const char* uZ = pP + ((long)rowbase + (long)n_ * 64) * (long)(N3P * 2);
; #pragma unroll
;         for (int t = 0; t < 2; ++t) r.z[t] = *(const u32x2*)(uZ + 32 * t + voz); };
;     auto load_c = [&](int n_, SsdOp& r) __attribute__((always_inline)) { const char* uC = pC + (((size_t)(b * 128 + n_)) * 8 + g) * 16384;
; #pragma unroll
;         for (int ks = 0; ks < 4; ++ks) r.cf[ks] = *(const bf16x8*)(uC + ks * 1024 + voc); };
;     auto load_b = [&](int n_, SsdOp& r) __attribute__((always_inline)) { const char* uB = pB + (((size_t)(b * 128 + n_)) * 8 + g) * 16384;
; #pragma unroll
;         for (int ks = 0; ks < 2; ++ks) r.bf[ks] = *(const bf16x8*)(uB + ks * 1024 + vob); };
;     auto load_op = [&](int n_, SsdOp& r) __attribute__((always_inline)) { load_z(n_, r); load_c(n_, r); load_b(n_, r); };
;     u32x2 p_d[2] = {(u32x2){0u, 0u}, (u32x2){0u, 0u}}; float ss_d = 0.f;
;     auto put = [&](int n_) __attribute__((always_inline)) {
;         const size_t r0_ = rowbase + (size_t)n_ * 64; char* uO = pO + r0_ * (size_t)(a.out_ld * 2); char* uS = pS + r0_ * 4;
; #pragma unroll
;         for (int t = 0; t < 2; ++t) *(u32x2*)(uO + 32 * t + voo) = p_d[t];
;         if (fq == 0) unsafeAtomicAdd((float*)(uS + vos), ss_d); };
;     float el_c = 0.f, dec_c = 0.f;
;     auto stage = [&](const SsdSt& c, LAS uchar* I) __attribute__((always_inline)) {
;         TAB[lane] = c.tb[0]; TAB[64 + lane] = c.tb[1];
;         asm volatile("s_waitcnt lgkmcnt(0)" ::: "memory");
;         const float cs_last = TAB[63];
;         { const int l = tid >> 3, m8 = (tid & 7) * 8; u32x4 p = (u32x4){0u, 0u, 0u, 0u}; const u32x4 cbc = c.cb;
.LBB0_693:
	s_cmpk_lt_u32 s46, 0x7e
	s_cselect_b64 s[38:39], -1, 0
	s_cmpk_gt_u32 s46, 0x7d
	s_cselect_b64 s[76:77], -1, 0
	s_and_b64 vcc, exec, s[76:77]
	v_lshl_add_u64 v[154:155], s[58:59], 0, v[130:131]
	v_lshl_add_u64 v[158:159], s[58:59], 0, v[132:133]
	v_lshl_add_u64 v[156:157], s[58:59], 0, v[134:135]
	v_lshl_add_u64 v[152:153], s[58:59], 0, v[136:137]
	v_lshl_add_u64 v[80:81], s[58:59], 0, v[138:139]
	v_lshl_add_u64 v[78:79], s[58:59], 0, v[140:141]
	s_cbranch_vccnz .LBB0_695
	s_mov_b64 s[100:101], 0x25774000
	v_lshl_add_u64 v[34:35], v[154:155], 0, s[100:101]
	s_add_i32 s78, s68, s46
	global_load_dword v208, v[34:35], off offset:2560
	s_mov_b64 s[100:101], 0x25774000
	v_lshl_add_u64 v[34:35], v[158:159], 0, s[100:101]
	s_add_i32 s78, s78, 2
	global_load_dword v209, v[34:35], off offset:2560
	s_mov_b64 s[100:101], 0x25774000
	v_lshl_add_u64 v[34:35], v[156:157], 0, s[100:101]
	s_ashr_i32 s79, s78, 31
	s_lshl_b64 s[78:79], s[78:79], 16
	global_load_dword v210, v[34:35], off offset:2560
	s_mov_b64 s[100:101], 0x25790000
	v_lshl_add_u64 v[34:35], v[154:155], 0, s[100:101]
	v_lshl_add_u64 v[2:3], v[120:121], 0, s[78:79]
	global_load_dwordx4 v[2:5], v[2:3], off
	s_nop 0
	global_load_dword v211, v[34:35], off
	s_mov_b64 s[100:101], 0x25774000
	v_lshl_add_u64 v[34:35], v[152:153], 0, s[100:101]
	global_load_dword v212, v[34:35], off offset:2560
	s_mov_b64 s[100:101], 0x25774000
	v_lshl_add_u64 v[34:35], v[80:81], 0, s[100:101]
	global_load_dword v213, v[34:35], off offset:2560
	s_mov_b64 s[100:101], 0x25774000
	v_lshl_add_u64 v[34:35], v[78:79], 0, s[100:101]
	global_load_dword v214, v[34:35], off offset:2560
	v_lshl_add_u64 v[34:35], v[124:125], 0, s[78:79]
	global_load_dword v215, v[34:35], off
	global_load_dword v216, v[34:35], off offset:256
.LBB0_695:
	v_lshl_add_u64 v[160:161], s[58:59], 0, v[142:143]
	s_mov_b64 s[100:101], 0x25548000
	v_lshl_add_u64 v[34:35], v[160:161], 0, s[100:101]
	global_load_dwordx2 v[150:151], v[34:35], off
	global_load_dwordx2 v[148:149], v[34:35], off offset:32
	ds_write2st64_b32 v180, v225, v226 offset1:1
	s_waitcnt lgkmcnt(0)
	v_mov_b32_e32 v34, s87
	ds_read_b32 v75, v34 offset:252
	v_mov_b32_e32 v34, 0
	v_mov_b32_e32 v35, 0
	v_mov_b32_e32 v36, 0
	v_mov_b32_e32 v37, 0
	s_and_saveexec_b64 s[78:79], s[40:41]
	s_cbranch_execz .LBB0_697
	ds_read2st64_b32 v[42:43], v181 offset1:1
	ds_read_b128 v[34:37], v182
	ds_read_b128 v[38:41], v182 offset:16
	v_lshlrev_b32_e32 v45, 16, v30
	s_waitcnt lgkmcnt(2)
	v_max_f32_e32 v43, v43, v43
	s_waitcnt lgkmcnt(1)
	v_sub_f32_e32 v34, v42, v34
	v_max_f32_e32 v43, 0x1e3ce508, v43
	v_min_f32_e32 v34, 0, v34
	v_rcp_f32_e32 v44, v43
	v_exp_f32_e32 v111, v34
	v_sub_f32_e32 v43, v42, v35
	v_min_f32_e32 v43, 0, v43
	v_exp_f32_e32 v43, v43
	v_pk_mul_f32 v[34:35], v[110:111], v[44:45]
	v_sub_f32_e32 v36, v42, v36
	v_add_f32_e32 v44, v34, v35
	v_cndmask_b32_e64 v35, v35, v44, s[4:5]
	v_and_b32_e32 v44, 0xffff0000, v30
	v_min_f32_e32 v36, 0, v36
	v_mul_f32_e32 v43, v43, v44
	v_exp_f32_e32 v36, v36
	v_cndmask_b32_e64 v43, 0, v43, s[6:7]
	v_add_f32_e32 v44, v34, v43
	v_sub_f32_e32 v37, v42, v37
	v_cndmask_b32_e64 v43, v43, v44, s[8:9]
	v_lshlrev_b32_e32 v44, 16, v31
	v_min_f32_e32 v37, 0, v37
	v_mul_f32_e32 v36, v36, v44
	v_exp_f32_e32 v37, v37
	v_cndmask_b32_e64 v36, v36, 0, s[10:11]
	v_add_f32_e32 v44, v34, v36
	s_waitcnt lgkmcnt(0)
	v_sub_f32_e32 v38, v42, v38
	v_cndmask_b32_e64 v36, v36, v44, s[12:13]
	v_and_b32_e32 v44, 0xffff0000, v31
	v_min_f32_e32 v38, 0, v38
	v_mul_f32_e32 v37, v37, v44
	v_exp_f32_e32 v38, v38
	v_cndmask_b32_e64 v37, v37, 0, s[14:15]
	v_add_f32_e32 v44, v34, v37
	v_sub_f32_e32 v39, v42, v39
	v_cndmask_b32_e64 v37, v37, v44, s[16:17]
	v_lshlrev_b32_e32 v44, 16, v32
	v_min_f32_e32 v39, 0, v39
	v_mul_f32_e32 v38, v38, v44
	v_exp_f32_e32 v39, v39
	v_cndmask_b32_e64 v38, v38, 0, s[18:19]
	v_add_f32_e32 v44, v34, v38
	v_sub_f32_e32 v40, v42, v40
	v_cndmask_b32_e64 v38, v38, v44, s[20:21]
	v_and_b32_e32 v44, 0xffff0000, v32
	v_min_f32_e32 v40, 0, v40
	v_mul_f32_e32 v39, v39, v44
	v_exp_f32_e32 v40, v40
	v_cndmask_b32_e64 v39, v39, 0, s[22:23]
	v_add_f32_e32 v44, v34, v39
	v_sub_f32_e32 v41, v42, v41
	v_cndmask_b32_e64 v39, v39, v44, s[24:25]
	v_lshlrev_b32_e32 v44, 16, v33
	v_min_f32_e32 v41, 0, v41
	v_mul_f32_e32 v40, v40, v44
	v_exp_f32_e32 v41, v41
	v_cndmask_b32_e64 v40, v40, 0, s[26:27]
	v_add_f32_e32 v42, v34, v40
	v_cndmask_b32_e64 v40, v40, v42, s[28:29]
	v_and_b32_e32 v42, 0xffff0000, v33
	v_mul_f32_e32 v41, v41, v42
	v_cndmask_b32_e64 v41, v41, 0, s[30:31]
	v_add_f32_e32 v34, v34, v41
	v_cndmask_b32_e64 v41, v41, v34, s[34:35]
	v_cvt_pk_bf16_f32 v34, v35, v43
	v_cvt_pk_bf16_f32 v35, v36, v37
	v_cvt_pk_bf16_f32 v36, v38, v39
	v_cvt_pk_bf16_f32 v37, v40, v41

; DI void ssd_unit(Frame& F, const Mix1Args& a, int u) {
;     ...
;     auto load_st = [&](int n_, SsdSt& r) __attribute__((always_inline)) {
;         const size_t T_ = ((size_t)(b * 128 + n_)) * 8 + g; const long r0_ = (long)rowbase + (long)n_ * 64;
;         const char* uCB = pCB + T_ * 8192; const char* uX = pP + (r0_ - 3) * (long)(N3P * 2); const char* uT = pT + (((size_t)(b * 128 + n_)) * 128 + h) * 512;
;         r.cb = *(const u32x4*)(uCB + vo16);
; #pragma unroll
;         for (int i = 0; i < 7; ++i) r.x[i] = (n_ == 0 && 4 * rg4 - 3 + i < 0) ? 0u : *(const unsigned*)(uX + vox[i]);
;         r.tb[0] = *(const float*)(uT + vot); r.tb[1] = *(const float*)(uT + 256 + vot); };
;     auto load_z = [&](int n_, SsdOp& r) __attribute__((always_inline)) { const char* uZ = pP + ((long)rowbase + (long)n_ * 64) * (long)(N3P * 2);
; #pragma unroll
;         for (int t = 0; t < 2; ++t) r.z[t] = *(const u32x2*)(uZ + 32 * t + voz); };
.LBB0_699:
	s_or_b64 exec, exec, s[78:79]
	s_andn2_b64 vcc, exec, s[38:39]
	s_cbranch_vccnz .LBB0_701
	s_mov_b64 s[100:101], 0x259bc000
	v_lshl_add_u64 v[162:163], v[154:155], 0, s[100:101]
	s_add_i32 s38, s68, s46
	s_mov_b64 s[100:101], 0x259bc000
	v_lshl_add_u64 v[158:159], v[158:159], 0, s[100:101]
	s_add_i32 s38, s38, 3
	s_mov_b64 s[100:101], 0x259bc000
	v_lshl_add_u64 v[156:157], v[156:157], 0, s[100:101]
	s_ashr_i32 s39, s38, 31
	s_mov_b64 s[100:101], 0x259d8000
	v_lshl_add_u64 v[154:155], v[154:155], 0, s[100:101]
	s_lshl_b64 s[38:39], s[38:39], 16
	s_mov_b64 s[100:101], 0x259bc000
	v_lshl_add_u64 v[152:153], v[152:153], 0, s[100:101]
	v_lshl_add_u64 v[30:31], v[120:121], 0, s[38:39]
	s_mov_b64 s[100:101], 0x259bc000
	v_lshl_add_u64 v[80:81], v[80:81], 0, s[100:101]
	global_load_dwordx4 v[30:33], v[30:31], off
	s_mov_b64 s[100:101], 0x259bc000
	v_lshl_add_u64 v[78:79], v[78:79], 0, s[100:101]
	global_load_dword v222, v[152:153], off offset:2560
	global_load_dword v223, v[80:81], off offset:2560
	global_load_dword v224, v[78:79], off offset:2560
	v_lshl_add_u64 v[78:79], v[124:125], 0, s[38:39]
	global_load_dword v218, v[162:163], off offset:2560
	global_load_dword v219, v[158:159], off offset:2560
	global_load_dword v220, v[156:157], off offset:2560
	global_load_dword v221, v[154:155], off
	global_load_dword v225, v[78:79], off
	global_load_dword v226, v[78:79], off offset:256
.LBB0_701:
	s_add_i32 s38, s46, 1
	s_cmpk_lt_u32 s38, 0x7f
	s_cselect_b64 s[78:79], -1, 0
	s_cmpk_gt_u32 s38, 0x7e
	s_cbranch_scc1 .LBB0_703
	s_mov_b64 s[100:101], 0x25790000
	v_lshl_add_u64 v[78:79], v[160:161], 0, s[100:101]
	global_load_dwordx2 v[112:113], v[78:79], off
	global_load_dwordx2 v[114:115], v[78:79], off offset:32
